# K-loop load segments without VALU copies/adds (direct lane-offset regs, one precomputed LDS base)
# baseline (speedup 1.0000x reference)
; #define PG8_STAGE(bufoff, gbase, voff) do { const char* gb_ = (const char*)(gbase); asm volatile("" : "+s"(gb_)); _Pragma("unroll") for (int _i = 0; _i < 2; ++_i) { unsigned vo_ = (voff)[_i]; asm volatile("" : "+v"(vo_));        \
;         __builtin_amdgcn_global_load_lds((const unsigned*)(gb_ + vo_), (PG8_LAS unsigned*)(lds + (bufoff) + ldsw + _i * 8192), 16, 0, 0); } } while (0)
; #define PG8_LDA(dst, b, h) do { _Pragma("unroll") for (int m = 0; m < 4; ++m) _Pragma("unroll") for (int k = 0; k < 2; ++k) dst[m][k] = *(const PG8_LAS bf16x8*)(lds + PG8_SA(b, h) + aoff + m * 2048 + k * 1024); } while (0)
; #define PG8_LDB(dst, b, h) do { _Pragma("unroll") for (int n = 0; n < 2; ++n) _Pragma("unroll") for (int k = 0; k < 2; ++k) dst[n][k] = *(const PG8_LAS bf16x8*)(lds + PG8_SB(b, h) + boff + n * 2048 + k * 1024); } while (0)
; #define PG8_WAIT_V(n) asm volatile("s_waitcnt vmcnt(" #n ")" ::: "memory")
; #define PG8_BAR __builtin_amdgcn_s_barrier()
; template <class Epi, class Sched, bool ALIGN_EPI = false, bool SP2 = false>
; __device__ __forceinline__ void gemm_phase(PG8_LAS unsigned char* lds, const Gemm g, const Sched& S, const Epi& E) {
;     ...
;         const bool has_next = S.next(ui + 1, nxt);
;         const char* nA = has_next ? (const char*)g.A + (size_t)nxt.pm * tstep : cA; const char* nB = has_next ? (const char*)g.Bt + (size_t)nxt.pn * tstep : cB;
;         for (int t = 0; t < nt; t += 2) {
;             const bool last = (t == nt - 2);
;             const char* a1 = cA + (size_t)(t + 1) * kstep;
;             const char* a2 = last ? nA : cA + (size_t)(t + 2) * kstep; const char* b2 = last ? nB : cB + (size_t)(t + 2) * kstep;
;             const char* a3 = a2 + kstep; const char* b3 = b2 + kstep;
;             if (last && has_next) S.a_ready(nxt);
;             if constexpr (SP2) {
;             PG8_LDB(B0, 0, 0); PG8_LDB(B1, 0, 1); PG8_SCHED; PG8_LDA(At, 0, 0); PG8_STAGE(PG8_SA(1, 1), a1 + hstep, voffA);
;             PG8_WAIT_V(8); PG8_WAIT_L(0); PG8_BAR; PG8_MMA(0, 0, At, B0); PG8_MMA(0, 1, At, B1); PG8_BAR; PG8_SCHED;
;     ...
; #pragma unroll
;         for (int a = 0; a < 2; ++a)
; #pragma unroll
;             for (int b = 0; b < 2; ++b)
; #pragma unroll
;                 for (int m = 0; m < 4; ++m)
; #pragma unroll
;                     for (int n = 0; n < 2; ++n) acc[a][b][m][n] = (f32x4){0.f, 0.f, 0.f, 0.f};
;         cur = nxt; cA = nA; cB = nB; ++ui;
.LBB0_231:
	s_ashr_i32 s49, s48, 31
	s_lshl_b64 s[6:7], s[48:49], 20
	s_add_u32 s50, s96, s6
	s_addc_u32 s51, s97, s7
	s_and_b64 s[6:7], s[36:37], exec
	s_cselect_b32 s24, s51, s1
	s_cselect_b32 s25, s50, s0
	s_ashr_i32 s47, s46, 31
	s_lshl_b64 s[6:7], s[46:47], 20
	v_readlane_b32 s8, v241, 44
	s_add_u32 s52, s8, s6
	v_readlane_b32 s6, v241, 45
	s_addc_u32 s53, s6, s7
	s_and_b64 s[6:7], s[36:37], exec
	s_cselect_b32 s26, s53, s3
	s_cselect_b32 s27, s52, s2
	s_add_u32 s28, s2, 0x100
	v_mov_b32_e32 v2, 0
	s_addc_u32 s29, s3, 0
	s_mov_b32 s30, -2
	v_mov_b32_e32 v3, v2
	v_mov_b32_e32 v4, v2
	v_mov_b32_e32 v5, v2
	v_mov_b32_e32 v6, v2
	v_mov_b32_e32 v7, v2
	v_mov_b32_e32 v8, v2
	v_mov_b32_e32 v9, v2
	v_mov_b32_e32 v10, v2
	s_waitcnt lgkmcnt(0)
	v_mov_b32_e32 v11, v2
	v_mov_b32_e32 v12, v2
	v_mov_b32_e32 v13, v2
	v_mov_b32_e32 v14, v2
	v_mov_b32_e32 v15, v2
	v_mov_b32_e32 v16, v2
	v_mov_b32_e32 v17, v2
	v_mov_b32_e32 v18, v2
	v_mov_b32_e32 v19, v2
	v_mov_b32_e32 v20, v2
	v_mov_b32_e32 v21, v2
	v_mov_b32_e32 v22, v2
	v_mov_b32_e32 v23, v2
	v_mov_b32_e32 v24, v2
	v_mov_b32_e32 v25, v2
	v_mov_b32_e32 v26, v2
	v_mov_b32_e32 v27, v2
	v_mov_b32_e32 v28, v2
	v_mov_b32_e32 v29, v2
	v_mov_b32_e32 v30, v2
	v_mov_b32_e32 v31, v2
	v_mov_b32_e32 v32, v2
	v_mov_b32_e32 v33, v2
	v_mov_b32_e32 v82, v2
	v_mov_b32_e32 v83, v2
	v_mov_b32_e32 v84, v2
	v_mov_b32_e32 v85, v2
	v_mov_b32_e32 v86, v2
	v_mov_b32_e32 v87, v2
	v_mov_b32_e32 v88, v2
	v_mov_b32_e32 v89, v2
	v_mov_b32_e32 v90, v2
	v_mov_b32_e32 v91, v2
	v_mov_b32_e32 v92, v2
	v_mov_b32_e32 v93, v2
	v_mov_b32_e32 v94, v2
	v_mov_b32_e32 v95, v2
	v_mov_b32_e32 v96, v2
	v_mov_b32_e32 v97, v2
	v_mov_b32_e32 v98, v2
	v_mov_b32_e32 v99, v2
	v_mov_b32_e32 v100, v2
	v_mov_b32_e32 v101, v2
	v_mov_b32_e32 v102, v2
	v_mov_b32_e32 v103, v2
	v_mov_b32_e32 v104, v2
	v_mov_b32_e32 v105, v2
	v_mov_b32_e32 v106, v2
	v_mov_b32_e32 v107, v2
	v_mov_b32_e32 v108, v2
	v_mov_b32_e32 v109, v2
	v_mov_b32_e32 v110, v2
	v_mov_b32_e32 v111, v2
	v_mov_b32_e32 v112, v2
	v_mov_b32_e32 v113, v2
	v_mov_b32_e32 v34, v2
	v_mov_b32_e32 v35, v2
	v_mov_b32_e32 v36, v2
	v_mov_b32_e32 v37, v2
	v_mov_b32_e32 v38, v2
	v_mov_b32_e32 v39, v2
	v_mov_b32_e32 v40, v2
	v_mov_b32_e32 v41, v2
	v_mov_b32_e32 v42, v2
	v_mov_b32_e32 v43, v2
	v_mov_b32_e32 v44, v2
	v_mov_b32_e32 v45, v2
	v_mov_b32_e32 v46, v2
	v_mov_b32_e32 v47, v2
	v_mov_b32_e32 v48, v2
	v_mov_b32_e32 v49, v2
	v_mov_b32_e32 v50, v2
	v_mov_b32_e32 v51, v2
	v_mov_b32_e32 v52, v2
	v_mov_b32_e32 v53, v2
	v_mov_b32_e32 v54, v2
	v_mov_b32_e32 v55, v2
	v_mov_b32_e32 v56, v2
	v_mov_b32_e32 v57, v2
	v_mov_b32_e32 v58, v2
	v_mov_b32_e32 v59, v2
	v_mov_b32_e32 v60, v2
	v_mov_b32_e32 v61, v2
	v_mov_b32_e32 v62, v2
	v_mov_b32_e32 v63, v2
	v_mov_b32_e32 v64, v2
	v_mov_b32_e32 v65, v2
	v_mov_b32_e32 v114, v2
	v_mov_b32_e32 v115, v2
	v_mov_b32_e32 v116, v2
	v_mov_b32_e32 v117, v2
	v_mov_b32_e32 v118, v2
	v_mov_b32_e32 v119, v2
	v_mov_b32_e32 v120, v2
	v_mov_b32_e32 v121, v2
	v_mov_b32_e32 v122, v2
	v_mov_b32_e32 v123, v2
	v_mov_b32_e32 v124, v2
	v_mov_b32_e32 v125, v2
	v_mov_b32_e32 v126, v2
	v_mov_b32_e32 v127, v2
	v_mov_b32_e32 v128, v2
	v_mov_b32_e32 v129, v2
	v_mov_b32_e32 v130, v2
	v_mov_b32_e32 v131, v2
	v_mov_b32_e32 v132, v2
	v_mov_b32_e32 v133, v2
	v_mov_b32_e32 v134, v2
	v_mov_b32_e32 v135, v2
	v_mov_b32_e32 v136, v2
	v_mov_b32_e32 v137, v2
	v_mov_b32_e32 v138, v2
	v_mov_b32_e32 v139, v2
	v_mov_b32_e32 v140, v2
	v_mov_b32_e32 v141, v2
	v_mov_b32_e32 v142, v2
	v_mov_b32_e32 v143, v2
	v_mov_b32_e32 v144, v2
	v_mov_b32_e32 v145, v2
	v_add_u32_e32 v244, 0x10000, v221
.LBB0_232:
	s_add_u32 s2, s0, 0x100
	s_addc_u32 s3, s1, 0
	s_cmp_eq_u32 s30, 28
	s_cselect_b32 s10, s25, s2
	s_cselect_b32 s11, s24, s3
	s_cselect_b32 s8, s27, s28
	s_cselect_b32 s9, s26, s29
	s_add_u32 s6, s10, 0x80
	s_addc_u32 s7, s11, 0
	s_add_i32 s31, 0, 0x10000
	s_add_i32 s33, 0, 0x14000
	ds_read_b128 v[66:69], v244
	ds_read_b128 v[70:73], v244 offset:1024
	ds_read_b128 v[74:77], v244 offset:2048
	ds_read_b128 v[78:81], v244 offset:3072
	ds_read_b128 v[146:149], v244 offset:16384
	ds_read_b128 v[150:153], v244 offset:17408
	ds_read_b128 v[154:157], v244 offset:18432
	ds_read_b128 v[158:161], v244 offset:19456
	s_add_u32 s0, s0, 0x80080
	s_addc_u32 s1, s1, 0
	ds_read_b128 v[178:181], v223
	ds_read_b128 v[182:185], v223 offset:1024
	ds_read_b128 v[192:195], v223 offset:2048
	ds_read_b128 v[196:199], v223 offset:3072
	ds_read_b128 v[200:203], v223 offset:4096
	ds_read_b128 v[204:207], v223 offset:5120
	ds_read_b128 v[208:211], v223 offset:6144
	ds_read_b128 v[212:215], v223 offset:7168
	s_add_i32 m0, s13, 0xc000
	s_nop 0
	global_load_lds_dwordx4 v1, s[0:1]
	s_add_i32 m0, s13, 0xe000
	s_nop 0
	global_load_lds_dwordx4 v191, s[0:1]
	s_waitcnt vmcnt(8)
	s_waitcnt lgkmcnt(0)
	s_barrier
; #define PG8_STAGE(bufoff, gbase, voff) do { const char* gb_ = (const char*)(gbase); asm volatile("" : "+s"(gb_)); _Pragma("unroll") for (int _i = 0; _i < 2; ++_i) { unsigned vo_ = (voff)[_i]; asm volatile("" : "+v"(vo_));        \
;         __builtin_amdgcn_global_load_lds((const unsigned*)(gb_ + vo_), (PG8_LAS unsigned*)(lds + (bufoff) + ldsw + _i * 8192), 16, 0, 0); } } while (0)
; #define PG8_LDA(dst, b, h) do { _Pragma("unroll") for (int m = 0; m < 4; ++m) _Pragma("unroll") for (int k = 0; k < 2; ++k) dst[m][k] = *(const PG8_LAS bf16x8*)(lds + PG8_SA(b, h) + aoff + m * 2048 + k * 1024); } while (0)
; #define PG8_LDB(dst, b, h) do { _Pragma("unroll") for (int n = 0; n < 2; ++n) _Pragma("unroll") for (int k = 0; k < 2; ++k) dst[n][k] = *(const PG8_LAS bf16x8*)(lds + PG8_SB(b, h) + boff + n * 2048 + k * 1024); } while (0)
; #define PG8_MMA(ai, bj, At, Bt) do { __builtin_amdgcn_s_setprio(1); _Pragma("unroll") for (int m = 0; m < 4; ++m) _Pragma("unroll") for (int n = 0; n < 2; ++n) _Pragma("unroll") for (int k = 0; k < 2; ++k) \
;         acc[ai][bj][m][n] = __builtin_amdgcn_mfma_f32_16x16x32_bf16(Bt[n][k], At[m][k], acc[ai][bj][m][n], 0, 0, 0); __builtin_amdgcn_s_setprio(0); } while (0)
; #define PG8_WAIT_V(n) asm volatile("s_waitcnt vmcnt(" #n ")" ::: "memory")
; #define PG8_WAIT_L(n) asm volatile("s_waitcnt lgkmcnt(" #n ")" ::: "memory")
; #define PG8_BAR __builtin_amdgcn_s_barrier()
; #define PG8_SCHED __builtin_amdgcn_sched_barrier(0)
; template <class Epi, class Sched, bool ALIGN_EPI = false, bool SP2 = false>
; __device__ __forceinline__ void gemm_phase(PG8_LAS unsigned char* lds, const Gemm g, const Sched& S, const Epi& E) {
;     ...
;             PG8_LDB(B0, 0, 0); PG8_LDB(B1, 0, 1); PG8_SCHED; PG8_LDA(At, 0, 0); PG8_STAGE(PG8_SA(1, 1), a1 + hstep, voffA);
;             PG8_WAIT_V(8); PG8_WAIT_L(0); PG8_BAR; PG8_MMA(0, 0, At, B0); PG8_MMA(0, 1, At, B1); PG8_BAR; PG8_SCHED;
;             PG8_LDA(At, 0, 1); PG8_STAGE(PG8_SB(0, 0), b2, voffB); PG8_STAGE(PG8_SB(0, 1), b2 + hstep, voffB); PG8_STAGE(PG8_SA(0, 0), a2, voffA);
;             PG8_WAIT_V(8); PG8_WAIT_L(0); PG8_BAR; PG8_MMA(1, 0, At, B0); PG8_MMA(1, 1, At, B1); PG8_BAR; PG8_SCHED;
	s_setprio 1
	s_waitcnt lgkmcnt(0)
	v_mfma_f32_16x16x32_bf16 v[142:145], v[66:69], v[178:181], v[142:145]
	v_mfma_f32_16x16x32_bf16 v[138:141], v[74:77], v[178:181], v[138:141]
	v_mfma_f32_16x16x32_bf16 v[134:137], v[66:69], v[192:195], v[134:137]
	v_mfma_f32_16x16x32_bf16 v[130:133], v[74:77], v[192:195], v[130:133]
	v_mfma_f32_16x16x32_bf16 v[126:129], v[66:69], v[200:203], v[126:129]
	v_mfma_f32_16x16x32_bf16 v[122:125], v[74:77], v[200:203], v[122:125]
	v_mfma_f32_16x16x32_bf16 v[118:121], v[66:69], v[208:211], v[118:121]
	v_mfma_f32_16x16x32_bf16 v[114:117], v[74:77], v[208:211], v[114:117]
	v_mfma_f32_16x16x32_bf16 v[142:145], v[70:73], v[182:185], v[142:145]
	v_mfma_f32_16x16x32_bf16 v[138:141], v[78:81], v[182:185], v[138:141]
	v_mfma_f32_16x16x32_bf16 v[134:137], v[70:73], v[196:199], v[134:137]
	v_mfma_f32_16x16x32_bf16 v[130:133], v[78:81], v[196:199], v[130:133]
	v_mfma_f32_16x16x32_bf16 v[126:129], v[70:73], v[204:207], v[126:129]
	v_mfma_f32_16x16x32_bf16 v[122:125], v[78:81], v[204:207], v[122:125]
	v_mfma_f32_16x16x32_bf16 v[118:121], v[70:73], v[212:215], v[118:121]
	v_mfma_f32_16x16x32_bf16 v[114:117], v[78:81], v[212:215], v[114:117]
	s_setprio 0
	s_setprio 1
	v_mfma_f32_16x16x32_bf16 v[62:65], v[146:149], v[178:181], v[62:65]
	v_mfma_f32_16x16x32_bf16 v[58:61], v[154:157], v[178:181], v[58:61]
	v_mfma_f32_16x16x32_bf16 v[54:57], v[146:149], v[192:195], v[54:57]
	v_mfma_f32_16x16x32_bf16 v[50:53], v[154:157], v[192:195], v[50:53]
	v_mfma_f32_16x16x32_bf16 v[46:49], v[146:149], v[200:203], v[46:49]
	v_mfma_f32_16x16x32_bf16 v[42:45], v[154:157], v[200:203], v[42:45]
	v_mfma_f32_16x16x32_bf16 v[38:41], v[146:149], v[208:211], v[38:41]
	v_mfma_f32_16x16x32_bf16 v[34:37], v[154:157], v[208:211], v[34:37]
	v_mfma_f32_16x16x32_bf16 v[62:65], v[150:153], v[182:185], v[62:65]
	v_mfma_f32_16x16x32_bf16 v[58:61], v[158:161], v[182:185], v[58:61]
	v_mfma_f32_16x16x32_bf16 v[54:57], v[150:153], v[196:199], v[54:57]
	v_mfma_f32_16x16x32_bf16 v[50:53], v[158:161], v[196:199], v[50:53]
	v_mfma_f32_16x16x32_bf16 v[46:49], v[150:153], v[204:207], v[46:49]
	v_mfma_f32_16x16x32_bf16 v[42:45], v[158:161], v[204:207], v[42:45]
	v_mfma_f32_16x16x32_bf16 v[38:41], v[150:153], v[212:215], v[38:41]
	v_mfma_f32_16x16x32_bf16 v[34:37], v[158:161], v[212:215], v[34:37]
	s_setprio 0
	s_barrier
	s_mov_b64 s[0:1], s[8:9]
	s_add_i32 s31, s31, s12
	ds_read_b128 v[178:181], v223 offset:16384
	ds_read_b128 v[182:185], v223 offset:17408
	ds_read_b128 v[192:195], v223 offset:18432
	ds_read_b128 v[196:199], v223 offset:19456
	ds_read_b128 v[200:203], v223 offset:20480
	ds_read_b128 v[204:207], v223 offset:21504
	ds_read_b128 v[208:211], v223 offset:22528
	ds_read_b128 v[212:215], v223 offset:23552
	s_mov_b32 m0, s31
	s_nop 0
	global_load_lds_dwordx4 v189, s[0:1]
	s_add_i32 m0, s31, 0x2000
	s_nop 0
	global_load_lds_dwordx4 v219, s[0:1]
	s_add_u32 s0, s8, 0x80000
	s_addc_u32 s1, s9, 0
	s_add_i32 s31, s33, s12
	s_mov_b32 m0, s31
	s_nop 0
	global_load_lds_dwordx4 v189, s[0:1]
	s_add_i32 m0, s31, 0x2000
	s_nop 0
	global_load_lds_dwordx4 v219, s[0:1]
	s_mov_b64 s[0:1], s[10:11]
	s_mov_b32 m0, s13
	s_nop 0
	global_load_lds_dwordx4 v1, s[0:1]
	s_mov_b32 m0, s14
	s_nop 0
	global_load_lds_dwordx4 v191, s[0:1]
	s_waitcnt vmcnt(8)
	s_waitcnt lgkmcnt(0)
	s_barrier
	s_setprio 1
	s_waitcnt lgkmcnt(0)
	v_mfma_f32_16x16x32_bf16 v[110:113], v[66:69], v[178:181], v[110:113]
	v_mfma_f32_16x16x32_bf16 v[106:109], v[74:77], v[178:181], v[106:109]
	v_mfma_f32_16x16x32_bf16 v[102:105], v[66:69], v[192:195], v[102:105]
	v_mfma_f32_16x16x32_bf16 v[98:101], v[74:77], v[192:195], v[98:101]
	v_mfma_f32_16x16x32_bf16 v[94:97], v[66:69], v[200:203], v[94:97]
	v_mfma_f32_16x16x32_bf16 v[90:93], v[74:77], v[200:203], v[90:93]
	v_mfma_f32_16x16x32_bf16 v[66:69], v[66:69], v[208:211], v[86:89]
	v_mfma_f32_16x16x32_bf16 v[110:113], v[70:73], v[182:185], v[110:113]
	v_mfma_f32_16x16x32_bf16 v[106:109], v[78:81], v[182:185], v[106:109]
	v_mfma_f32_16x16x32_bf16 v[102:105], v[70:73], v[196:199], v[102:105]
	v_mfma_f32_16x16x32_bf16 v[98:101], v[78:81], v[196:199], v[98:101]
	v_mfma_f32_16x16x32_bf16 v[94:97], v[70:73], v[204:207], v[94:97]
	v_mfma_f32_16x16x32_bf16 v[90:93], v[78:81], v[204:207], v[90:93]
	v_mfma_f32_16x16x32_bf16 v[66:69], v[70:73], v[212:215], v[66:69]
	v_mfma_f32_16x16x32_bf16 v[70:73], v[74:77], v[208:211], v[82:85]
	v_mfma_f32_16x16x32_bf16 v[70:73], v[78:81], v[212:215], v[70:73]
	s_setprio 0
	s_setprio 1
	v_mfma_f32_16x16x32_bf16 v[30:33], v[146:149], v[178:181], v[30:33]
	v_mfma_f32_16x16x32_bf16 v[26:29], v[154:157], v[178:181], v[26:29]
	v_mfma_f32_16x16x32_bf16 v[22:25], v[146:149], v[192:195], v[22:25]
	v_mfma_f32_16x16x32_bf16 v[18:21], v[154:157], v[192:195], v[18:21]
	v_mfma_f32_16x16x32_bf16 v[14:17], v[146:149], v[200:203], v[14:17]
	v_mfma_f32_16x16x32_bf16 v[10:13], v[154:157], v[200:203], v[10:13]
	v_mfma_f32_16x16x32_bf16 v[6:9], v[146:149], v[208:211], v[6:9]
	v_mfma_f32_16x16x32_bf16 v[2:5], v[154:157], v[208:211], v[2:5]
	v_mfma_f32_16x16x32_bf16 v[30:33], v[150:153], v[182:185], v[30:33]
	v_mfma_f32_16x16x32_bf16 v[26:29], v[158:161], v[182:185], v[26:29]
	v_mfma_f32_16x16x32_bf16 v[22:25], v[150:153], v[196:199], v[22:25]
	v_mfma_f32_16x16x32_bf16 v[18:21], v[158:161], v[196:199], v[18:21]
	v_mfma_f32_16x16x32_bf16 v[14:17], v[150:153], v[204:207], v[14:17]
	v_mfma_f32_16x16x32_bf16 v[10:13], v[158:161], v[204:207], v[10:13]
	v_mfma_f32_16x16x32_bf16 v[6:9], v[150:153], v[212:215], v[6:9]
	v_mfma_f32_16x16x32_bf16 v[2:5], v[158:161], v[212:215], v[2:5]
	s_setprio 0
	s_barrier
; #define PG8_STAGE(bufoff, gbase, voff) do { const char* gb_ = (const char*)(gbase); asm volatile("" : "+s"(gb_)); _Pragma("unroll") for (int _i = 0; _i < 2; ++_i) { unsigned vo_ = (voff)[_i]; asm volatile("" : "+v"(vo_));        \
;         __builtin_amdgcn_global_load_lds((const unsigned*)(gb_ + vo_), (PG8_LAS unsigned*)(lds + (bufoff) + ldsw + _i * 8192), 16, 0, 0); } } while (0)
; #define PG8_LDA(dst, b, h) do { _Pragma("unroll") for (int m = 0; m < 4; ++m) _Pragma("unroll") for (int k = 0; k < 2; ++k) dst[m][k] = *(const PG8_LAS bf16x8*)(lds + PG8_SA(b, h) + aoff + m * 2048 + k * 1024); } while (0)
; #define PG8_LDB(dst, b, h) do { _Pragma("unroll") for (int n = 0; n < 2; ++n) _Pragma("unroll") for (int k = 0; k < 2; ++k) dst[n][k] = *(const PG8_LAS bf16x8*)(lds + PG8_SB(b, h) + boff + n * 2048 + k * 1024); } while (0)
; #define PG8_MMA(ai, bj, At, Bt) do { __builtin_amdgcn_s_setprio(1); _Pragma("unroll") for (int m = 0; m < 4; ++m) _Pragma("unroll") for (int n = 0; n < 2; ++n) _Pragma("unroll") for (int k = 0; k < 2; ++k) \
;         acc[ai][bj][m][n] = __builtin_amdgcn_mfma_f32_16x16x32_bf16(Bt[n][k], At[m][k], acc[ai][bj][m][n], 0, 0, 0); __builtin_amdgcn_s_setprio(0); } while (0)
; #define PG8_WAIT_V(n) asm volatile("s_waitcnt vmcnt(" #n ")" ::: "memory")
; #define PG8_WAIT_L(n) asm volatile("s_waitcnt lgkmcnt(" #n ")" ::: "memory")
; #define PG8_BAR __builtin_amdgcn_s_barrier()
; #define PG8_SCHED __builtin_amdgcn_sched_barrier(0)
; template <class Epi, class Sched, bool ALIGN_EPI = false, bool SP2 = false>
; __device__ __forceinline__ void gemm_phase(PG8_LAS unsigned char* lds, const Gemm g, const Sched& S, const Epi& E) {
;     ...
;             PG8_LDB(B0, 1, 0); PG8_LDB(B1, 1, 1); PG8_SCHED; PG8_LDA(At, 1, 0); PG8_STAGE(PG8_SA(0, 1), a2 + hstep, voffA);
;             PG8_WAIT_V(8); PG8_WAIT_L(0); PG8_BAR; PG8_MMA(0, 0, At, B0); PG8_MMA(0, 1, At, B1); PG8_BAR; PG8_SCHED;
;             PG8_LDA(At, 1, 1); PG8_STAGE(PG8_SB(1, 0), b3, voffB); PG8_STAGE(PG8_SB(1, 1), b3 + hstep, voffB); PG8_STAGE(PG8_SA(1, 0), a3, voffA);
;             PG8_WAIT_V(8); PG8_WAIT_L(0); PG8_BAR; PG8_MMA(1, 0, At, B0); PG8_MMA(1, 1, At, B1); PG8_BAR; PG8_SCHED;
	s_add_i32 s31, 0, 0x18000
	s_add_i32 s33, 0, 0x1c000
	ds_read_b128 v[74:77], v244 offset:32768
	ds_read_b128 v[78:81], v244 offset:33792
	ds_read_b128 v[82:85], v244 offset:34816
	ds_read_b128 v[146:149], v244 offset:35840
	ds_read_b128 v[150:153], v244 offset:49152
	ds_read_b128 v[154:157], v244 offset:50176
	ds_read_b128 v[158:161], v244 offset:51200
	ds_read_b128 v[178:181], v244 offset:52224
	s_add_u32 s0, s10, 0x80000
	s_addc_u32 s1, s11, 0
	s_mov_b32 m0, s15
	ds_read_b128 v[86:89], v223 offset:32768
	ds_read_b128 v[182:185], v223 offset:33792
	ds_read_b128 v[192:195], v223 offset:34816
	ds_read_b128 v[196:199], v223 offset:35840
	ds_read_b128 v[200:203], v223 offset:36864
	ds_read_b128 v[204:207], v223 offset:37888
	ds_read_b128 v[208:211], v223 offset:38912
	ds_read_b128 v[212:215], v223 offset:39936
	s_nop 0
	global_load_lds_dwordx4 v1, s[0:1]
	s_mov_b32 m0, s16
	s_nop 0
	global_load_lds_dwordx4 v191, s[0:1]
	s_waitcnt vmcnt(8)
	s_waitcnt lgkmcnt(0)
	s_barrier
	s_setprio 1
	s_waitcnt lgkmcnt(0)
	v_mfma_f32_16x16x32_bf16 v[142:145], v[74:77], v[86:89], v[142:145]
	v_mfma_f32_16x16x32_bf16 v[138:141], v[82:85], v[86:89], v[138:141]
	v_mfma_f32_16x16x32_bf16 v[134:137], v[74:77], v[192:195], v[134:137]
	v_mfma_f32_16x16x32_bf16 v[130:133], v[82:85], v[192:195], v[130:133]
	v_mfma_f32_16x16x32_bf16 v[126:129], v[74:77], v[200:203], v[126:129]
	v_mfma_f32_16x16x32_bf16 v[122:125], v[82:85], v[200:203], v[122:125]
	v_mfma_f32_16x16x32_bf16 v[118:121], v[74:77], v[208:211], v[118:121]
	v_mfma_f32_16x16x32_bf16 v[114:117], v[82:85], v[208:211], v[114:117]
	v_mfma_f32_16x16x32_bf16 v[142:145], v[78:81], v[182:185], v[142:145]
	v_mfma_f32_16x16x32_bf16 v[138:141], v[146:149], v[182:185], v[138:141]
	v_mfma_f32_16x16x32_bf16 v[134:137], v[78:81], v[196:199], v[134:137]
	v_mfma_f32_16x16x32_bf16 v[130:133], v[146:149], v[196:199], v[130:133]
	v_mfma_f32_16x16x32_bf16 v[126:129], v[78:81], v[204:207], v[126:129]
	v_mfma_f32_16x16x32_bf16 v[122:125], v[146:149], v[204:207], v[122:125]
	v_mfma_f32_16x16x32_bf16 v[118:121], v[78:81], v[212:215], v[118:121]
	v_mfma_f32_16x16x32_bf16 v[114:117], v[146:149], v[212:215], v[114:117]
	s_setprio 0
	s_setprio 1
	v_mfma_f32_16x16x32_bf16 v[62:65], v[150:153], v[86:89], v[62:65]
	v_mfma_f32_16x16x32_bf16 v[58:61], v[158:161], v[86:89], v[58:61]
	v_mfma_f32_16x16x32_bf16 v[54:57], v[150:153], v[192:195], v[54:57]
	v_mfma_f32_16x16x32_bf16 v[50:53], v[158:161], v[192:195], v[50:53]
	v_mfma_f32_16x16x32_bf16 v[46:49], v[150:153], v[200:203], v[46:49]
	v_mfma_f32_16x16x32_bf16 v[42:45], v[158:161], v[200:203], v[42:45]
	v_mfma_f32_16x16x32_bf16 v[38:41], v[150:153], v[208:211], v[38:41]
	v_mfma_f32_16x16x32_bf16 v[34:37], v[158:161], v[208:211], v[34:37]
	v_mfma_f32_16x16x32_bf16 v[62:65], v[154:157], v[182:185], v[62:65]
	v_mfma_f32_16x16x32_bf16 v[58:61], v[178:181], v[182:185], v[58:61]
	v_mfma_f32_16x16x32_bf16 v[54:57], v[154:157], v[196:199], v[54:57]
	v_mfma_f32_16x16x32_bf16 v[50:53], v[178:181], v[196:199], v[50:53]
	v_mfma_f32_16x16x32_bf16 v[46:49], v[154:157], v[204:207], v[46:49]
	v_mfma_f32_16x16x32_bf16 v[42:45], v[178:181], v[204:207], v[42:45]
	v_mfma_f32_16x16x32_bf16 v[38:41], v[154:157], v[212:215], v[38:41]
	v_mfma_f32_16x16x32_bf16 v[34:37], v[178:181], v[212:215], v[34:37]
	s_setprio 0
	s_barrier
	s_add_u32 s0, s8, 0x80
	s_addc_u32 s1, s9, 0
	s_add_i32 s10, s31, s12
	ds_read_b128 v[182:185], v223 offset:49152
	ds_read_b128 v[192:195], v223 offset:50176
	ds_read_b128 v[196:199], v223 offset:51200
	ds_read_b128 v[200:203], v223 offset:52224
	ds_read_b128 v[204:207], v223 offset:53248
	ds_read_b128 v[208:211], v223 offset:54272
	ds_read_b128 v[212:215], v223 offset:55296
	ds_read_b128 v[224:227], v223 offset:56320
	s_mov_b32 m0, s10
	s_nop 0
	global_load_lds_dwordx4 v189, s[0:1]
	s_add_i32 m0, s10, 0x2000
	s_nop 0
	global_load_lds_dwordx4 v219, s[0:1]
	s_add_u32 s0, s8, 0x80080
	s_addc_u32 s1, s9, 0
	s_add_i32 s8, s33, s12
	s_mov_b32 m0, s8
	s_nop 0
	global_load_lds_dwordx4 v189, s[0:1]
	s_add_i32 m0, s8, 0x2000
	s_nop 0
	global_load_lds_dwordx4 v219, s[0:1]
	s_mov_b32 m0, s19
	s_nop 0
	global_load_lds_dwordx4 v1, s[6:7]
	s_mov_b32 m0, s20
	s_nop 0
	global_load_lds_dwordx4 v191, s[6:7]
	s_waitcnt vmcnt(8)
	s_waitcnt lgkmcnt(0)
	s_barrier
	s_setprio 1
	s_waitcnt lgkmcnt(0)
	v_mfma_f32_16x16x32_bf16 v[86:89], v[74:77], v[182:185], v[110:113]
	v_mfma_f32_16x16x32_bf16 v[110:113], v[78:81], v[192:195], v[86:89]
	v_mfma_f32_16x16x32_bf16 v[86:89], v[82:85], v[182:185], v[106:109]
	v_mfma_f32_16x16x32_bf16 v[106:109], v[146:149], v[192:195], v[86:89]
	v_mfma_f32_16x16x32_bf16 v[86:89], v[74:77], v[196:199], v[102:105]
	v_mfma_f32_16x16x32_bf16 v[102:105], v[78:81], v[200:203], v[86:89]
	v_mfma_f32_16x16x32_bf16 v[86:89], v[82:85], v[196:199], v[98:101]
	v_mfma_f32_16x16x32_bf16 v[98:101], v[146:149], v[200:203], v[86:89]
	v_mfma_f32_16x16x32_bf16 v[86:89], v[74:77], v[204:207], v[94:97]
	v_mfma_f32_16x16x32_bf16 v[94:97], v[78:81], v[208:211], v[86:89]
	v_mfma_f32_16x16x32_bf16 v[86:89], v[82:85], v[204:207], v[90:93]
	v_mfma_f32_16x16x32_bf16 v[66:69], v[74:77], v[212:215], v[66:69]
	v_mfma_f32_16x16x32_bf16 v[90:93], v[146:149], v[208:211], v[86:89]
	v_mfma_f32_16x16x32_bf16 v[86:89], v[78:81], v[224:227], v[66:69]
	v_mfma_f32_16x16x32_bf16 v[66:69], v[82:85], v[212:215], v[70:73]
	v_mfma_f32_16x16x32_bf16 v[82:85], v[146:149], v[224:227], v[66:69]
	s_setprio 0
	s_setprio 1
	v_mfma_f32_16x16x32_bf16 v[30:33], v[150:153], v[182:185], v[30:33]
	v_mfma_f32_16x16x32_bf16 v[26:29], v[158:161], v[182:185], v[26:29]
	v_mfma_f32_16x16x32_bf16 v[22:25], v[150:153], v[196:199], v[22:25]
	v_mfma_f32_16x16x32_bf16 v[18:21], v[158:161], v[196:199], v[18:21]
	v_mfma_f32_16x16x32_bf16 v[14:17], v[150:153], v[204:207], v[14:17]
	v_mfma_f32_16x16x32_bf16 v[10:13], v[158:161], v[204:207], v[10:13]
	v_mfma_f32_16x16x32_bf16 v[6:9], v[150:153], v[212:215], v[6:9]
	v_mfma_f32_16x16x32_bf16 v[2:5], v[158:161], v[212:215], v[2:5]
	v_mfma_f32_16x16x32_bf16 v[30:33], v[154:157], v[192:195], v[30:33]
	v_mfma_f32_16x16x32_bf16 v[26:29], v[178:181], v[192:195], v[26:29]
	v_mfma_f32_16x16x32_bf16 v[22:25], v[154:157], v[200:203], v[22:25]
	v_mfma_f32_16x16x32_bf16 v[18:21], v[178:181], v[200:203], v[18:21]
	v_mfma_f32_16x16x32_bf16 v[14:17], v[154:157], v[208:211], v[14:17]
	v_mfma_f32_16x16x32_bf16 v[10:13], v[178:181], v[208:211], v[10:13]
	v_mfma_f32_16x16x32_bf16 v[6:9], v[154:157], v[224:227], v[6:9]
	v_mfma_f32_16x16x32_bf16 v[2:5], v[178:181], v[224:227], v[2:5]
	s_setprio 0
	s_barrier
	s_add_i32 s30, s30, 2
	s_add_u32 s28, s28, 0x100
	s_addc_u32 s29, s29, 0
	s_cmp_gt_u32 s30, 29
	s_mov_b64 s[0:1], s[2:3]
	s_cbranch_scc0 .LBB0_232
	s_and_b64 vcc, exec, s[44:45]
	s_cbranch_vccz .LBB0_235
	s_barrier

; #define PG8_STAGE(bufoff, gbase, voff) do { const char* gb_ = (const char*)(gbase); asm volatile("" : "+s"(gb_)); _Pragma("unroll") for (int _i = 0; _i < 2; ++_i) { unsigned vo_ = (voff)[_i]; asm volatile("" : "+v"(vo_));        \
;         __builtin_amdgcn_global_load_lds((const unsigned*)(gb_ + vo_), (PG8_LAS unsigned*)(lds + (bufoff) + ldsw + _i * 8192), 16, 0, 0); } } while (0)
; #define PG8_LDA(dst, b, h) do { _Pragma("unroll") for (int m = 0; m < 4; ++m) _Pragma("unroll") for (int k = 0; k < 2; ++k) dst[m][k] = *(const PG8_LAS bf16x8*)(lds + PG8_SA(b, h) + aoff + m * 2048 + k * 1024); } while (0)
; #define PG8_LDB(dst, b, h) do { _Pragma("unroll") for (int n = 0; n < 2; ++n) _Pragma("unroll") for (int k = 0; k < 2; ++k) dst[n][k] = *(const PG8_LAS bf16x8*)(lds + PG8_SB(b, h) + boff + n * 2048 + k * 1024); } while (0)
; #define PG8_WAIT_V(n) asm volatile("s_waitcnt vmcnt(" #n ")" ::: "memory")
; #define PG8_BAR __builtin_amdgcn_s_barrier()
; template <class Epi, class Sched, bool ALIGN_EPI = false, bool SP2 = false>
; __device__ __forceinline__ void gemm_phase(PG8_LAS unsigned char* lds, const Gemm g, const Sched& S, const Epi& E) {
;     ...
;         const bool has_next = S.next(ui + 1, nxt);
;         const char* nA = has_next ? (const char*)g.A + (size_t)nxt.pm * tstep : cA; const char* nB = has_next ? (const char*)g.Bt + (size_t)nxt.pn * tstep : cB;
;         for (int t = 0; t < nt; t += 2) {
;             const bool last = (t == nt - 2);
;             const char* a1 = cA + (size_t)(t + 1) * kstep;
;             const char* a2 = last ? nA : cA + (size_t)(t + 2) * kstep; const char* b2 = last ? nB : cB + (size_t)(t + 2) * kstep;
;             const char* a3 = a2 + kstep; const char* b3 = b2 + kstep;
;             if (last && has_next) S.a_ready(nxt);
;             if constexpr (SP2) {
;             PG8_LDB(B0, 0, 0); PG8_LDB(B1, 0, 1); PG8_SCHED; PG8_LDA(At, 0, 0); PG8_STAGE(PG8_SA(1, 1), a1 + hstep, voffA);
;             PG8_WAIT_V(8); PG8_WAIT_L(0); PG8_BAR; PG8_MMA(0, 0, At, B0); PG8_MMA(0, 1, At, B1); PG8_BAR; PG8_SCHED;
;     ...
; #pragma unroll
;         for (int a = 0; a < 2; ++a)
; #pragma unroll
;             for (int b = 0; b < 2; ++b)
; #pragma unroll
;                 for (int m = 0; m < 4; ++m)
; #pragma unroll
;                     for (int n = 0; n < 2; ++n) acc[a][b][m][n] = (f32x4){0.f, 0.f, 0.f, 0.f};
;         cur = nxt; cA = nA; cB = nB; ++ui;
.LBB0_554:
	s_ashr_i32 s51, s50, 31
	v_cmp_lt_i64_e32 vcc, s[8:9], v[172:173]
	s_lshl_b64 s[8:9], s[50:51], 20
	v_readlane_b32 s10, v242, 30
	s_add_u32 s52, s10, s8
	v_readlane_b32 s8, v242, 31
	s_addc_u32 s53, s8, s9
	s_and_b64 s[8:9], vcc, exec
	s_cselect_b32 s34, s53, s5
	s_cselect_b32 s35, s52, s4
	s_ashr_i32 s49, s48, 31
	s_lshl_b64 s[8:9], s[48:49], 20
	s_add_u32 s54, s15, s8
	s_addc_u32 s55, s16, s9
	s_and_b64 s[8:9], vcc, exec
	s_cselect_b32 s38, s55, s7
	s_cselect_b32 s39, s54, s6
	s_add_u32 s40, s6, 0x100
	v_mov_b32_e32 v2, 0
	s_addc_u32 s49, s7, 0
	s_mov_b32 s51, -2
	s_waitcnt lgkmcnt(0)
	v_mov_b32_e32 v3, v2
	v_mov_b32_e32 v4, v2
	v_mov_b32_e32 v5, v2
	v_mov_b32_e32 v6, v2
	v_mov_b32_e32 v7, v2
	v_mov_b32_e32 v8, v2
	v_mov_b32_e32 v9, v2
	v_mov_b32_e32 v10, v2
	s_waitcnt lgkmcnt(0)
	v_mov_b32_e32 v11, v2
	v_mov_b32_e32 v12, v2
	v_mov_b32_e32 v13, v2
	v_mov_b32_e32 v14, v2
	v_mov_b32_e32 v15, v2
	v_mov_b32_e32 v16, v2
	v_mov_b32_e32 v17, v2
	v_mov_b32_e32 v18, v2
	v_mov_b32_e32 v19, v2
	v_mov_b32_e32 v20, v2
	v_mov_b32_e32 v21, v2
	v_mov_b32_e32 v22, v2
	v_mov_b32_e32 v23, v2
	v_mov_b32_e32 v24, v2
	v_mov_b32_e32 v25, v2
	v_mov_b32_e32 v34, v2
	v_mov_b32_e32 v35, v2
	v_mov_b32_e32 v36, v2
	v_mov_b32_e32 v37, v2
	v_mov_b32_e32 v38, v2
	v_mov_b32_e32 v39, v2
	v_mov_b32_e32 v40, v2
	v_mov_b32_e32 v41, v2
	v_mov_b32_e32 v74, v2
	v_mov_b32_e32 v75, v2
	v_mov_b32_e32 v76, v2
	v_mov_b32_e32 v77, v2
	v_mov_b32_e32 v78, v2
	v_mov_b32_e32 v79, v2
	v_mov_b32_e32 v80, v2
	v_mov_b32_e32 v81, v2
	v_mov_b32_e32 v82, v2
	v_mov_b32_e32 v83, v2
	v_mov_b32_e32 v84, v2
	v_mov_b32_e32 v85, v2
	v_mov_b32_e32 v86, v2
	v_mov_b32_e32 v87, v2
	v_mov_b32_e32 v88, v2
	v_mov_b32_e32 v89, v2
	v_mov_b32_e32 v90, v2
	v_mov_b32_e32 v91, v2
	v_mov_b32_e32 v92, v2
	v_mov_b32_e32 v93, v2
	v_mov_b32_e32 v94, v2
	v_mov_b32_e32 v95, v2
	v_mov_b32_e32 v96, v2
	v_mov_b32_e32 v97, v2
	v_mov_b32_e32 v106, v2
	v_mov_b32_e32 v107, v2
	v_mov_b32_e32 v108, v2
	v_mov_b32_e32 v109, v2
	v_mov_b32_e32 v110, v2
	v_mov_b32_e32 v111, v2
	v_mov_b32_e32 v112, v2
	v_mov_b32_e32 v113, v2
	v_mov_b32_e32 v42, v2
	v_mov_b32_e32 v43, v2
	v_mov_b32_e32 v44, v2
	v_mov_b32_e32 v45, v2
	v_mov_b32_e32 v46, v2
	v_mov_b32_e32 v47, v2
	v_mov_b32_e32 v48, v2
	v_mov_b32_e32 v49, v2
	v_mov_b32_e32 v50, v2
	v_mov_b32_e32 v51, v2
	v_mov_b32_e32 v52, v2
	v_mov_b32_e32 v53, v2
	v_mov_b32_e32 v54, v2
	v_mov_b32_e32 v55, v2
	v_mov_b32_e32 v56, v2
	v_mov_b32_e32 v57, v2
	v_mov_b32_e32 v58, v2
	v_mov_b32_e32 v59, v2
	v_mov_b32_e32 v60, v2
	v_mov_b32_e32 v61, v2
	v_mov_b32_e32 v62, v2
	v_mov_b32_e32 v63, v2
	v_mov_b32_e32 v64, v2
	v_mov_b32_e32 v65, v2
	v_mov_b32_e32 v66, v2
	v_mov_b32_e32 v67, v2
	v_mov_b32_e32 v68, v2
	v_mov_b32_e32 v69, v2
	v_mov_b32_e32 v70, v2
	v_mov_b32_e32 v71, v2
	v_mov_b32_e32 v72, v2
	v_mov_b32_e32 v73, v2
	v_mov_b32_e32 v114, v2
	v_mov_b32_e32 v115, v2
	v_mov_b32_e32 v116, v2
	v_mov_b32_e32 v117, v2
	v_mov_b32_e32 v118, v2
	v_mov_b32_e32 v119, v2
	v_mov_b32_e32 v120, v2
	v_mov_b32_e32 v121, v2
	v_mov_b32_e32 v122, v2
	v_mov_b32_e32 v123, v2
	v_mov_b32_e32 v124, v2
	v_mov_b32_e32 v125, v2
	v_mov_b32_e32 v126, v2
	v_mov_b32_e32 v127, v2
	v_mov_b32_e32 v128, v2
	v_mov_b32_e32 v129, v2
	v_mov_b32_e32 v130, v2
	v_mov_b32_e32 v131, v2
	v_mov_b32_e32 v132, v2
	v_mov_b32_e32 v133, v2
	v_mov_b32_e32 v134, v2
	v_mov_b32_e32 v135, v2
	v_mov_b32_e32 v136, v2
	v_mov_b32_e32 v137, v2
	v_mov_b32_e32 v138, v2
	v_mov_b32_e32 v139, v2
	v_mov_b32_e32 v140, v2
	v_mov_b32_e32 v141, v2
	v_mov_b32_e32 v142, v2
	v_mov_b32_e32 v143, v2
	v_mov_b32_e32 v144, v2
	v_mov_b32_e32 v145, v2
	v_add_u32_e32 v244, 0x10000, v208
.LBB0_555:
	s_add_u32 s6, s4, 0x100
	s_addc_u32 s7, s5, 0
	s_cmp_eq_u32 s51, 28
	s_cselect_b32 s12, s35, s6
	s_cselect_b32 s13, s34, s7
	s_cselect_b32 s10, s39, s40
	s_cselect_b32 s11, s38, s49
	s_add_u32 s8, s12, 0x80
	s_addc_u32 s9, s13, 0
	s_add_i32 s56, 0, 0x10000
	s_add_i32 s57, 0, 0x14000
	ds_read_b128 v[26:29], v244
	ds_read_b128 v[30:33], v244 offset:1024
	ds_read_b128 v[98:101], v244 offset:2048
	ds_read_b128 v[102:105], v244 offset:3072
	ds_read_b128 v[146:149], v244 offset:16384
	ds_read_b128 v[150:153], v244 offset:17408
	ds_read_b128 v[154:157], v244 offset:18432
	ds_read_b128 v[158:161], v244 offset:19456
	s_add_u32 s4, s4, 0x80080
	s_addc_u32 s5, s5, 0
	ds_read_b128 v[178:181], v210
	ds_read_b128 v[182:185], v210 offset:1024
	ds_read_b128 v[186:189], v210 offset:2048
	ds_read_b128 v[190:193], v210 offset:3072
	ds_read_b128 v[194:197], v210 offset:4096
	ds_read_b128 v[198:201], v210 offset:5120
	ds_read_b128 v[202:205], v210 offset:6144
	ds_read_b128 v[212:215], v210 offset:7168
	s_add_i32 m0, s18, 0xc000
	s_nop 0
	global_load_lds_dwordx4 v1, s[4:5]
	s_add_i32 m0, s18, 0xe000
	s_nop 0
	global_load_lds_dwordx4 v164, s[4:5]
	s_waitcnt vmcnt(8)
	s_waitcnt lgkmcnt(0)
	s_barrier
; #define PG8_STAGE(bufoff, gbase, voff) do { const char* gb_ = (const char*)(gbase); asm volatile("" : "+s"(gb_)); _Pragma("unroll") for (int _i = 0; _i < 2; ++_i) { unsigned vo_ = (voff)[_i]; asm volatile("" : "+v"(vo_));        \
;         __builtin_amdgcn_global_load_lds((const unsigned*)(gb_ + vo_), (PG8_LAS unsigned*)(lds + (bufoff) + ldsw + _i * 8192), 16, 0, 0); } } while (0)
; #define PG8_LDA(dst, b, h) do { _Pragma("unroll") for (int m = 0; m < 4; ++m) _Pragma("unroll") for (int k = 0; k < 2; ++k) dst[m][k] = *(const PG8_LAS bf16x8*)(lds + PG8_SA(b, h) + aoff + m * 2048 + k * 1024); } while (0)
; #define PG8_LDB(dst, b, h) do { _Pragma("unroll") for (int n = 0; n < 2; ++n) _Pragma("unroll") for (int k = 0; k < 2; ++k) dst[n][k] = *(const PG8_LAS bf16x8*)(lds + PG8_SB(b, h) + boff + n * 2048 + k * 1024); } while (0)
; #define PG8_MMA(ai, bj, At, Bt) do { __builtin_amdgcn_s_setprio(1); _Pragma("unroll") for (int m = 0; m < 4; ++m) _Pragma("unroll") for (int n = 0; n < 2; ++n) _Pragma("unroll") for (int k = 0; k < 2; ++k) \
;         acc[ai][bj][m][n] = __builtin_amdgcn_mfma_f32_16x16x32_bf16(Bt[n][k], At[m][k], acc[ai][bj][m][n], 0, 0, 0); __builtin_amdgcn_s_setprio(0); } while (0)
; #define PG8_WAIT_V(n) asm volatile("s_waitcnt vmcnt(" #n ")" ::: "memory")
; #define PG8_WAIT_L(n) asm volatile("s_waitcnt lgkmcnt(" #n ")" ::: "memory")
; #define PG8_BAR __builtin_amdgcn_s_barrier()
; #define PG8_SCHED __builtin_amdgcn_sched_barrier(0)
; template <class Epi, class Sched, bool ALIGN_EPI = false, bool SP2 = false>
; __device__ __forceinline__ void gemm_phase(PG8_LAS unsigned char* lds, const Gemm g, const Sched& S, const Epi& E) {
;     ...
;             PG8_LDB(B0, 0, 0); PG8_LDB(B1, 0, 1); PG8_SCHED; PG8_LDA(At, 0, 0); PG8_STAGE(PG8_SA(1, 1), a1 + hstep, voffA);
;             PG8_WAIT_V(8); PG8_WAIT_L(0); PG8_BAR; PG8_MMA(0, 0, At, B0); PG8_MMA(0, 1, At, B1); PG8_BAR; PG8_SCHED;
;             PG8_LDA(At, 0, 1); PG8_STAGE(PG8_SB(0, 0), b2, voffB); PG8_STAGE(PG8_SB(0, 1), b2 + hstep, voffB); PG8_STAGE(PG8_SA(0, 0), a2, voffA);
;             PG8_WAIT_V(8); PG8_WAIT_L(0); PG8_BAR; PG8_MMA(1, 0, At, B0); PG8_MMA(1, 1, At, B1); PG8_BAR; PG8_SCHED;
	s_setprio 1
	s_waitcnt lgkmcnt(0)
	v_mfma_f32_16x16x32_bf16 v[142:145], v[26:29], v[178:181], v[142:145]
	v_mfma_f32_16x16x32_bf16 v[138:141], v[98:101], v[178:181], v[138:141]
	v_mfma_f32_16x16x32_bf16 v[134:137], v[26:29], v[186:189], v[134:137]
	v_mfma_f32_16x16x32_bf16 v[130:133], v[98:101], v[186:189], v[130:133]
	v_mfma_f32_16x16x32_bf16 v[126:129], v[26:29], v[194:197], v[126:129]
	v_mfma_f32_16x16x32_bf16 v[122:125], v[98:101], v[194:197], v[122:125]
	v_mfma_f32_16x16x32_bf16 v[118:121], v[26:29], v[202:205], v[118:121]
	v_mfma_f32_16x16x32_bf16 v[114:117], v[98:101], v[202:205], v[114:117]
	v_mfma_f32_16x16x32_bf16 v[142:145], v[30:33], v[182:185], v[142:145]
	v_mfma_f32_16x16x32_bf16 v[138:141], v[102:105], v[182:185], v[138:141]
	v_mfma_f32_16x16x32_bf16 v[134:137], v[30:33], v[190:193], v[134:137]
	v_mfma_f32_16x16x32_bf16 v[130:133], v[102:105], v[190:193], v[130:133]
	v_mfma_f32_16x16x32_bf16 v[126:129], v[30:33], v[198:201], v[126:129]
	v_mfma_f32_16x16x32_bf16 v[122:125], v[102:105], v[198:201], v[122:125]
	v_mfma_f32_16x16x32_bf16 v[118:121], v[30:33], v[212:215], v[118:121]
	v_mfma_f32_16x16x32_bf16 v[114:117], v[102:105], v[212:215], v[114:117]
	s_setprio 0
	s_setprio 1
	v_mfma_f32_16x16x32_bf16 v[70:73], v[146:149], v[178:181], v[70:73]
	v_mfma_f32_16x16x32_bf16 v[66:69], v[154:157], v[178:181], v[66:69]
	v_mfma_f32_16x16x32_bf16 v[62:65], v[146:149], v[186:189], v[62:65]
	v_mfma_f32_16x16x32_bf16 v[58:61], v[154:157], v[186:189], v[58:61]
	v_mfma_f32_16x16x32_bf16 v[54:57], v[146:149], v[194:197], v[54:57]
	v_mfma_f32_16x16x32_bf16 v[50:53], v[154:157], v[194:197], v[50:53]
	v_mfma_f32_16x16x32_bf16 v[46:49], v[146:149], v[202:205], v[46:49]
	v_mfma_f32_16x16x32_bf16 v[42:45], v[154:157], v[202:205], v[42:45]
	v_mfma_f32_16x16x32_bf16 v[70:73], v[150:153], v[182:185], v[70:73]
	v_mfma_f32_16x16x32_bf16 v[66:69], v[158:161], v[182:185], v[66:69]
	v_mfma_f32_16x16x32_bf16 v[62:65], v[150:153], v[190:193], v[62:65]
	v_mfma_f32_16x16x32_bf16 v[58:61], v[158:161], v[190:193], v[58:61]
	v_mfma_f32_16x16x32_bf16 v[54:57], v[150:153], v[198:201], v[54:57]
	v_mfma_f32_16x16x32_bf16 v[50:53], v[158:161], v[198:201], v[50:53]
	v_mfma_f32_16x16x32_bf16 v[46:49], v[150:153], v[212:215], v[46:49]
	v_mfma_f32_16x16x32_bf16 v[42:45], v[158:161], v[212:215], v[42:45]
	s_setprio 0
	s_barrier
	s_mov_b64 s[4:5], s[10:11]
	s_add_i32 s56, s56, s17
	ds_read_b128 v[178:181], v210 offset:16384
	ds_read_b128 v[182:185], v210 offset:17408
	ds_read_b128 v[186:189], v210 offset:18432
	ds_read_b128 v[190:193], v210 offset:19456
	ds_read_b128 v[194:197], v210 offset:20480
	ds_read_b128 v[198:201], v210 offset:21504
	ds_read_b128 v[202:205], v210 offset:22528
	ds_read_b128 v[212:215], v210 offset:23552
	s_mov_b32 m0, s56
	s_nop 0
	global_load_lds_dwordx4 v162, s[4:5]
	s_add_i32 m0, s56, 0x2000
	s_nop 0
	global_load_lds_dwordx4 v206, s[4:5]
	s_add_u32 s4, s10, 0x80000
	s_addc_u32 s5, s11, 0
	s_add_i32 s56, s57, s17
	s_mov_b32 m0, s56
	s_nop 0
	global_load_lds_dwordx4 v162, s[4:5]
	s_add_i32 m0, s56, 0x2000
	s_nop 0
	global_load_lds_dwordx4 v206, s[4:5]
	s_mov_b64 s[4:5], s[12:13]
	s_mov_b32 m0, s18
	s_nop 0
	global_load_lds_dwordx4 v1, s[4:5]
	s_mov_b32 m0, s19
	s_nop 0
	global_load_lds_dwordx4 v164, s[4:5]
	s_waitcnt vmcnt(8)
	s_waitcnt lgkmcnt(0)
	s_barrier
	s_setprio 1
	s_waitcnt lgkmcnt(0)
	v_mfma_f32_16x16x32_bf16 v[110:113], v[26:29], v[178:181], v[110:113]
	v_mfma_f32_16x16x32_bf16 v[106:109], v[98:101], v[178:181], v[106:109]
	v_mfma_f32_16x16x32_bf16 v[94:97], v[26:29], v[186:189], v[94:97]
	v_mfma_f32_16x16x32_bf16 v[90:93], v[98:101], v[186:189], v[90:93]
	v_mfma_f32_16x16x32_bf16 v[86:89], v[26:29], v[194:197], v[86:89]
	v_mfma_f32_16x16x32_bf16 v[82:85], v[98:101], v[194:197], v[82:85]
	v_mfma_f32_16x16x32_bf16 v[26:29], v[26:29], v[202:205], v[78:81]
	v_mfma_f32_16x16x32_bf16 v[110:113], v[30:33], v[182:185], v[110:113]
	v_mfma_f32_16x16x32_bf16 v[106:109], v[102:105], v[182:185], v[106:109]
	v_mfma_f32_16x16x32_bf16 v[94:97], v[30:33], v[190:193], v[94:97]
	v_mfma_f32_16x16x32_bf16 v[90:93], v[102:105], v[190:193], v[90:93]
	v_mfma_f32_16x16x32_bf16 v[86:89], v[30:33], v[198:201], v[86:89]
	v_mfma_f32_16x16x32_bf16 v[82:85], v[102:105], v[198:201], v[82:85]
	v_mfma_f32_16x16x32_bf16 v[26:29], v[30:33], v[212:215], v[26:29]
	v_mfma_f32_16x16x32_bf16 v[30:33], v[98:101], v[202:205], v[74:77]
	v_mfma_f32_16x16x32_bf16 v[30:33], v[102:105], v[212:215], v[30:33]
	s_setprio 0
	s_setprio 1
	v_mfma_f32_16x16x32_bf16 v[38:41], v[146:149], v[178:181], v[38:41]
	v_mfma_f32_16x16x32_bf16 v[34:37], v[154:157], v[178:181], v[34:37]
	v_mfma_f32_16x16x32_bf16 v[22:25], v[146:149], v[186:189], v[22:25]
	v_mfma_f32_16x16x32_bf16 v[18:21], v[154:157], v[186:189], v[18:21]
	v_mfma_f32_16x16x32_bf16 v[14:17], v[146:149], v[194:197], v[14:17]
	v_mfma_f32_16x16x32_bf16 v[10:13], v[154:157], v[194:197], v[10:13]
	v_mfma_f32_16x16x32_bf16 v[6:9], v[146:149], v[202:205], v[6:9]
	v_mfma_f32_16x16x32_bf16 v[2:5], v[154:157], v[202:205], v[2:5]
	v_mfma_f32_16x16x32_bf16 v[38:41], v[150:153], v[182:185], v[38:41]
	v_mfma_f32_16x16x32_bf16 v[34:37], v[158:161], v[182:185], v[34:37]
	v_mfma_f32_16x16x32_bf16 v[22:25], v[150:153], v[190:193], v[22:25]
	v_mfma_f32_16x16x32_bf16 v[18:21], v[158:161], v[190:193], v[18:21]
	v_mfma_f32_16x16x32_bf16 v[14:17], v[150:153], v[198:201], v[14:17]
	v_mfma_f32_16x16x32_bf16 v[10:13], v[158:161], v[198:201], v[10:13]
	v_mfma_f32_16x16x32_bf16 v[6:9], v[150:153], v[212:215], v[6:9]
	v_mfma_f32_16x16x32_bf16 v[2:5], v[158:161], v[212:215], v[2:5]
	s_setprio 0
	s_barrier
; #define PG8_STAGE(bufoff, gbase, voff) do { const char* gb_ = (const char*)(gbase); asm volatile("" : "+s"(gb_)); _Pragma("unroll") for (int _i = 0; _i < 2; ++_i) { unsigned vo_ = (voff)[_i]; asm volatile("" : "+v"(vo_));        \
;         __builtin_amdgcn_global_load_lds((const unsigned*)(gb_ + vo_), (PG8_LAS unsigned*)(lds + (bufoff) + ldsw + _i * 8192), 16, 0, 0); } } while (0)
; #define PG8_LDA(dst, b, h) do { _Pragma("unroll") for (int m = 0; m < 4; ++m) _Pragma("unroll") for (int k = 0; k < 2; ++k) dst[m][k] = *(const PG8_LAS bf16x8*)(lds + PG8_SA(b, h) + aoff + m * 2048 + k * 1024); } while (0)
; #define PG8_LDB(dst, b, h) do { _Pragma("unroll") for (int n = 0; n < 2; ++n) _Pragma("unroll") for (int k = 0; k < 2; ++k) dst[n][k] = *(const PG8_LAS bf16x8*)(lds + PG8_SB(b, h) + boff + n * 2048 + k * 1024); } while (0)
; #define PG8_MMA(ai, bj, At, Bt) do { __builtin_amdgcn_s_setprio(1); _Pragma("unroll") for (int m = 0; m < 4; ++m) _Pragma("unroll") for (int n = 0; n < 2; ++n) _Pragma("unroll") for (int k = 0; k < 2; ++k) \
;         acc[ai][bj][m][n] = __builtin_amdgcn_mfma_f32_16x16x32_bf16(Bt[n][k], At[m][k], acc[ai][bj][m][n], 0, 0, 0); __builtin_amdgcn_s_setprio(0); } while (0)
; #define PG8_WAIT_V(n) asm volatile("s_waitcnt vmcnt(" #n ")" ::: "memory")
; #define PG8_WAIT_L(n) asm volatile("s_waitcnt lgkmcnt(" #n ")" ::: "memory")
; #define PG8_BAR __builtin_amdgcn_s_barrier()
; #define PG8_SCHED __builtin_amdgcn_sched_barrier(0)
; template <class Epi, class Sched, bool ALIGN_EPI = false, bool SP2 = false>
; __device__ __forceinline__ void gemm_phase(PG8_LAS unsigned char* lds, const Gemm g, const Sched& S, const Epi& E) {
;     ...
;             PG8_LDB(B0, 1, 0); PG8_LDB(B1, 1, 1); PG8_SCHED; PG8_LDA(At, 1, 0); PG8_STAGE(PG8_SA(0, 1), a2 + hstep, voffA);
;             PG8_WAIT_V(8); PG8_WAIT_L(0); PG8_BAR; PG8_MMA(0, 0, At, B0); PG8_MMA(0, 1, At, B1); PG8_BAR; PG8_SCHED;
;             PG8_LDA(At, 1, 1); PG8_STAGE(PG8_SB(1, 0), b3, voffB); PG8_STAGE(PG8_SB(1, 1), b3 + hstep, voffB); PG8_STAGE(PG8_SA(1, 0), a3, voffA);
;             PG8_WAIT_V(8); PG8_WAIT_L(0); PG8_BAR; PG8_MMA(1, 0, At, B0); PG8_MMA(1, 1, At, B1); PG8_BAR; PG8_SCHED;
	s_add_i32 s56, 0, 0x18000
	s_add_i32 s57, 0, 0x1c000
	ds_read_b128 v[74:77], v244 offset:32768
	ds_read_b128 v[78:81], v244 offset:33792
	ds_read_b128 v[98:101], v244 offset:34816
	ds_read_b128 v[102:105], v244 offset:35840
	ds_read_b128 v[146:149], v244 offset:49152
	ds_read_b128 v[150:153], v244 offset:50176
	ds_read_b128 v[154:157], v244 offset:51200
	ds_read_b128 v[158:161], v244 offset:52224
	s_add_u32 s4, s12, 0x80000
	s_addc_u32 s5, s13, 0
	s_mov_b32 m0, s20
	ds_read_b128 v[178:181], v210 offset:32768
	ds_read_b128 v[182:185], v210 offset:33792
	ds_read_b128 v[186:189], v210 offset:34816
	ds_read_b128 v[190:193], v210 offset:35840
	ds_read_b128 v[194:197], v210 offset:36864
	ds_read_b128 v[198:201], v210 offset:37888
	ds_read_b128 v[202:205], v210 offset:38912
	ds_read_b128 v[212:215], v210 offset:39936
	s_nop 0
	global_load_lds_dwordx4 v1, s[4:5]
	s_mov_b32 m0, s21
	s_nop 0
	global_load_lds_dwordx4 v164, s[4:5]
	s_waitcnt vmcnt(8)
	s_waitcnt lgkmcnt(0)
	s_barrier
	s_setprio 1
	s_waitcnt lgkmcnt(0)
	v_mfma_f32_16x16x32_bf16 v[142:145], v[74:77], v[178:181], v[142:145]
	v_mfma_f32_16x16x32_bf16 v[138:141], v[98:101], v[178:181], v[138:141]
	v_mfma_f32_16x16x32_bf16 v[134:137], v[74:77], v[186:189], v[134:137]
	v_mfma_f32_16x16x32_bf16 v[130:133], v[98:101], v[186:189], v[130:133]
	v_mfma_f32_16x16x32_bf16 v[126:129], v[74:77], v[194:197], v[126:129]
	v_mfma_f32_16x16x32_bf16 v[122:125], v[98:101], v[194:197], v[122:125]
	v_mfma_f32_16x16x32_bf16 v[118:121], v[74:77], v[202:205], v[118:121]
	v_mfma_f32_16x16x32_bf16 v[114:117], v[98:101], v[202:205], v[114:117]
	v_mfma_f32_16x16x32_bf16 v[142:145], v[78:81], v[182:185], v[142:145]
	v_mfma_f32_16x16x32_bf16 v[138:141], v[102:105], v[182:185], v[138:141]
	v_mfma_f32_16x16x32_bf16 v[134:137], v[78:81], v[190:193], v[134:137]
	v_mfma_f32_16x16x32_bf16 v[130:133], v[102:105], v[190:193], v[130:133]
	v_mfma_f32_16x16x32_bf16 v[126:129], v[78:81], v[198:201], v[126:129]
	v_mfma_f32_16x16x32_bf16 v[122:125], v[102:105], v[198:201], v[122:125]
	v_mfma_f32_16x16x32_bf16 v[118:121], v[78:81], v[212:215], v[118:121]
	v_mfma_f32_16x16x32_bf16 v[114:117], v[102:105], v[212:215], v[114:117]
	s_setprio 0
	s_setprio 1
	v_mfma_f32_16x16x32_bf16 v[70:73], v[146:149], v[178:181], v[70:73]
	v_mfma_f32_16x16x32_bf16 v[66:69], v[154:157], v[178:181], v[66:69]
	v_mfma_f32_16x16x32_bf16 v[62:65], v[146:149], v[186:189], v[62:65]
	v_mfma_f32_16x16x32_bf16 v[58:61], v[154:157], v[186:189], v[58:61]
	v_mfma_f32_16x16x32_bf16 v[54:57], v[146:149], v[194:197], v[54:57]
	v_mfma_f32_16x16x32_bf16 v[50:53], v[154:157], v[194:197], v[50:53]
	v_mfma_f32_16x16x32_bf16 v[46:49], v[146:149], v[202:205], v[46:49]
	v_mfma_f32_16x16x32_bf16 v[42:45], v[154:157], v[202:205], v[42:45]
	v_mfma_f32_16x16x32_bf16 v[70:73], v[150:153], v[182:185], v[70:73]
	v_mfma_f32_16x16x32_bf16 v[66:69], v[158:161], v[182:185], v[66:69]
	v_mfma_f32_16x16x32_bf16 v[62:65], v[150:153], v[190:193], v[62:65]
	v_mfma_f32_16x16x32_bf16 v[58:61], v[158:161], v[190:193], v[58:61]
	v_mfma_f32_16x16x32_bf16 v[54:57], v[150:153], v[198:201], v[54:57]
	v_mfma_f32_16x16x32_bf16 v[50:53], v[158:161], v[198:201], v[50:53]
	v_mfma_f32_16x16x32_bf16 v[46:49], v[150:153], v[212:215], v[46:49]
	v_mfma_f32_16x16x32_bf16 v[42:45], v[158:161], v[212:215], v[42:45]
	s_setprio 0
	s_barrier
	s_add_u32 s4, s10, 0x80
	s_addc_u32 s5, s11, 0
	s_add_i32 s12, s56, s17
	ds_read_b128 v[178:181], v210 offset:49152
	ds_read_b128 v[182:185], v210 offset:50176
	ds_read_b128 v[186:189], v210 offset:51200
	ds_read_b128 v[190:193], v210 offset:52224
	ds_read_b128 v[194:197], v210 offset:53248
	ds_read_b128 v[198:201], v210 offset:54272
	ds_read_b128 v[202:205], v210 offset:55296
	ds_read_b128 v[212:215], v210 offset:56320
	s_mov_b32 m0, s12
	s_nop 0
	global_load_lds_dwordx4 v162, s[4:5]
	s_add_i32 m0, s12, 0x2000
	s_nop 0
	global_load_lds_dwordx4 v206, s[4:5]
	s_add_u32 s4, s10, 0x80080
	s_addc_u32 s5, s11, 0
	s_add_i32 s10, s57, s17
	s_mov_b32 m0, s10
	s_nop 0
	global_load_lds_dwordx4 v162, s[4:5]
	s_add_i32 m0, s10, 0x2000
	s_nop 0
	global_load_lds_dwordx4 v206, s[4:5]
	s_mov_b32 m0, s26
	s_nop 0
	global_load_lds_dwordx4 v1, s[8:9]
	s_mov_b32 m0, s27
	s_nop 0
	global_load_lds_dwordx4 v164, s[8:9]
	s_waitcnt vmcnt(8)
	s_waitcnt lgkmcnt(0)
	s_barrier
	s_setprio 1
	s_waitcnt lgkmcnt(0)
	v_mfma_f32_16x16x32_bf16 v[110:113], v[74:77], v[178:181], v[110:113]
	v_mfma_f32_16x16x32_bf16 v[94:97], v[74:77], v[186:189], v[94:97]
	v_mfma_f32_16x16x32_bf16 v[86:89], v[74:77], v[194:197], v[86:89]
	v_mfma_f32_16x16x32_bf16 v[26:29], v[74:77], v[202:205], v[26:29]
	v_mfma_f32_16x16x32_bf16 v[110:113], v[78:81], v[182:185], v[110:113]
	v_mfma_f32_16x16x32_bf16 v[106:109], v[98:101], v[178:181], v[106:109]
	v_mfma_f32_16x16x32_bf16 v[94:97], v[78:81], v[190:193], v[94:97]
	v_mfma_f32_16x16x32_bf16 v[90:93], v[98:101], v[186:189], v[90:93]
	v_mfma_f32_16x16x32_bf16 v[86:89], v[78:81], v[198:201], v[86:89]
	v_mfma_f32_16x16x32_bf16 v[82:85], v[98:101], v[194:197], v[82:85]
	v_mfma_f32_16x16x32_bf16 v[78:81], v[78:81], v[212:215], v[26:29]
	v_mfma_f32_16x16x32_bf16 v[26:29], v[98:101], v[202:205], v[30:33]
	v_mfma_f32_16x16x32_bf16 v[106:109], v[102:105], v[182:185], v[106:109]
	v_mfma_f32_16x16x32_bf16 v[90:93], v[102:105], v[190:193], v[90:93]
	v_mfma_f32_16x16x32_bf16 v[82:85], v[102:105], v[198:201], v[82:85]
	v_mfma_f32_16x16x32_bf16 v[74:77], v[102:105], v[212:215], v[26:29]
	s_setprio 0
	s_setprio 1
	v_mfma_f32_16x16x32_bf16 v[26:29], v[146:149], v[178:181], v[38:41]
	v_mfma_f32_16x16x32_bf16 v[38:41], v[150:153], v[182:185], v[26:29]
	v_mfma_f32_16x16x32_bf16 v[26:29], v[154:157], v[178:181], v[34:37]
	v_mfma_f32_16x16x32_bf16 v[22:25], v[146:149], v[186:189], v[22:25]
	v_mfma_f32_16x16x32_bf16 v[18:21], v[154:157], v[186:189], v[18:21]
	v_mfma_f32_16x16x32_bf16 v[14:17], v[146:149], v[194:197], v[14:17]
	v_mfma_f32_16x16x32_bf16 v[10:13], v[154:157], v[194:197], v[10:13]
	v_mfma_f32_16x16x32_bf16 v[6:9], v[146:149], v[202:205], v[6:9]
	v_mfma_f32_16x16x32_bf16 v[2:5], v[154:157], v[202:205], v[2:5]
	v_mfma_f32_16x16x32_bf16 v[34:37], v[158:161], v[182:185], v[26:29]
	v_mfma_f32_16x16x32_bf16 v[22:25], v[150:153], v[190:193], v[22:25]
	v_mfma_f32_16x16x32_bf16 v[18:21], v[158:161], v[190:193], v[18:21]
	v_mfma_f32_16x16x32_bf16 v[14:17], v[150:153], v[198:201], v[14:17]
	v_mfma_f32_16x16x32_bf16 v[10:13], v[158:161], v[198:201], v[10:13]
	v_mfma_f32_16x16x32_bf16 v[6:9], v[150:153], v[212:215], v[6:9]
	v_mfma_f32_16x16x32_bf16 v[2:5], v[158:161], v[212:215], v[2:5]
	s_setprio 0
	s_barrier
;     __device__ __forceinline__ void operator()(const f32x4 (&acc)[2][2][4][2], const Unit& u, int wr, int wc, int fr, int fq) const {
;         const int row0 = u.pm * BM + wr * 64 + fr, col0 = u.pn * BM + wc * 32 + 8 * fq, b = (u.pm * BM) / rows_per_batch;
;         const float* g = gate + (size_t)b * gate_bstride + col0;
;         float ssq[2][4];
; #pragma unroll
;         for (int ai = 0; ai < 2; ++ai)
; #pragma unroll
;             for (int m = 0; m < 4; ++m) ssq[ai][m] = 0.f;
;         f32x4 gv[2][2], Gv[2][2];
; #pragma unroll
;         for (int bj = 0; bj < 2; ++bj) { gv[bj][0] = *(const f32x4*)(g + bj * HALF); gv[bj][1] = *(const f32x4*)(g + bj * HALF + 4); Gv[bj][0] = (f32x4){0.f, 0.f, 0.f, 0.f}; Gv[bj][1] = (f32x4){0.f, 0.f, 0.f, 0.f};
;             if (Hn) { const float* sc = scnext + (size_t)b * gate_bstride + col0 + bj * HALF;
;                 Gv[bj][0] = *(const f32x4*)(gnext + col0 + bj * HALF) * (1.0f + *(const f32x4*)(sc)); Gv[bj][1] = *(const f32x4*)(gnext + col0 + bj * HALF + 4) * (1.0f + *(const f32x4*)(sc + 4)); } }
; #pragma unroll
;         for (int bj = 0; bj < 2; ++bj) {
;             const f32x4 g0 = gv[bj][0], g1 = gv[bj][1], G0 = Gv[bj][0], G1 = Gv[bj][1];
; #pragma unroll
;             for (int ai = 0; ai < 2; ++ai)
; #pragma unroll
;                 for (int m = 0; m < 4; ++m) { const size_t off = (size_t)(row0 + ai * HALF + m * 16) * 2048 + col0 + bj * HALF;
;                     f32x4 x0 = __builtin_nontemporal_load((const f32x4*)(base + off)), x1 = __builtin_nontemporal_load((const f32x4*)(base + off + 4));
;                     if constexpr (HAS_DIN) { const u32x4 dw = __builtin_nontemporal_load((const u32x4*)(dbuf + off));
;                         x0 += (f32x4){__builtin_bit_cast(float, dw.x << 16), __builtin_bit_cast(float, dw.x & 0xffff0000u), __builtin_bit_cast(float, dw.y << 16), __builtin_bit_cast(float, dw.y & 0xffff0000u)};
;                         x1 += (f32x4){__builtin_bit_cast(float, dw.z << 16), __builtin_bit_cast(float, dw.z & 0xffff0000u), __builtin_bit_cast(float, dw.w << 16), __builtin_bit_cast(float, dw.w & 0xffff0000u)}; }
;                     f32x4 o0, o1;
;                     if constexpr (OUT_DELTA) { const f32x4 d0 = g0 * acc[ai][bj][m][0], d1 = g1 * acc[ai][bj][m][1];
	s_add_i32 s51, s51, 2
	s_add_u32 s40, s40, 0x100
	s_addc_u32 s49, s49, 0
	s_cmp_gt_u32 s51, 29
	s_mov_b64 s[4:5], s[6:7]
	s_cbranch_scc0 .LBB0_555
	s_ashr_i32 s4, s29, 31
	s_lshr_b32 s4, s4, 27
	s_add_i32 s4, s29, s4
	s_ashr_i32 s4, s4, 5
	v_lshl_or_b32 v148, s33, 8, v209
	s_mul_i32 s7, s4, 0xc000
	v_ashrrev_i32_e32 v149, 31, v148
	s_mul_hi_i32 s6, s4, 0xc000
	s_add_u32 s4, s22, s7
	s_addc_u32 s5, s23, s6
	v_lshlrev_b64 v[26:27], 2, v[148:149]
	v_lshl_add_u64 v[146:147], s[4:5], 0, v[26:27]
	s_add_u32 s4, s24, s7
	s_addc_u32 s5, s25, s6
	v_lshl_add_u64 v[160:161], s[4:5], 0, v[26:27]
	v_lshl_add_u64 v[178:179], s[46:47], 0, v[26:27]
	global_load_dwordx4 v[98:101], v[146:147], off offset:16
	global_load_dwordx4 v[102:105], v[146:147], off
	global_load_dwordx4 v[26:29], v[178:179], off offset:16
	global_load_dwordx4 v[30:33], v[178:179], off
	global_load_dwordx4 v[150:153], v[160:161], off offset:16
	global_load_dwordx4 v[154:157], v[160:161], off
	s_mov_b64 s[4:5], 0x40000
	s_waitcnt vmcnt(0)
	v_pk_mul_f32 v[188:189], v[140:141], v[100:101]
	v_pk_mul_f32 v[142:143], v[142:143], v[102:103]
	v_pk_mul_f32 v[144:145], v[144:145], v[104:105]
	v_pk_mul_f32 v[140:141], v[138:139], v[98:99]
	v_pk_mul_f32 v[136:137], v[136:137], v[104:105]
	v_pk_add_f32 v[156:157], v[156:157], 1.0 op_sel_hi:[1,0]
	v_pk_add_f32 v[154:155], v[154:155], 1.0 op_sel_hi:[1,0]
	v_pk_mul_f32 v[198:199], v[32:33], v[156:157]
	v_pk_mul_f32 v[200:201], v[30:31], v[154:155]
	v_pk_add_f32 v[30:31], v[152:153], 1.0 op_sel_hi:[1,0]
	v_pk_add_f32 v[32:33], v[150:151], 1.0 op_sel_hi:[1,0]
	v_pk_mul_f32 v[202:203], v[28:29], v[30:31]
	v_pk_mul_f32 v[204:205], v[26:27], v[32:33]
	global_load_dwordx4 v[26:29], v[146:147], off offset:528
	global_load_dwordx4 v[30:33], v[146:147], off offset:512
	global_load_dwordx4 v[156:159], v[178:179], off offset:528
	global_load_dwordx4 v[152:155], v[178:179], off offset:512
	s_nop 0
	global_load_dwordx4 v[178:181], v[160:161], off offset:528
	global_load_dwordx4 v[182:185], v[160:161], off offset:512
	v_pk_mul_f32 v[134:135], v[134:135], v[102:103]
	v_pk_mul_f32 v[130:131], v[130:131], v[98:99]
	v_pk_mul_f32 v[132:133], v[132:133], v[100:101]
	v_pk_mul_f32 v[128:129], v[128:129], v[104:105]
	v_pk_mul_f32 v[126:127], v[126:127], v[102:103]
	v_pk_mul_f32 v[122:123], v[122:123], v[98:99]
	v_pk_mul_f32 v[124:125], v[124:125], v[100:101]
	v_pk_mul_f32 v[120:121], v[120:121], v[104:105]
	v_pk_mul_f32 v[118:119], v[118:119], v[102:103]
	v_pk_mul_f32 v[114:115], v[114:115], v[98:99]
	v_pk_mul_f32 v[116:117], v[116:117], v[100:101]
	v_pk_mul_f32 v[112:113], v[112:113], v[104:105]
	v_pk_mul_f32 v[110:111], v[110:111], v[102:103]
	v_pk_mul_f32 v[106:107], v[106:107], v[98:99]
	v_pk_mul_f32 v[108:109], v[108:109], v[100:101]
	v_pk_mul_f32 v[96:97], v[96:97], v[104:105]
	v_pk_mul_f32 v[94:95], v[94:95], v[102:103]
	v_pk_mul_f32 v[90:91], v[90:91], v[98:99]
	v_pk_mul_f32 v[92:93], v[92:93], v[100:101]
	v_pk_mul_f32 v[88:89], v[88:89], v[104:105]
	v_pk_mul_f32 v[86:87], v[86:87], v[102:103]
	v_pk_mul_f32 v[82:83], v[82:83], v[98:99]
	v_pk_mul_f32 v[84:85], v[84:85], v[100:101]
	v_pk_mul_f32 v[80:81], v[80:81], v[104:105]
	v_pk_mul_f32 v[78:79], v[78:79], v[102:103]
	v_pk_mul_f32 v[74:75], v[74:75], v[98:99]
	v_pk_mul_f32 v[76:77], v[76:77], v[100:101]
	s_waitcnt vmcnt(5)
	v_pk_mul_f32 v[58:59], v[58:59], v[26:27]
	s_waitcnt vmcnt(4)
	v_pk_mul_f32 v[72:73], v[72:73], v[32:33]
	v_pk_mul_f32 v[70:71], v[70:71], v[30:31]
	v_pk_mul_f32 v[64:65], v[64:65], v[32:33]
	v_pk_mul_f32 v[62:63], v[62:63], v[30:31]
	s_waitcnt vmcnt(0)
	v_pk_add_f32 v[146:147], v[184:185], 1.0 op_sel_hi:[1,0]
	v_pk_add_f32 v[160:161], v[182:183], 1.0 op_sel_hi:[1,0]
	v_pk_mul_f32 v[150:151], v[154:155], v[146:147]
	v_pk_add_f32 v[146:147], v[180:181], 1.0 op_sel_hi:[1,0]
	v_pk_mul_f32 v[152:153], v[152:153], v[160:161]
	v_pk_mul_f32 v[154:155], v[158:159], v[146:147]
	v_lshl_add_u32 v146, s29, 8, v207
	v_ashrrev_i32_e32 v147, 31, v146
	v_lshlrev_b64 v[184:185], 11, v[146:147]
	v_lshl_add_u64 v[186:187], v[184:185], 0, v[148:149]
	v_pk_add_f32 v[160:161], v[178:179], 1.0 op_sel_hi:[1,0]
	v_lshl_add_u64 v[178:179], v[186:187], 2, s[44:45]
	v_pk_mul_f32 v[156:157], v[156:157], v[160:161]
	global_load_dwordx4 v[158:161], v[178:179], off nt
	global_load_dwordx4 v[180:183], v[178:179], off offset:16 nt
	v_cvt_pk_bf16_f32 v138, v142, v143
	v_lshlrev_b64 v[142:143], 1, v[186:187]
	v_cvt_pk_bf16_f32 v139, v144, v145
	v_cvt_pk_bf16_f32 v140, v140, v141
	v_cvt_pk_bf16_f32 v141, v188, v189
	v_lshl_add_u64 v[144:145], s[90:91], 0, v[142:143]
	global_store_dwordx4 v[144:145], v[138:141], off
	v_lshlrev_b32_e32 v144, 16, v140
	v_and_b32_e32 v145, 0xffff0000, v140
	v_lshlrev_b32_e32 v140, 16, v141
	v_and_b32_e32 v141, 0xffff0000, v141
	v_lshl_add_u64 v[142:143], s[96:97], 0, v[142:143]
	v_pk_mul_f32 v[60:61], v[60:61], v[28:29]
	v_pk_mul_f32 v[56:57], v[56:57], v[32:33]
	v_pk_mul_f32 v[54:55], v[54:55], v[30:31]
	v_pk_mul_f32 v[50:51], v[50:51], v[26:27]
	v_pk_mul_f32 v[52:53], v[52:53], v[28:29]
	v_pk_mul_f32 v[48:49], v[48:49], v[32:33]
	v_pk_mul_f32 v[46:47], v[46:47], v[30:31]
	v_pk_mul_f32 v[42:43], v[42:43], v[26:27]
	v_pk_mul_f32 v[44:45], v[44:45], v[28:29]
	v_pk_mul_f32 v[40:41], v[40:41], v[32:33]
	v_pk_mul_f32 v[38:39], v[38:39], v[30:31]
	v_pk_mul_f32 v[34:35], v[34:35], v[26:27]
	v_pk_mul_f32 v[36:37], v[36:37], v[28:29]
	v_pk_mul_f32 v[24:25], v[24:25], v[32:33]
	v_pk_mul_f32 v[22:23], v[22:23], v[30:31]
	v_pk_mul_f32 v[18:19], v[18:19], v[26:27]
	v_pk_mul_f32 v[20:21], v[20:21], v[28:29]
	v_pk_mul_f32 v[16:17], v[16:17], v[32:33]
	v_pk_mul_f32 v[14:15], v[14:15], v[30:31]
	v_pk_mul_f32 v[10:11], v[10:11], v[26:27]
	v_pk_mul_f32 v[12:13], v[12:13], v[28:29]
	v_pk_mul_f32 v[8:9], v[8:9], v[32:33]
	v_pk_mul_f32 v[6:7], v[6:7], v[30:31]
	v_pk_mul_f32 v[2:3], v[2:3], v[26:27]
	v_pk_mul_f32 v[4:5], v[4:5], v[28:29]
	s_waitcnt vmcnt(1)
; __device__ __forceinline__ unsigned cvt_pk_bf16(float lo, float hi) { unsigned r; asm volatile("v_cvt_pk_bf16_f32 %0, %1, %2" : "=v"(r) : "v"(lo), "v"(hi)); return r; }
;     __device__ __forceinline__ void operator()(const f32x4 (&acc)[2][2][4][2], const Unit& u, int wr, int wc, int fr, int fq) const {
;     ...
;                 for (int m = 0; m < 4; ++m) { const size_t off = (size_t)(row0 + ai * HALF + m * 16) * 2048 + col0 + bj * HALF;
;                     f32x4 x0 = __builtin_nontemporal_load((const f32x4*)(base + off)), x1 = __builtin_nontemporal_load((const f32x4*)(base + off + 4));
;                     if constexpr (HAS_DIN) { const u32x4 dw = __builtin_nontemporal_load((const u32x4*)(dbuf + off));
;                         x0 += (f32x4){__builtin_bit_cast(float, dw.x << 16), __builtin_bit_cast(float, dw.x & 0xffff0000u), __builtin_bit_cast(float, dw.y << 16), __builtin_bit_cast(float, dw.y & 0xffff0000u)};
;                         x1 += (f32x4){__builtin_bit_cast(float, dw.z << 16), __builtin_bit_cast(float, dw.z & 0xffff0000u), __builtin_bit_cast(float, dw.w << 16), __builtin_bit_cast(float, dw.w & 0xffff0000u)}; }
;                     f32x4 o0, o1;
;                     if constexpr (OUT_DELTA) { const f32x4 d0 = g0 * acc[ai][bj][m][0], d1 = g1 * acc[ai][bj][m][1];
;                         u32x4 w; w.x = cvt_pk_bf16(d0[0], d0[1]); w.y = cvt_pk_bf16(d0[2], d0[3]); w.z = cvt_pk_bf16(d1[0], d1[1]); w.w = cvt_pk_bf16(d1[2], d1[3]);
;                         *(u32x4*)(dbuf + off) = w;
;                         o0 = x0 + (f32x4){__builtin_bit_cast(float, w.x << 16), __builtin_bit_cast(float, w.x & 0xffff0000u), __builtin_bit_cast(float, w.y << 16), __builtin_bit_cast(float, w.y & 0xffff0000u)};
;                         o1 = x1 + (f32x4){__builtin_bit_cast(float, w.z << 16), __builtin_bit_cast(float, w.z & 0xffff0000u), __builtin_bit_cast(float, w.w << 16), __builtin_bit_cast(float, w.w & 0xffff0000u)}; }
;                     else { o0 = x0 + g0 * acc[ai][bj][m][0]; o1 = x1 + g1 * acc[ai][bj][m][1]; *(f32x4*)(out + off) = o0; *(f32x4*)(out + off + 4) = o1; }
;                     if (Hn) { const f32x4 h0 = o0 * G0, h1 = o1 * G1;
;                         u32x4 w; w.x = cvt_pk_bf16(h0[0], h0[1]); w.y = cvt_pk_bf16(h0[2], h0[3]); w.z = cvt_pk_bf16(h1[0], h1[1]); w.w = cvt_pk_bf16(h1[2], h1[3]);
;                         *(u32x4*)(Hn + off) = w;
	v_pk_add_f32 v[182:183], v[182:183], v[140:141]
	v_lshlrev_b32_e32 v140, 16, v138
	v_and_b32_e32 v141, 0xffff0000, v138
	v_lshlrev_b32_e32 v138, 16, v139
	v_and_b32_e32 v139, 0xffff0000, v139
	v_pk_add_f32 v[158:159], v[158:159], v[140:141]
	v_pk_add_f32 v[160:161], v[160:161], v[138:139]
	v_pk_mul_f32 v[138:139], v[200:201], v[158:159]
	v_pk_add_f32 v[144:145], v[180:181], v[144:145]
	v_pk_mul_f32 v[140:141], v[198:199], v[160:161]
	v_cvt_pk_bf16_f32 v138, v138, v139
	v_pk_mul_f32 v[180:181], v[202:203], v[182:183]
	v_cvt_pk_bf16_f32 v139, v140, v141
	v_pk_mul_f32 v[186:187], v[204:205], v[144:145]
	s_nop 0
	v_cvt_pk_bf16_f32 v140, v186, v187
	v_cvt_pk_bf16_f32 v141, v180, v181
	global_store_dwordx4 v[142:143], v[138:141], off
	s_nop 1
	v_mul_f32_e32 v138, v159, v159
	v_mul_f32_e32 v139, v161, v161
	v_fmac_f32_e32 v138, v158, v158
	v_fmac_f32_e32 v139, v160, v160
	v_add_f32_e32 v138, v138, v139
	v_mul_f32_e32 v139, v145, v145
	v_mul_f32_e32 v140, v183, v183
	v_fmac_f32_e32 v139, v144, v144
	v_fmac_f32_e32 v140, v182, v182
	v_add_f32_e32 v139, v139, v140
	v_add_f32_e32 v211, v138, v139
	v_or_b32_e32 v138, 16, v146
	v_ashrrev_i32_e32 v139, 31, v138
	v_lshlrev_b64 v[140:141], 11, v[138:139]
	v_lshl_add_u64 v[180:181], v[140:141], 0, v[148:149]
	v_lshl_add_u64 v[138:139], v[180:181], 2, s[44:45]
	global_load_dwordx4 v[142:145], v[138:139], off nt
	global_load_dwordx4 v[158:161], v[138:139], off offset:16 nt
	v_lshlrev_b64 v[180:181], 1, v[180:181]
	v_cvt_pk_bf16_f32 v134, v134, v135
	v_cvt_pk_bf16_f32 v135, v136, v137
	v_cvt_pk_bf16_f32 v136, v130, v131
	v_cvt_pk_bf16_f32 v137, v132, v133
	v_lshl_add_u64 v[130:131], s[90:91], 0, v[180:181]
	global_store_dwordx4 v[130:131], v[134:137], off
	v_lshlrev_b32_e32 v132, 16, v136
	v_and_b32_e32 v133, 0xffff0000, v136
	v_lshlrev_b32_e32 v130, 16, v137
	v_and_b32_e32 v131, 0xffff0000, v137
	v_lshlrev_b32_e32 v136, 16, v134
	v_and_b32_e32 v137, 0xffff0000, v134
	v_lshlrev_b32_e32 v134, 16, v135
	v_and_b32_e32 v135, 0xffff0000, v135
	s_waitcnt vmcnt(2)
	v_pk_add_f32 v[134:135], v[144:145], v[134:135]
	s_waitcnt vmcnt(1)
	v_pk_add_f32 v[130:131], v[160:161], v[130:131]
	v_pk_add_f32 v[136:137], v[142:143], v[136:137]
	v_pk_add_f32 v[132:133], v[158:159], v[132:133]
	v_pk_mul_f32 v[144:145], v[198:199], v[134:135]
	v_pk_mul_f32 v[142:143], v[200:201], v[136:137]
	v_pk_mul_f32 v[158:159], v[202:203], v[130:131]
	v_pk_mul_f32 v[160:161], v[204:205], v[132:133]
	v_cvt_pk_bf16_f32 v142, v142, v143
	v_cvt_pk_bf16_f32 v143, v144, v145
	s_nop 0
	v_cvt_pk_bf16_f32 v144, v160, v161
	v_cvt_pk_bf16_f32 v145, v158, v159
	v_lshl_add_u64 v[158:159], s[96:97], 0, v[180:181]
	global_store_dwordx4 v[158:159], v[142:145], off
	s_nop 1
	v_or_b32_e32 v142, 32, v146
	v_ashrrev_i32_e32 v143, 31, v142
	v_lshlrev_b64 v[144:145], 11, v[142:143]
	v_lshl_add_u64 v[186:187], v[144:145], 0, v[148:149]
	v_lshl_add_u64 v[142:143], v[186:187], 2, s[44:45]
	global_load_dwordx4 v[158:161], v[142:143], off nt
	global_load_dwordx4 v[180:183], v[142:143], off offset:16 nt
	v_lshlrev_b64 v[186:187], 1, v[186:187]
	v_cvt_pk_bf16_f32 v126, v126, v127
	v_cvt_pk_bf16_f32 v127, v128, v129
	v_cvt_pk_bf16_f32 v128, v122, v123
	v_cvt_pk_bf16_f32 v129, v124, v125
	v_lshl_add_u64 v[122:123], s[90:91], 0, v[186:187]
	global_store_dwordx4 v[122:123], v[126:129], off
	v_lshlrev_b32_e32 v124, 16, v128
	v_and_b32_e32 v125, 0xffff0000, v128
	v_lshlrev_b32_e32 v122, 16, v129
	v_and_b32_e32 v123, 0xffff0000, v129
	v_lshlrev_b32_e32 v128, 16, v126
	v_and_b32_e32 v129, 0xffff0000, v126
	v_lshlrev_b32_e32 v126, 16, v127
	v_and_b32_e32 v127, 0xffff0000, v127
	s_waitcnt vmcnt(2)
	v_pk_add_f32 v[126:127], v[160:161], v[126:127]
	s_waitcnt vmcnt(1)
	v_pk_add_f32 v[122:123], v[182:183], v[122:123]
	v_pk_add_f32 v[128:129], v[158:159], v[128:129]
	v_pk_add_f32 v[124:125], v[180:181], v[124:125]
	v_pk_mul_f32 v[160:161], v[198:199], v[126:127]
	v_pk_mul_f32 v[158:159], v[200:201], v[128:129]
	v_pk_mul_f32 v[180:181], v[202:203], v[122:123]
	v_pk_mul_f32 v[182:183], v[204:205], v[124:125]
	v_cvt_pk_bf16_f32 v158, v158, v159
	v_cvt_pk_bf16_f32 v159, v160, v161
	s_nop 0
	v_cvt_pk_bf16_f32 v160, v182, v183
	v_cvt_pk_bf16_f32 v161, v180, v181
	v_lshl_add_u64 v[180:181], s[96:97], 0, v[186:187]
	global_store_dwordx4 v[180:181], v[158:161], off
	s_nop 1
	v_or_b32_e32 v158, 48, v146
	v_ashrrev_i32_e32 v159, 31, v158
	v_lshlrev_b64 v[160:161], 11, v[158:159]
	v_lshl_add_u64 v[190:191], v[160:161], 0, v[148:149]
	v_lshl_add_u64 v[158:159], v[190:191], 2, s[44:45]
	global_load_dwordx4 v[180:183], v[158:159], off nt
	global_load_dwordx4 v[186:189], v[158:159], off offset:16 nt
	v_lshlrev_b64 v[190:191], 1, v[190:191]
	v_cvt_pk_bf16_f32 v118, v118, v119
	v_cvt_pk_bf16_f32 v119, v120, v121
	v_cvt_pk_bf16_f32 v120, v114, v115
	v_cvt_pk_bf16_f32 v121, v116, v117
	v_lshl_add_u64 v[114:115], s[90:91], 0, v[190:191]
	global_store_dwordx4 v[114:115], v[118:121], off
	v_lshlrev_b32_e32 v116, 16, v120
	v_and_b32_e32 v117, 0xffff0000, v120
	v_lshlrev_b32_e32 v114, 16, v121
	v_and_b32_e32 v115, 0xffff0000, v121
	v_lshlrev_b32_e32 v120, 16, v118
	v_and_b32_e32 v121, 0xffff0000, v118
	v_lshlrev_b32_e32 v118, 16, v119
	v_and_b32_e32 v119, 0xffff0000, v119
	s_waitcnt vmcnt(2)
	v_pk_add_f32 v[118:119], v[182:183], v[118:119]
	s_waitcnt vmcnt(1)
; __device__ __forceinline__ unsigned cvt_pk_bf16(float lo, float hi) { unsigned r; asm volatile("v_cvt_pk_bf16_f32 %0, %1, %2" : "=v"(r) : "v"(lo), "v"(hi)); return r; }
;     __device__ __forceinline__ void operator()(const f32x4 (&acc)[2][2][4][2], const Unit& u, int wr, int wc, int fr, int fq) const {
;     ...
;                 for (int m = 0; m < 4; ++m) { const size_t off = (size_t)(row0 + ai * HALF + m * 16) * 2048 + col0 + bj * HALF;
;                     f32x4 x0 = __builtin_nontemporal_load((const f32x4*)(base + off)), x1 = __builtin_nontemporal_load((const f32x4*)(base + off + 4));
;                     if constexpr (HAS_DIN) { const u32x4 dw = __builtin_nontemporal_load((const u32x4*)(dbuf + off));
;                         x0 += (f32x4){__builtin_bit_cast(float, dw.x << 16), __builtin_bit_cast(float, dw.x & 0xffff0000u), __builtin_bit_cast(float, dw.y << 16), __builtin_bit_cast(float, dw.y & 0xffff0000u)};
;                         x1 += (f32x4){__builtin_bit_cast(float, dw.z << 16), __builtin_bit_cast(float, dw.z & 0xffff0000u), __builtin_bit_cast(float, dw.w << 16), __builtin_bit_cast(float, dw.w & 0xffff0000u)}; }
;                     f32x4 o0, o1;
;                     if constexpr (OUT_DELTA) { const f32x4 d0 = g0 * acc[ai][bj][m][0], d1 = g1 * acc[ai][bj][m][1];
;                         u32x4 w; w.x = cvt_pk_bf16(d0[0], d0[1]); w.y = cvt_pk_bf16(d0[2], d0[3]); w.z = cvt_pk_bf16(d1[0], d1[1]); w.w = cvt_pk_bf16(d1[2], d1[3]);
;                         *(u32x4*)(dbuf + off) = w;
;                         o0 = x0 + (f32x4){__builtin_bit_cast(float, w.x << 16), __builtin_bit_cast(float, w.x & 0xffff0000u), __builtin_bit_cast(float, w.y << 16), __builtin_bit_cast(float, w.y & 0xffff0000u)};
;                         o1 = x1 + (f32x4){__builtin_bit_cast(float, w.z << 16), __builtin_bit_cast(float, w.z & 0xffff0000u), __builtin_bit_cast(float, w.w << 16), __builtin_bit_cast(float, w.w & 0xffff0000u)}; }
;                     else { o0 = x0 + g0 * acc[ai][bj][m][0]; o1 = x1 + g1 * acc[ai][bj][m][1]; *(f32x4*)(out + off) = o0; *(f32x4*)(out + off + 4) = o1; }
;                     if (Hn) { const f32x4 h0 = o0 * G0, h1 = o1 * G1;
;                         u32x4 w; w.x = cvt_pk_bf16(h0[0], h0[1]); w.y = cvt_pk_bf16(h0[2], h0[3]); w.z = cvt_pk_bf16(h1[0], h1[1]); w.w = cvt_pk_bf16(h1[2], h1[3]);
;                         *(u32x4*)(Hn + off) = w;
	v_pk_add_f32 v[114:115], v[188:189], v[114:115]
	v_pk_add_f32 v[120:121], v[180:181], v[120:121]
	v_pk_add_f32 v[116:117], v[186:187], v[116:117]
	v_pk_mul_f32 v[182:183], v[198:199], v[118:119]
	v_pk_mul_f32 v[180:181], v[200:201], v[120:121]
	v_pk_mul_f32 v[186:187], v[202:203], v[114:115]
	v_pk_mul_f32 v[188:189], v[204:205], v[116:117]
	v_cvt_pk_bf16_f32 v180, v180, v181
	v_cvt_pk_bf16_f32 v181, v182, v183
	s_nop 0
	v_cvt_pk_bf16_f32 v182, v188, v189
	v_cvt_pk_bf16_f32 v183, v186, v187
	v_lshl_add_u64 v[186:187], s[96:97], 0, v[190:191]
	global_store_dwordx4 v[186:187], v[180:183], off
	s_nop 1
	v_lshl_add_u64 v[182:183], v[184:185], 0, s[4:5]
	v_lshl_add_u64 v[194:195], v[182:183], 0, v[148:149]
	v_lshl_add_u64 v[180:181], v[194:195], 2, s[44:45]
	global_load_dwordx4 v[186:189], v[180:181], off nt
	global_load_dwordx4 v[190:193], v[180:181], off offset:16 nt
	v_lshlrev_b64 v[194:195], 1, v[194:195]
	v_cvt_pk_bf16_f32 v110, v110, v111
	v_cvt_pk_bf16_f32 v111, v112, v113
	v_cvt_pk_bf16_f32 v112, v106, v107
	v_cvt_pk_bf16_f32 v113, v108, v109
	v_lshl_add_u64 v[106:107], s[90:91], 0, v[194:195]
	global_store_dwordx4 v[106:107], v[110:113], off
	v_lshlrev_b32_e32 v108, 16, v112
	v_and_b32_e32 v109, 0xffff0000, v112
	v_lshlrev_b32_e32 v106, 16, v113
	v_and_b32_e32 v107, 0xffff0000, v113
	v_lshlrev_b32_e32 v112, 16, v110
	v_and_b32_e32 v113, 0xffff0000, v110
	v_lshlrev_b32_e32 v110, 16, v111
	v_and_b32_e32 v111, 0xffff0000, v111
	s_mov_b64 s[4:5], 0x48000
	s_waitcnt vmcnt(2)
	v_pk_add_f32 v[110:111], v[188:189], v[110:111]
	s_waitcnt vmcnt(1)
	v_pk_add_f32 v[106:107], v[192:193], v[106:107]
	v_pk_add_f32 v[112:113], v[186:187], v[112:113]
	v_pk_add_f32 v[108:109], v[190:191], v[108:109]
	v_pk_mul_f32 v[188:189], v[198:199], v[110:111]
	v_pk_mul_f32 v[186:187], v[200:201], v[112:113]
	v_pk_mul_f32 v[190:191], v[202:203], v[106:107]
	v_pk_mul_f32 v[192:193], v[204:205], v[108:109]
	v_cvt_pk_bf16_f32 v186, v186, v187
	v_cvt_pk_bf16_f32 v187, v188, v189
	s_nop 0
	v_cvt_pk_bf16_f32 v188, v192, v193
	v_cvt_pk_bf16_f32 v189, v190, v191
	v_lshl_add_u64 v[190:191], s[96:97], 0, v[194:195]
	global_store_dwordx4 v[190:191], v[186:189], off
	s_nop 1
	v_lshl_add_u64 v[188:189], v[184:185], 0, s[4:5]
	v_lshl_add_u64 v[212:213], v[188:189], 0, v[148:149]
	v_lshl_add_u64 v[186:187], v[212:213], 2, s[44:45]
	global_load_dwordx4 v[190:193], v[186:187], off nt
	global_load_dwordx4 v[194:197], v[186:187], off offset:16 nt
	v_lshlrev_b64 v[212:213], 1, v[212:213]
	v_cvt_pk_bf16_f32 v94, v94, v95
	v_cvt_pk_bf16_f32 v95, v96, v97
	v_cvt_pk_bf16_f32 v96, v90, v91
	v_cvt_pk_bf16_f32 v97, v92, v93
	v_lshl_add_u64 v[90:91], s[90:91], 0, v[212:213]
	global_store_dwordx4 v[90:91], v[94:97], off
	v_lshlrev_b32_e32 v92, 16, v96
	v_and_b32_e32 v93, 0xffff0000, v96
	v_lshlrev_b32_e32 v90, 16, v97
	v_and_b32_e32 v91, 0xffff0000, v97
	v_lshlrev_b32_e32 v96, 16, v94
	v_and_b32_e32 v97, 0xffff0000, v94
	v_lshlrev_b32_e32 v94, 16, v95
	v_and_b32_e32 v95, 0xffff0000, v95
	s_mov_b64 s[4:5], 0x50000
	s_waitcnt vmcnt(2)
	v_pk_add_f32 v[94:95], v[192:193], v[94:95]
	s_waitcnt vmcnt(1)
	v_pk_add_f32 v[90:91], v[196:197], v[90:91]
	v_pk_add_f32 v[96:97], v[190:191], v[96:97]
	v_pk_add_f32 v[92:93], v[194:195], v[92:93]
	v_pk_mul_f32 v[192:193], v[198:199], v[94:95]
	v_pk_mul_f32 v[190:191], v[200:201], v[96:97]
	v_pk_mul_f32 v[194:195], v[202:203], v[90:91]
	v_pk_mul_f32 v[196:197], v[204:205], v[92:93]
	v_cvt_pk_bf16_f32 v190, v190, v191
	v_cvt_pk_bf16_f32 v191, v192, v193
	s_nop 0
	v_cvt_pk_bf16_f32 v192, v196, v197
	v_cvt_pk_bf16_f32 v193, v194, v195
	v_lshl_add_u64 v[194:195], s[96:97], 0, v[212:213]
	global_store_dwordx4 v[194:195], v[190:193], off
	s_nop 1
	v_lshl_add_u64 v[192:193], v[184:185], 0, s[4:5]
	v_lshl_add_u64 v[220:221], v[192:193], 0, v[148:149]
	v_lshl_add_u64 v[190:191], v[220:221], 2, s[44:45]
	global_load_dwordx4 v[194:197], v[190:191], off nt
	global_load_dwordx4 v[212:215], v[190:191], off offset:16 nt
	v_lshlrev_b64 v[220:221], 1, v[220:221]
	v_cvt_pk_bf16_f32 v86, v86, v87
	v_cvt_pk_bf16_f32 v87, v88, v89
	v_cvt_pk_bf16_f32 v88, v82, v83
	v_cvt_pk_bf16_f32 v89, v84, v85
	v_lshl_add_u64 v[82:83], s[90:91], 0, v[220:221]
	global_store_dwordx4 v[82:83], v[86:89], off
	v_lshlrev_b32_e32 v84, 16, v88
	v_and_b32_e32 v85, 0xffff0000, v88
	v_lshlrev_b32_e32 v82, 16, v89
	v_and_b32_e32 v83, 0xffff0000, v89
	v_lshlrev_b32_e32 v88, 16, v86
	v_and_b32_e32 v89, 0xffff0000, v86
	v_lshlrev_b32_e32 v86, 16, v87
	v_and_b32_e32 v87, 0xffff0000, v87
	s_mov_b64 s[4:5], 0x58000
	s_waitcnt vmcnt(2)
	v_pk_add_f32 v[86:87], v[196:197], v[86:87]
	s_waitcnt vmcnt(1)
	v_pk_add_f32 v[82:83], v[214:215], v[82:83]
	v_pk_add_f32 v[88:89], v[194:195], v[88:89]
	v_pk_add_f32 v[84:85], v[212:213], v[84:85]
	v_pk_mul_f32 v[196:197], v[198:199], v[86:87]
	v_pk_mul_f32 v[194:195], v[200:201], v[88:89]
	v_pk_mul_f32 v[212:213], v[202:203], v[82:83]
	v_pk_mul_f32 v[214:215], v[204:205], v[84:85]
	v_cvt_pk_bf16_f32 v194, v194, v195
	v_cvt_pk_bf16_f32 v195, v196, v197
	s_nop 0
	v_cvt_pk_bf16_f32 v196, v214, v215
	v_cvt_pk_bf16_f32 v197, v212, v213
	v_lshl_add_u64 v[212:213], s[96:97], 0, v[220:221]
	global_store_dwordx4 v[212:213], v[194:197], off
	s_nop 1
	v_lshl_add_u64 v[196:197], v[184:185], 0, s[4:5]
	v_lshl_add_u64 v[224:225], v[196:197], 0, v[148:149]
	v_lshl_add_u64 v[194:195], v[224:225], 2, s[44:45]
	global_load_dwordx4 v[212:215], v[194:195], off nt
	global_load_dwordx4 v[220:223], v[194:195], off offset:16 nt
	v_lshlrev_b64 v[102:103], 1, v[224:225]
	v_cvt_pk_bf16_f32 v78, v78, v79
	v_cvt_pk_bf16_f32 v79, v80, v81
	v_cvt_pk_bf16_f32 v80, v74, v75
	v_cvt_pk_bf16_f32 v81, v76, v77
	v_lshl_add_u64 v[74:75], s[90:91], 0, v[102:103]
	global_store_dwordx4 v[74:75], v[78:81], off
	v_lshlrev_b32_e32 v76, 16, v80
	v_and_b32_e32 v77, 0xffff0000, v80
	v_lshlrev_b32_e32 v74, 16, v81
	v_and_b32_e32 v75, 0xffff0000, v81
	v_lshlrev_b32_e32 v80, 16, v78
	v_and_b32_e32 v81, 0xffff0000, v78
	v_lshlrev_b32_e32 v78, 16, v79
	v_and_b32_e32 v79, 0xffff0000, v79
	v_lshl_add_u64 v[102:103], s[96:97], 0, v[102:103]
	v_or_b32_e32 v148, 0x80, v148
	s_waitcnt vmcnt(2)
; __device__ __forceinline__ unsigned cvt_pk_bf16(float lo, float hi) { unsigned r; asm volatile("v_cvt_pk_bf16_f32 %0, %1, %2" : "=v"(r) : "v"(lo), "v"(hi)); return r; }
;     __device__ __forceinline__ void operator()(const f32x4 (&acc)[2][2][4][2], const Unit& u, int wr, int wc, int fr, int fq) const {
;     ...
;                 for (int m = 0; m < 4; ++m) { const size_t off = (size_t)(row0 + ai * HALF + m * 16) * 2048 + col0 + bj * HALF;
;                     f32x4 x0 = __builtin_nontemporal_load((const f32x4*)(base + off)), x1 = __builtin_nontemporal_load((const f32x4*)(base + off + 4));
;                     if constexpr (HAS_DIN) { const u32x4 dw = __builtin_nontemporal_load((const u32x4*)(dbuf + off));
;                         x0 += (f32x4){__builtin_bit_cast(float, dw.x << 16), __builtin_bit_cast(float, dw.x & 0xffff0000u), __builtin_bit_cast(float, dw.y << 16), __builtin_bit_cast(float, dw.y & 0xffff0000u)};
;                         x1 += (f32x4){__builtin_bit_cast(float, dw.z << 16), __builtin_bit_cast(float, dw.z & 0xffff0000u), __builtin_bit_cast(float, dw.w << 16), __builtin_bit_cast(float, dw.w & 0xffff0000u)}; }
;                     f32x4 o0, o1;
;                     if constexpr (OUT_DELTA) { const f32x4 d0 = g0 * acc[ai][bj][m][0], d1 = g1 * acc[ai][bj][m][1];
;                         u32x4 w; w.x = cvt_pk_bf16(d0[0], d0[1]); w.y = cvt_pk_bf16(d0[2], d0[3]); w.z = cvt_pk_bf16(d1[0], d1[1]); w.w = cvt_pk_bf16(d1[2], d1[3]);
;                         *(u32x4*)(dbuf + off) = w;
;                         o0 = x0 + (f32x4){__builtin_bit_cast(float, w.x << 16), __builtin_bit_cast(float, w.x & 0xffff0000u), __builtin_bit_cast(float, w.y << 16), __builtin_bit_cast(float, w.y & 0xffff0000u)};
;                         o1 = x1 + (f32x4){__builtin_bit_cast(float, w.z << 16), __builtin_bit_cast(float, w.z & 0xffff0000u), __builtin_bit_cast(float, w.w << 16), __builtin_bit_cast(float, w.w & 0xffff0000u)}; }
;                     else { o0 = x0 + g0 * acc[ai][bj][m][0]; o1 = x1 + g1 * acc[ai][bj][m][1]; *(f32x4*)(out + off) = o0; *(f32x4*)(out + off + 4) = o1; }
;                     if (Hn) { const f32x4 h0 = o0 * G0, h1 = o1 * G1;
;                         u32x4 w; w.x = cvt_pk_bf16(h0[0], h0[1]); w.y = cvt_pk_bf16(h0[2], h0[3]); w.z = cvt_pk_bf16(h1[0], h1[1]); w.w = cvt_pk_bf16(h1[2], h1[3]);
;                         *(u32x4*)(Hn + off) = w;
	v_pk_add_f32 v[78:79], v[214:215], v[78:79]
	v_pk_add_f32 v[80:81], v[212:213], v[80:81]
	s_waitcnt vmcnt(1)
	v_pk_add_f32 v[74:75], v[222:223], v[74:75]
	v_pk_add_f32 v[76:77], v[220:221], v[76:77]
	v_pk_mul_f32 v[100:101], v[198:199], v[78:79]
	v_pk_mul_f32 v[98:99], v[200:201], v[80:81]
	v_pk_mul_f32 v[104:105], v[202:203], v[74:75]
	v_pk_mul_f32 v[198:199], v[204:205], v[76:77]
	v_cvt_pk_bf16_f32 v98, v98, v99
	v_cvt_pk_bf16_f32 v99, v100, v101
	s_nop 0
	v_cvt_pk_bf16_f32 v100, v198, v199
	v_cvt_pk_bf16_f32 v101, v104, v105
	global_store_dwordx4 v[102:103], v[98:101], off
	global_load_dwordx4 v[100:103], v[178:179], off offset:512 nt
	global_load_dwordx4 v[198:201], v[178:179], off offset:528 nt
	v_lshl_add_u64 v[98:99], v[184:185], 0, v[148:149]
	v_pk_mul_f32 v[104:105], v[68:69], v[28:29]
	v_pk_mul_f32 v[68:69], v[66:67], v[26:27]
	v_cvt_pk_bf16_f32 v66, v70, v71
	v_cvt_pk_bf16_f32 v67, v72, v73
	s_nop 0
	v_cvt_pk_bf16_f32 v68, v68, v69
	v_cvt_pk_bf16_f32 v69, v104, v105
	v_lshlrev_b64 v[104:105], 1, v[98:99]
	v_lshl_add_u64 v[70:71], s[90:91], 0, v[104:105]
	global_store_dwordx4 v[70:71], v[66:69], off
	v_lshlrev_b32_e32 v72, 16, v68
	v_and_b32_e32 v73, 0xffff0000, v68
	v_lshlrev_b32_e32 v68, 16, v69
	v_and_b32_e32 v69, 0xffff0000, v69
	s_waitcnt vmcnt(1)
	v_pk_add_f32 v[70:71], v[200:201], v[68:69]
	v_lshlrev_b32_e32 v68, 16, v66
	v_and_b32_e32 v69, 0xffff0000, v66
	v_lshlrev_b32_e32 v66, 16, v67
	v_and_b32_e32 v67, 0xffff0000, v67
	v_pk_add_f32 v[98:99], v[102:103], v[66:67]
	v_pk_add_f32 v[100:101], v[100:101], v[68:69]
	v_pk_add_f32 v[72:73], v[198:199], v[72:73]
	v_pk_mul_f32 v[68:69], v[150:151], v[98:99]
	v_pk_mul_f32 v[66:67], v[152:153], v[100:101]
	v_pk_mul_f32 v[102:103], v[154:155], v[70:71]
	v_pk_mul_f32 v[178:179], v[156:157], v[72:73]
	v_cvt_pk_bf16_f32 v66, v66, v67
	v_cvt_pk_bf16_f32 v67, v68, v69
	s_nop 0
	v_cvt_pk_bf16_f32 v68, v178, v179
	v_cvt_pk_bf16_f32 v69, v102, v103
	v_lshl_add_u64 v[102:103], s[96:97], 0, v[104:105]
	global_store_dwordx4 v[102:103], v[66:69], off
	s_nop 1
	v_mul_f32_e32 v66, v101, v101
	v_mul_f32_e32 v67, v99, v99
	v_fmac_f32_e32 v66, v100, v100
	v_fmac_f32_e32 v67, v98, v98
	v_add_f32_e32 v66, v66, v67
	v_mul_f32_e32 v67, v73, v73
	v_mul_f32_e32 v68, v71, v71
	v_fmac_f32_e32 v67, v72, v72
	v_fmac_f32_e32 v68, v70, v70
	v_add_f32_e32 v67, v67, v68
	global_load_dwordx4 v[68:71], v[138:139], off offset:512 nt
	global_load_dwordx4 v[98:101], v[138:139], off offset:528 nt
	v_lshl_add_u64 v[72:73], v[140:141], 0, v[148:149]
	v_lshlrev_b64 v[72:73], 1, v[72:73]
	v_cvt_pk_bf16_f32 v62, v62, v63
	v_cvt_pk_bf16_f32 v63, v64, v65
	v_cvt_pk_bf16_f32 v64, v58, v59
	v_cvt_pk_bf16_f32 v65, v60, v61
	v_lshl_add_u64 v[58:59], s[90:91], 0, v[72:73]
	global_store_dwordx4 v[58:59], v[62:65], off
	v_lshlrev_b32_e32 v60, 16, v64
	v_and_b32_e32 v61, 0xffff0000, v64
	v_lshlrev_b32_e32 v58, 16, v65
	v_and_b32_e32 v59, 0xffff0000, v65
	v_lshlrev_b32_e32 v64, 16, v62
	v_and_b32_e32 v65, 0xffff0000, v62
	v_lshlrev_b32_e32 v62, 16, v63
	v_and_b32_e32 v63, 0xffff0000, v63
	v_lshl_add_u64 v[72:73], s[96:97], 0, v[72:73]
	v_add_f32_e32 v66, v66, v67
	v_add_f32_e32 v66, v211, v66
	s_waitcnt vmcnt(2)
	v_pk_add_f32 v[62:63], v[70:71], v[62:63]
	v_pk_add_f32 v[64:65], v[68:69], v[64:65]
	s_waitcnt vmcnt(1)
	v_pk_add_f32 v[58:59], v[100:101], v[58:59]
	v_pk_add_f32 v[60:61], v[98:99], v[60:61]
	v_pk_mul_f32 v[70:71], v[150:151], v[62:63]
	v_pk_mul_f32 v[68:69], v[152:153], v[64:65]
	v_pk_mul_f32 v[98:99], v[154:155], v[58:59]
	v_pk_mul_f32 v[100:101], v[156:157], v[60:61]
	v_cvt_pk_bf16_f32 v68, v68, v69
	v_cvt_pk_bf16_f32 v69, v70, v71
	s_nop 0
	v_cvt_pk_bf16_f32 v70, v100, v101
	v_cvt_pk_bf16_f32 v71, v98, v99
	global_store_dwordx4 v[72:73], v[68:71], off
	global_load_dwordx4 v[68:71], v[142:143], off offset:512 nt
	s_nop 0
	global_load_dwordx4 v[98:101], v[142:143], off offset:528 nt
	v_lshl_add_u64 v[72:73], v[144:145], 0, v[148:149]
	v_lshlrev_b64 v[72:73], 1, v[72:73]
	v_cvt_pk_bf16_f32 v54, v54, v55
	v_cvt_pk_bf16_f32 v55, v56, v57
	v_cvt_pk_bf16_f32 v56, v50, v51
	v_cvt_pk_bf16_f32 v57, v52, v53
	v_lshl_add_u64 v[50:51], s[90:91], 0, v[72:73]
	global_store_dwordx4 v[50:51], v[54:57], off
	v_lshlrev_b32_e32 v52, 16, v56
	v_and_b32_e32 v53, 0xffff0000, v56
	v_lshlrev_b32_e32 v50, 16, v57
	v_and_b32_e32 v51, 0xffff0000, v57
	v_lshlrev_b32_e32 v56, 16, v54
	v_and_b32_e32 v57, 0xffff0000, v54
	v_lshlrev_b32_e32 v54, 16, v55
	v_and_b32_e32 v55, 0xffff0000, v55
	v_lshl_add_u64 v[72:73], s[96:97], 0, v[72:73]
	s_waitcnt vmcnt(2)
	v_pk_add_f32 v[54:55], v[70:71], v[54:55]
	v_pk_add_f32 v[56:57], v[68:69], v[56:57]
	s_waitcnt vmcnt(1)
	v_pk_add_f32 v[50:51], v[100:101], v[50:51]
	v_pk_add_f32 v[52:53], v[98:99], v[52:53]
	v_pk_mul_f32 v[70:71], v[150:151], v[54:55]
	v_pk_mul_f32 v[68:69], v[152:153], v[56:57]
	v_pk_mul_f32 v[98:99], v[154:155], v[50:51]
	v_pk_mul_f32 v[100:101], v[156:157], v[52:53]
	v_cvt_pk_bf16_f32 v68, v68, v69
	v_cvt_pk_bf16_f32 v69, v70, v71
	s_nop 0
	v_cvt_pk_bf16_f32 v70, v100, v101
	v_cvt_pk_bf16_f32 v71, v98, v99
	global_store_dwordx4 v[72:73], v[68:71], off
	global_load_dwordx4 v[68:71], v[158:159], off offset:512 nt
	s_nop 0
	global_load_dwordx4 v[98:101], v[158:159], off offset:528 nt
	v_lshl_add_u64 v[72:73], v[160:161], 0, v[148:149]
	v_lshlrev_b64 v[72:73], 1, v[72:73]
	v_cvt_pk_bf16_f32 v46, v46, v47
	v_cvt_pk_bf16_f32 v47, v48, v49
	v_cvt_pk_bf16_f32 v48, v42, v43
	v_cvt_pk_bf16_f32 v49, v44, v45
	v_lshl_add_u64 v[42:43], s[90:91], 0, v[72:73]
	global_store_dwordx4 v[42:43], v[46:49], off
	v_lshlrev_b32_e32 v44, 16, v48
	v_and_b32_e32 v45, 0xffff0000, v48
	v_lshlrev_b32_e32 v42, 16, v49
	v_and_b32_e32 v43, 0xffff0000, v49
	v_lshlrev_b32_e32 v48, 16, v46
	v_and_b32_e32 v49, 0xffff0000, v46
	v_lshlrev_b32_e32 v46, 16, v47
	v_and_b32_e32 v47, 0xffff0000, v47
	v_lshl_add_u64 v[72:73], s[96:97], 0, v[72:73]
	s_waitcnt vmcnt(2)
; __device__ __forceinline__ unsigned cvt_pk_bf16(float lo, float hi) { unsigned r; asm volatile("v_cvt_pk_bf16_f32 %0, %1, %2" : "=v"(r) : "v"(lo), "v"(hi)); return r; }
;     __device__ __forceinline__ void operator()(const f32x4 (&acc)[2][2][4][2], const Unit& u, int wr, int wc, int fr, int fq) const {
;     ...
;                 for (int m = 0; m < 4; ++m) { const size_t off = (size_t)(row0 + ai * HALF + m * 16) * 2048 + col0 + bj * HALF;
;                     f32x4 x0 = __builtin_nontemporal_load((const f32x4*)(base + off)), x1 = __builtin_nontemporal_load((const f32x4*)(base + off + 4));
;                     if constexpr (HAS_DIN) { const u32x4 dw = __builtin_nontemporal_load((const u32x4*)(dbuf + off));
;                         x0 += (f32x4){__builtin_bit_cast(float, dw.x << 16), __builtin_bit_cast(float, dw.x & 0xffff0000u), __builtin_bit_cast(float, dw.y << 16), __builtin_bit_cast(float, dw.y & 0xffff0000u)};
;                         x1 += (f32x4){__builtin_bit_cast(float, dw.z << 16), __builtin_bit_cast(float, dw.z & 0xffff0000u), __builtin_bit_cast(float, dw.w << 16), __builtin_bit_cast(float, dw.w & 0xffff0000u)}; }
;                     f32x4 o0, o1;
;                     if constexpr (OUT_DELTA) { const f32x4 d0 = g0 * acc[ai][bj][m][0], d1 = g1 * acc[ai][bj][m][1];
;                         u32x4 w; w.x = cvt_pk_bf16(d0[0], d0[1]); w.y = cvt_pk_bf16(d0[2], d0[3]); w.z = cvt_pk_bf16(d1[0], d1[1]); w.w = cvt_pk_bf16(d1[2], d1[3]);
;                         *(u32x4*)(dbuf + off) = w;
;                         o0 = x0 + (f32x4){__builtin_bit_cast(float, w.x << 16), __builtin_bit_cast(float, w.x & 0xffff0000u), __builtin_bit_cast(float, w.y << 16), __builtin_bit_cast(float, w.y & 0xffff0000u)};
;                         o1 = x1 + (f32x4){__builtin_bit_cast(float, w.z << 16), __builtin_bit_cast(float, w.z & 0xffff0000u), __builtin_bit_cast(float, w.w << 16), __builtin_bit_cast(float, w.w & 0xffff0000u)}; }
;                     else { o0 = x0 + g0 * acc[ai][bj][m][0]; o1 = x1 + g1 * acc[ai][bj][m][1]; *(f32x4*)(out + off) = o0; *(f32x4*)(out + off + 4) = o1; }
;                     if (Hn) { const f32x4 h0 = o0 * G0, h1 = o1 * G1;
;                         u32x4 w; w.x = cvt_pk_bf16(h0[0], h0[1]); w.y = cvt_pk_bf16(h0[2], h0[3]); w.z = cvt_pk_bf16(h1[0], h1[1]); w.w = cvt_pk_bf16(h1[2], h1[3]);
;                         *(u32x4*)(Hn + off) = w;
	v_pk_add_f32 v[46:47], v[70:71], v[46:47]
	v_pk_add_f32 v[48:49], v[68:69], v[48:49]
	s_waitcnt vmcnt(1)
	v_pk_add_f32 v[42:43], v[100:101], v[42:43]
	v_pk_add_f32 v[44:45], v[98:99], v[44:45]
	v_pk_mul_f32 v[70:71], v[150:151], v[46:47]
	v_pk_mul_f32 v[68:69], v[152:153], v[48:49]
	v_pk_mul_f32 v[98:99], v[154:155], v[42:43]
	v_pk_mul_f32 v[100:101], v[156:157], v[44:45]
	v_cvt_pk_bf16_f32 v68, v68, v69
	v_cvt_pk_bf16_f32 v69, v70, v71
	s_nop 0
	v_cvt_pk_bf16_f32 v70, v100, v101
	v_cvt_pk_bf16_f32 v71, v98, v99
	global_store_dwordx4 v[72:73], v[68:71], off
	global_load_dwordx4 v[68:71], v[180:181], off offset:512 nt
	s_nop 0
	global_load_dwordx4 v[98:101], v[180:181], off offset:528 nt
	v_lshl_add_u64 v[72:73], v[182:183], 0, v[148:149]
	v_lshlrev_b64 v[72:73], 1, v[72:73]
	v_cvt_pk_bf16_f32 v38, v38, v39
	v_cvt_pk_bf16_f32 v39, v40, v41
	v_cvt_pk_bf16_f32 v40, v34, v35
	v_cvt_pk_bf16_f32 v41, v36, v37
	v_lshl_add_u64 v[34:35], s[90:91], 0, v[72:73]
	global_store_dwordx4 v[34:35], v[38:41], off
	v_lshlrev_b32_e32 v36, 16, v40
	v_and_b32_e32 v37, 0xffff0000, v40
	v_lshlrev_b32_e32 v34, 16, v41
	v_and_b32_e32 v35, 0xffff0000, v41
	v_lshlrev_b32_e32 v40, 16, v38
	v_and_b32_e32 v41, 0xffff0000, v38
	v_lshlrev_b32_e32 v38, 16, v39
	v_and_b32_e32 v39, 0xffff0000, v39
	v_lshl_add_u64 v[72:73], s[96:97], 0, v[72:73]
	s_waitcnt vmcnt(2)
	v_pk_add_f32 v[38:39], v[70:71], v[38:39]
	v_pk_add_f32 v[40:41], v[68:69], v[40:41]
	s_waitcnt vmcnt(1)
	v_pk_add_f32 v[34:35], v[100:101], v[34:35]
	v_pk_add_f32 v[36:37], v[98:99], v[36:37]
	v_pk_mul_f32 v[70:71], v[150:151], v[38:39]
	v_pk_mul_f32 v[68:69], v[152:153], v[40:41]
	v_pk_mul_f32 v[98:99], v[154:155], v[34:35]
	v_pk_mul_f32 v[100:101], v[156:157], v[36:37]
	v_cvt_pk_bf16_f32 v68, v68, v69
	v_cvt_pk_bf16_f32 v69, v70, v71
	s_nop 0
	v_cvt_pk_bf16_f32 v70, v100, v101
	v_cvt_pk_bf16_f32 v71, v98, v99
	global_store_dwordx4 v[72:73], v[68:71], off
	global_load_dwordx4 v[68:71], v[186:187], off offset:512 nt
	s_nop 0
	global_load_dwordx4 v[98:101], v[186:187], off offset:528 nt
	v_lshl_add_u64 v[72:73], v[188:189], 0, v[148:149]
	v_lshlrev_b64 v[72:73], 1, v[72:73]
	v_cvt_pk_bf16_f32 v22, v22, v23
	v_cvt_pk_bf16_f32 v23, v24, v25
	v_cvt_pk_bf16_f32 v24, v18, v19
	v_cvt_pk_bf16_f32 v25, v20, v21
	v_lshl_add_u64 v[18:19], s[90:91], 0, v[72:73]
	global_store_dwordx4 v[18:19], v[22:25], off
	v_lshlrev_b32_e32 v20, 16, v24
	v_and_b32_e32 v21, 0xffff0000, v24
	v_lshlrev_b32_e32 v18, 16, v25
	v_and_b32_e32 v19, 0xffff0000, v25
	v_lshlrev_b32_e32 v24, 16, v22
	v_and_b32_e32 v25, 0xffff0000, v22
	v_lshlrev_b32_e32 v22, 16, v23
	v_and_b32_e32 v23, 0xffff0000, v23
	v_lshl_add_u64 v[72:73], s[96:97], 0, v[72:73]
	s_waitcnt vmcnt(2)
	v_pk_add_f32 v[22:23], v[70:71], v[22:23]
	v_pk_add_f32 v[24:25], v[68:69], v[24:25]
	s_waitcnt vmcnt(1)
	v_pk_add_f32 v[18:19], v[100:101], v[18:19]
	v_pk_add_f32 v[20:21], v[98:99], v[20:21]
	v_pk_mul_f32 v[70:71], v[150:151], v[22:23]
	v_pk_mul_f32 v[68:69], v[152:153], v[24:25]
	v_pk_mul_f32 v[98:99], v[154:155], v[18:19]
	v_pk_mul_f32 v[100:101], v[156:157], v[20:21]
	v_cvt_pk_bf16_f32 v68, v68, v69
	v_cvt_pk_bf16_f32 v69, v70, v71
	s_nop 0
	v_cvt_pk_bf16_f32 v70, v100, v101
	v_cvt_pk_bf16_f32 v71, v98, v99
	global_store_dwordx4 v[72:73], v[68:71], off
	global_load_dwordx4 v[68:71], v[190:191], off offset:512 nt
	s_nop 0
	global_load_dwordx4 v[98:101], v[190:191], off offset:528 nt
	v_lshl_add_u64 v[72:73], v[192:193], 0, v[148:149]
	v_lshlrev_b64 v[72:73], 1, v[72:73]
	v_cvt_pk_bf16_f32 v14, v14, v15
	v_cvt_pk_bf16_f32 v15, v16, v17
	v_cvt_pk_bf16_f32 v16, v10, v11
	v_cvt_pk_bf16_f32 v17, v12, v13
	v_lshl_add_u64 v[10:11], s[90:91], 0, v[72:73]
	global_store_dwordx4 v[10:11], v[14:17], off
	v_lshlrev_b32_e32 v12, 16, v16
	v_and_b32_e32 v13, 0xffff0000, v16
	v_lshlrev_b32_e32 v10, 16, v17
	v_and_b32_e32 v11, 0xffff0000, v17
	v_lshlrev_b32_e32 v16, 16, v14
	v_and_b32_e32 v17, 0xffff0000, v14
	v_lshlrev_b32_e32 v14, 16, v15
	v_and_b32_e32 v15, 0xffff0000, v15
	v_lshl_add_u64 v[72:73], s[96:97], 0, v[72:73]
	s_waitcnt vmcnt(2)
	v_pk_add_f32 v[14:15], v[70:71], v[14:15]
	v_pk_add_f32 v[16:17], v[68:69], v[16:17]
	s_waitcnt vmcnt(1)
	v_pk_add_f32 v[10:11], v[100:101], v[10:11]
	v_pk_add_f32 v[12:13], v[98:99], v[12:13]
	v_pk_mul_f32 v[70:71], v[150:151], v[14:15]
	v_pk_mul_f32 v[68:69], v[152:153], v[16:17]
	v_pk_mul_f32 v[98:99], v[154:155], v[10:11]
	v_pk_mul_f32 v[100:101], v[156:157], v[12:13]
	v_cvt_pk_bf16_f32 v68, v68, v69
	v_cvt_pk_bf16_f32 v69, v70, v71
	s_nop 0
	v_cvt_pk_bf16_f32 v70, v100, v101
	v_cvt_pk_bf16_f32 v71, v98, v99
	global_store_dwordx4 v[72:73], v[68:71], off
	global_load_dwordx4 v[68:71], v[194:195], off offset:512 nt
	s_nop 0
	global_load_dwordx4 v[98:101], v[194:195], off offset:528 nt
	v_lshl_add_u64 v[72:73], v[196:197], 0, v[148:149]
	v_lshlrev_b64 v[30:31], 1, v[72:73]
	v_cvt_pk_bf16_f32 v6, v6, v7
	v_cvt_pk_bf16_f32 v7, v8, v9
	v_cvt_pk_bf16_f32 v8, v2, v3
	v_cvt_pk_bf16_f32 v9, v4, v5
	v_lshl_add_u64 v[2:3], s[90:91], 0, v[30:31]
	global_store_dwordx4 v[2:3], v[6:9], off
	v_lshlrev_b32_e32 v4, 16, v8
	v_and_b32_e32 v5, 0xffff0000, v8
	v_lshlrev_b32_e32 v2, 16, v9
	v_and_b32_e32 v3, 0xffff0000, v9
	v_lshlrev_b32_e32 v8, 16, v6
	v_and_b32_e32 v9, 0xffff0000, v6
	v_lshlrev_b32_e32 v6, 16, v7
	v_and_b32_e32 v7, 0xffff0000, v7
	v_lshl_add_u64 v[30:31], s[96:97], 0, v[30:31]
	s_waitcnt vmcnt(2)
	v_pk_add_f32 v[8:9], v[68:69], v[8:9]
	v_pk_add_f32 v[6:7], v[70:71], v[6:7]
	v_pk_mul_f32 v[26:27], v[152:153], v[8:9]
	s_waitcnt vmcnt(1)
	v_pk_add_f32 v[2:3], v[100:101], v[2:3]
	v_pk_add_f32 v[4:5], v[98:99], v[4:5]
	v_pk_mul_f32 v[28:29], v[150:151], v[6:7]
	v_cvt_pk_bf16_f32 v26, v26, v27
	v_pk_mul_f32 v[32:33], v[154:155], v[2:3]
	v_cvt_pk_bf16_f32 v27, v28, v29
	v_pk_mul_f32 v[68:69], v[156:157], v[4:5]
	s_nop 0
	v_cvt_pk_bf16_f32 v28, v68, v69
	v_cvt_pk_bf16_f32 v29, v32, v33
	global_store_dwordx4 v[30:31], v[26:29], off
	s_nop 1
	v_and_b32_e32 v27, 64, v218
	v_xor_b32_e32 v26, 16, v218
	v_add_u32_e32 v27, 64, v27
	v_cmp_lt_i32_e32 vcc, v26, v27
	s_nop 1
	v_cndmask_b32_e32 v26, v218, v26, vcc
	v_lshlrev_b32_e32 v28, 2, v26
	v_xor_b32_e32 v26, 32, v218
	v_cmp_lt_i32_e32 vcc, v26, v27
	s_nop 1
	v_cndmask_b32_e32 v26, v218, v26, vcc
	v_lshlrev_b32_e32 v29, 2, v26
	ds_bpermute_b32 v26, v28, v66
	s_waitcnt lgkmcnt(0)
	v_add_f32_e32 v30, v66, v26
	ds_bpermute_b32 v31, v29, v30
	v_lshl_add_u64 v[26:27], v[146:147], 3, s[42:43]
	s_and_saveexec_b64 s[4:5], s[0:1]
	s_mov_b32 s8, 0x2f800000
	s_mov_b32 s9, 0xcf800000
	s_cbranch_execz .LBB0_558
	s_waitcnt lgkmcnt(0)
	v_add_f32_e32 v30, v30, v31
	v_mul_f32_e32 v30, 0x47800000, v30
	v_rndne_f32_e32 v30, v30
	v_mul_f32_e64 v31, |v30|, s8
	v_floor_f32_e32 v31, v31
	v_fma_f32 v32, v31, s9, |v30|
	v_cvt_u32_f32_e32 v32, v32
	v_cvt_u32_f32_e32 v31, v31
	v_ashrrev_i32_e32 v33, 31, v30
	v_xor_b32_e32 v30, v32, v33
	v_xor_b32_e32 v31, v31, v33
	v_sub_co_u32_e32 v30, vcc, v30, v33
	s_nop 1
	v_subb_co_u32_e32 v31, vcc, v31, v33, vcc
	global_atomic_add_x2 v[26:27], v[30:31], off

; #define PG8_STAGE(bufoff, gbase, voff) do { const char* gb_ = (const char*)(gbase); asm volatile("" : "+s"(gb_)); _Pragma("unroll") for (int _i = 0; _i < 2; ++_i) { unsigned vo_ = (voff)[_i]; asm volatile("" : "+v"(vo_));        \
;         __builtin_amdgcn_global_load_lds((const unsigned*)(gb_ + vo_), (PG8_LAS unsigned*)(lds + (bufoff) + ldsw + _i * 8192), 16, 0, 0); } } while (0)
; #define PG8_LDA(dst, b, h) do { _Pragma("unroll") for (int m = 0; m < 4; ++m) _Pragma("unroll") for (int k = 0; k < 2; ++k) dst[m][k] = *(const PG8_LAS bf16x8*)(lds + PG8_SA(b, h) + aoff + m * 2048 + k * 1024); } while (0)
; #define PG8_LDB(dst, b, h) do { _Pragma("unroll") for (int n = 0; n < 2; ++n) _Pragma("unroll") for (int k = 0; k < 2; ++k) dst[n][k] = *(const PG8_LAS bf16x8*)(lds + PG8_SB(b, h) + boff + n * 2048 + k * 1024); } while (0)
; #define PG8_WAIT_V(n) asm volatile("s_waitcnt vmcnt(" #n ")" ::: "memory")
; #define PG8_BAR __builtin_amdgcn_s_barrier()
; template <class Epi, class Sched, bool ALIGN_EPI = false, bool SP2 = false>
; __device__ __forceinline__ void gemm_phase(PG8_LAS unsigned char* lds, const Gemm g, const Sched& S, const Epi& E) {
;     ...
;         const bool has_next = S.next(ui + 1, nxt);
;         const char* nA = has_next ? (const char*)g.A + (size_t)nxt.pm * tstep : cA; const char* nB = has_next ? (const char*)g.Bt + (size_t)nxt.pn * tstep : cB;
;         for (int t = 0; t < nt; t += 2) {
;             const bool last = (t == nt - 2);
;             const char* a1 = cA + (size_t)(t + 1) * kstep;
;             const char* a2 = last ? nA : cA + (size_t)(t + 2) * kstep; const char* b2 = last ? nB : cB + (size_t)(t + 2) * kstep;
;             const char* a3 = a2 + kstep; const char* b3 = b2 + kstep;
;             if (last && has_next) S.a_ready(nxt);
;             if constexpr (SP2) {
;             PG8_LDB(B0, 0, 0); PG8_LDB(B1, 0, 1); PG8_SCHED; PG8_LDA(At, 0, 0); PG8_STAGE(PG8_SA(1, 1), a1 + hstep, voffA);
;             PG8_WAIT_V(8); PG8_WAIT_L(0); PG8_BAR; PG8_MMA(0, 0, At, B0); PG8_MMA(0, 1, At, B1); PG8_BAR; PG8_SCHED;
;     ...
; #pragma unroll
;         for (int a = 0; a < 2; ++a)
; #pragma unroll
;             for (int b = 0; b < 2; ++b)
; #pragma unroll
;                 for (int m = 0; m < 4; ++m)
; #pragma unroll
;                     for (int n = 0; n < 2; ++n) acc[a][b][m][n] = (f32x4){0.f, 0.f, 0.f, 0.f};
;         cur = nxt; cA = nA; cB = nB; ++ui;
.LBB0_633:
	s_ashr_i32 s7, s6, 31
	s_lshl_b64 s[8:9], s[6:7], 20
	s_add_u32 s8, s96, s8
	s_addc_u32 s9, s97, s9
	s_and_b64 s[10:11], s[12:13], exec
	s_cselect_b32 s7, s9, s15
	s_cselect_b32 s49, s8, s14
	s_ashr_i32 s5, s4, 31
	s_lshl_b64 s[10:11], s[4:5], 20
	s_add_u32 s10, s24, s10
	s_addc_u32 s11, s25, s11
	s_and_b64 s[18:19], s[12:13], exec
	s_cselect_b32 s5, s11, s17
	s_cselect_b32 s50, s10, s16
	s_add_u32 s51, s16, 0x100
	v_mov_b32_e32 v2, 0
	s_addc_u32 s52, s17, 0
	s_mov_b32 s53, -2
	v_mov_b32_e32 v3, v2
	v_mov_b32_e32 v4, v2
	v_mov_b32_e32 v5, v2
	v_mov_b32_e32 v6, v2
	v_mov_b32_e32 v7, v2
	v_mov_b32_e32 v8, v2
	v_mov_b32_e32 v9, v2
	v_mov_b32_e32 v18, v2
	v_mov_b32_e32 v19, v2
	v_mov_b32_e32 v20, v2
	v_mov_b32_e32 v21, v2
	v_mov_b32_e32 v22, v2
	v_mov_b32_e32 v23, v2
	v_mov_b32_e32 v24, v2
	v_mov_b32_e32 v25, v2
	v_mov_b32_e32 v34, v2
	v_mov_b32_e32 v35, v2
	v_mov_b32_e32 v36, v2
	v_mov_b32_e32 v37, v2
	v_mov_b32_e32 v38, v2
	v_mov_b32_e32 v39, v2
	v_mov_b32_e32 v40, v2
	v_mov_b32_e32 v41, v2
	v_mov_b32_e32 v50, v2
	v_mov_b32_e32 v51, v2
	v_mov_b32_e32 v52, v2
	v_mov_b32_e32 v53, v2
	v_mov_b32_e32 v54, v2
	v_mov_b32_e32 v55, v2
	v_mov_b32_e32 v56, v2
	v_mov_b32_e32 v57, v2
	v_mov_b32_e32 v10, v2
	v_mov_b32_e32 v11, v2
	v_mov_b32_e32 v12, v2
	v_mov_b32_e32 v13, v2
	v_mov_b32_e32 v14, v2
	v_mov_b32_e32 v15, v2
	v_mov_b32_e32 v16, v2
	v_mov_b32_e32 v17, v2
	v_mov_b32_e32 v26, v2
	v_mov_b32_e32 v27, v2
	v_mov_b32_e32 v28, v2
	v_mov_b32_e32 v29, v2
	v_mov_b32_e32 v30, v2
	v_mov_b32_e32 v31, v2
	v_mov_b32_e32 v32, v2
	v_mov_b32_e32 v33, v2
	v_mov_b32_e32 v42, v2
	v_mov_b32_e32 v43, v2
	v_mov_b32_e32 v44, v2
	v_mov_b32_e32 v45, v2
	v_mov_b32_e32 v46, v2
	v_mov_b32_e32 v47, v2
	v_mov_b32_e32 v48, v2
	v_mov_b32_e32 v49, v2
	v_mov_b32_e32 v58, v2
	v_mov_b32_e32 v59, v2
	v_mov_b32_e32 v60, v2
	v_mov_b32_e32 v61, v2
	v_mov_b32_e32 v62, v2
	v_mov_b32_e32 v63, v2
	v_mov_b32_e32 v64, v2
	v_mov_b32_e32 v65, v2
	v_mov_b32_e32 v66, v2
	v_mov_b32_e32 v67, v2
	v_mov_b32_e32 v68, v2
	v_mov_b32_e32 v69, v2
	v_mov_b32_e32 v70, v2
	v_mov_b32_e32 v71, v2
	v_mov_b32_e32 v72, v2
	v_mov_b32_e32 v73, v2
	v_mov_b32_e32 v98, v2
	v_mov_b32_e32 v99, v2
	v_mov_b32_e32 v100, v2
	v_mov_b32_e32 v101, v2
	v_mov_b32_e32 v102, v2
	v_mov_b32_e32 v103, v2
	v_mov_b32_e32 v104, v2
	v_mov_b32_e32 v105, v2
	v_mov_b32_e32 v114, v2
	v_mov_b32_e32 v115, v2
	v_mov_b32_e32 v116, v2
	v_mov_b32_e32 v117, v2
	v_mov_b32_e32 v118, v2
	v_mov_b32_e32 v119, v2
	v_mov_b32_e32 v120, v2
	v_mov_b32_e32 v121, v2
	v_mov_b32_e32 v130, v2
	v_mov_b32_e32 v131, v2
	v_mov_b32_e32 v132, v2
	v_mov_b32_e32 v133, v2
	v_mov_b32_e32 v134, v2
	v_mov_b32_e32 v135, v2
	v_mov_b32_e32 v136, v2
	v_mov_b32_e32 v137, v2
	v_mov_b32_e32 v74, v2
	v_mov_b32_e32 v75, v2
	v_mov_b32_e32 v76, v2
	v_mov_b32_e32 v77, v2
	v_mov_b32_e32 v78, v2
	v_mov_b32_e32 v79, v2
	v_mov_b32_e32 v80, v2
	v_mov_b32_e32 v81, v2
	v_mov_b32_e32 v106, v2
	v_mov_b32_e32 v107, v2
	v_mov_b32_e32 v108, v2
	v_mov_b32_e32 v109, v2
	v_mov_b32_e32 v110, v2
	v_mov_b32_e32 v111, v2
	v_mov_b32_e32 v112, v2
	v_mov_b32_e32 v113, v2
	v_mov_b32_e32 v122, v2
	v_mov_b32_e32 v123, v2
	v_mov_b32_e32 v124, v2
	v_mov_b32_e32 v125, v2
	v_mov_b32_e32 v126, v2
	v_mov_b32_e32 v127, v2
	v_mov_b32_e32 v128, v2
	v_mov_b32_e32 v129, v2
	v_mov_b32_e32 v138, v2
	v_mov_b32_e32 v139, v2
	v_mov_b32_e32 v140, v2
	v_mov_b32_e32 v141, v2
	v_mov_b32_e32 v142, v2
	v_mov_b32_e32 v143, v2
	v_mov_b32_e32 v144, v2
	v_mov_b32_e32 v145, v2
	v_add_u32_e32 v244, 0x10000, v186
.LBB0_634:
	s_add_u32 s16, s14, 0x100
	s_addc_u32 s17, s15, 0
	s_cmp_eq_u32 s53, 28
	s_cselect_b32 s22, s49, s16
	s_cselect_b32 s23, s7, s17
	s_cselect_b32 s20, s50, s51
	s_cselect_b32 s21, s5, s52
	s_add_u32 s18, s22, 0x80
	s_addc_u32 s19, s23, 0
	s_add_i32 s54, 0, 0x10000
	s_add_i32 s55, 0, 0x14000
	ds_read_b128 v[82:85], v244
	ds_read_b128 v[86:89], v244 offset:1024
	ds_read_b128 v[90:93], v244 offset:2048
	ds_read_b128 v[94:97], v244 offset:3072
	ds_read_b128 v[146:149], v244 offset:16384
	ds_read_b128 v[150:153], v244 offset:17408
	ds_read_b128 v[154:157], v244 offset:18432
	ds_read_b128 v[158:161], v244 offset:19456
	s_add_u32 s14, s14, 0x80080
	s_addc_u32 s15, s15, 0
	ds_read_b128 v[178:181], v188
	ds_read_b128 v[190:193], v188 offset:1024
	ds_read_b128 v[194:197], v188 offset:2048
	ds_read_b128 v[198:201], v188 offset:3072
	ds_read_b128 v[202:205], v188 offset:4096
	ds_read_b128 v[206:209], v188 offset:5120
	ds_read_b128 v[210:213], v188 offset:6144
	ds_read_b128 v[220:223], v188 offset:7168
	s_add_i32 m0, s27, 0xc000
	s_nop 0
	global_load_lds_dwordx4 v1, s[14:15]
	s_add_i32 m0, s27, 0xe000
	s_nop 0
	global_load_lds_dwordx4 v164, s[14:15]
	s_waitcnt vmcnt(8)
	s_waitcnt lgkmcnt(0)
	s_barrier
; #define PG8_STAGE(bufoff, gbase, voff) do { const char* gb_ = (const char*)(gbase); asm volatile("" : "+s"(gb_)); _Pragma("unroll") for (int _i = 0; _i < 2; ++_i) { unsigned vo_ = (voff)[_i]; asm volatile("" : "+v"(vo_));        \
;         __builtin_amdgcn_global_load_lds((const unsigned*)(gb_ + vo_), (PG8_LAS unsigned*)(lds + (bufoff) + ldsw + _i * 8192), 16, 0, 0); } } while (0)
; #define PG8_LDA(dst, b, h) do { _Pragma("unroll") for (int m = 0; m < 4; ++m) _Pragma("unroll") for (int k = 0; k < 2; ++k) dst[m][k] = *(const PG8_LAS bf16x8*)(lds + PG8_SA(b, h) + aoff + m * 2048 + k * 1024); } while (0)
; #define PG8_LDB(dst, b, h) do { _Pragma("unroll") for (int n = 0; n < 2; ++n) _Pragma("unroll") for (int k = 0; k < 2; ++k) dst[n][k] = *(const PG8_LAS bf16x8*)(lds + PG8_SB(b, h) + boff + n * 2048 + k * 1024); } while (0)
; #define PG8_MMA(ai, bj, At, Bt) do { __builtin_amdgcn_s_setprio(1); _Pragma("unroll") for (int m = 0; m < 4; ++m) _Pragma("unroll") for (int n = 0; n < 2; ++n) _Pragma("unroll") for (int k = 0; k < 2; ++k) \
;         acc[ai][bj][m][n] = __builtin_amdgcn_mfma_f32_16x16x32_bf16(Bt[n][k], At[m][k], acc[ai][bj][m][n], 0, 0, 0); __builtin_amdgcn_s_setprio(0); } while (0)
; #define PG8_WAIT_V(n) asm volatile("s_waitcnt vmcnt(" #n ")" ::: "memory")
; #define PG8_WAIT_L(n) asm volatile("s_waitcnt lgkmcnt(" #n ")" ::: "memory")
; #define PG8_BAR __builtin_amdgcn_s_barrier()
; #define PG8_SCHED __builtin_amdgcn_sched_barrier(0)
; template <class Epi, class Sched, bool ALIGN_EPI = false, bool SP2 = false>
; __device__ __forceinline__ void gemm_phase(PG8_LAS unsigned char* lds, const Gemm g, const Sched& S, const Epi& E) {
;     ...
;             PG8_LDB(B0, 0, 0); PG8_LDB(B1, 0, 1); PG8_SCHED; PG8_LDA(At, 0, 0); PG8_STAGE(PG8_SA(1, 1), a1 + hstep, voffA);
;             PG8_WAIT_V(8); PG8_WAIT_L(0); PG8_BAR; PG8_MMA(0, 0, At, B0); PG8_MMA(0, 1, At, B1); PG8_BAR; PG8_SCHED;
;             PG8_LDA(At, 0, 1); PG8_STAGE(PG8_SB(0, 0), b2, voffB); PG8_STAGE(PG8_SB(0, 1), b2 + hstep, voffB); PG8_STAGE(PG8_SA(0, 0), a2, voffA);
;             PG8_WAIT_V(8); PG8_WAIT_L(0); PG8_BAR; PG8_MMA(1, 0, At, B0); PG8_MMA(1, 1, At, B1); PG8_BAR; PG8_SCHED;
	s_setprio 1
	s_waitcnt lgkmcnt(0)
	v_mfma_f32_16x16x32_bf16 v[142:145], v[82:85], v[178:181], v[142:145]
	v_mfma_f32_16x16x32_bf16 v[138:141], v[90:93], v[178:181], v[138:141]
	v_mfma_f32_16x16x32_bf16 v[126:129], v[82:85], v[194:197], v[126:129]
	v_mfma_f32_16x16x32_bf16 v[122:125], v[90:93], v[194:197], v[122:125]
	v_mfma_f32_16x16x32_bf16 v[110:113], v[82:85], v[202:205], v[110:113]
	v_mfma_f32_16x16x32_bf16 v[106:109], v[90:93], v[202:205], v[106:109]
	v_mfma_f32_16x16x32_bf16 v[78:81], v[82:85], v[210:213], v[78:81]
	v_mfma_f32_16x16x32_bf16 v[74:77], v[90:93], v[210:213], v[74:77]
	v_mfma_f32_16x16x32_bf16 v[142:145], v[86:89], v[190:193], v[142:145]
	v_mfma_f32_16x16x32_bf16 v[138:141], v[94:97], v[190:193], v[138:141]
	v_mfma_f32_16x16x32_bf16 v[126:129], v[86:89], v[198:201], v[126:129]
	v_mfma_f32_16x16x32_bf16 v[122:125], v[94:97], v[198:201], v[122:125]
	v_mfma_f32_16x16x32_bf16 v[110:113], v[86:89], v[206:209], v[110:113]
	v_mfma_f32_16x16x32_bf16 v[106:109], v[94:97], v[206:209], v[106:109]
	v_mfma_f32_16x16x32_bf16 v[78:81], v[86:89], v[220:223], v[78:81]
	v_mfma_f32_16x16x32_bf16 v[74:77], v[94:97], v[220:223], v[74:77]
	s_setprio 0
	s_setprio 1
	v_mfma_f32_16x16x32_bf16 v[134:137], v[146:149], v[178:181], v[134:137]
	v_mfma_f32_16x16x32_bf16 v[130:133], v[154:157], v[178:181], v[130:133]
	v_mfma_f32_16x16x32_bf16 v[118:121], v[146:149], v[194:197], v[118:121]
	v_mfma_f32_16x16x32_bf16 v[114:117], v[154:157], v[194:197], v[114:117]
	v_mfma_f32_16x16x32_bf16 v[102:105], v[146:149], v[202:205], v[102:105]
	v_mfma_f32_16x16x32_bf16 v[98:101], v[154:157], v[202:205], v[98:101]
	v_mfma_f32_16x16x32_bf16 v[70:73], v[146:149], v[210:213], v[70:73]
	v_mfma_f32_16x16x32_bf16 v[66:69], v[154:157], v[210:213], v[66:69]
	v_mfma_f32_16x16x32_bf16 v[134:137], v[150:153], v[190:193], v[134:137]
	v_mfma_f32_16x16x32_bf16 v[130:133], v[158:161], v[190:193], v[130:133]
	v_mfma_f32_16x16x32_bf16 v[118:121], v[150:153], v[198:201], v[118:121]
	v_mfma_f32_16x16x32_bf16 v[114:117], v[158:161], v[198:201], v[114:117]
	v_mfma_f32_16x16x32_bf16 v[102:105], v[150:153], v[206:209], v[102:105]
	v_mfma_f32_16x16x32_bf16 v[98:101], v[158:161], v[206:209], v[98:101]
	v_mfma_f32_16x16x32_bf16 v[70:73], v[150:153], v[220:223], v[70:73]
	v_mfma_f32_16x16x32_bf16 v[66:69], v[158:161], v[220:223], v[66:69]
	s_setprio 0
	s_barrier
	s_mov_b64 s[14:15], s[20:21]
	s_add_i32 s54, s54, s26
	ds_read_b128 v[178:181], v188 offset:16384
	ds_read_b128 v[190:193], v188 offset:17408
	ds_read_b128 v[194:197], v188 offset:18432
	ds_read_b128 v[198:201], v188 offset:19456
	ds_read_b128 v[202:205], v188 offset:20480
	ds_read_b128 v[206:209], v188 offset:21504
	ds_read_b128 v[210:213], v188 offset:22528
	ds_read_b128 v[220:223], v188 offset:23552
	s_mov_b32 m0, s54
	s_nop 0
	global_load_lds_dwordx4 v162, s[14:15]
	s_add_i32 m0, s54, 0x2000
	s_nop 0
	global_load_lds_dwordx4 v184, s[14:15]
	s_add_u32 s14, s20, 0x80000
	s_addc_u32 s15, s21, 0
	s_add_i32 s54, s55, s26
	s_mov_b32 m0, s54
	s_nop 0
	global_load_lds_dwordx4 v162, s[14:15]
	s_add_i32 m0, s54, 0x2000
	s_nop 0
	global_load_lds_dwordx4 v184, s[14:15]
	s_mov_b64 s[14:15], s[22:23]
	s_mov_b32 m0, s27
	s_nop 0
	global_load_lds_dwordx4 v1, s[14:15]
	s_mov_b32 m0, s28
	s_nop 0
	global_load_lds_dwordx4 v164, s[14:15]
	s_waitcnt vmcnt(8)
	s_waitcnt lgkmcnt(0)
	s_barrier
	s_setprio 1
	s_waitcnt lgkmcnt(0)
	v_mfma_f32_16x16x32_bf16 v[62:65], v[82:85], v[178:181], v[62:65]
	v_mfma_f32_16x16x32_bf16 v[58:61], v[90:93], v[178:181], v[58:61]
	v_mfma_f32_16x16x32_bf16 v[46:49], v[82:85], v[194:197], v[46:49]
	v_mfma_f32_16x16x32_bf16 v[42:45], v[90:93], v[194:197], v[42:45]
	v_mfma_f32_16x16x32_bf16 v[30:33], v[82:85], v[202:205], v[30:33]
	v_mfma_f32_16x16x32_bf16 v[26:29], v[90:93], v[202:205], v[26:29]
	v_mfma_f32_16x16x32_bf16 v[14:17], v[82:85], v[210:213], v[14:17]
	v_mfma_f32_16x16x32_bf16 v[10:13], v[90:93], v[210:213], v[10:13]
	v_mfma_f32_16x16x32_bf16 v[62:65], v[86:89], v[190:193], v[62:65]
	v_mfma_f32_16x16x32_bf16 v[58:61], v[94:97], v[190:193], v[58:61]
	v_mfma_f32_16x16x32_bf16 v[46:49], v[86:89], v[198:201], v[46:49]
	v_mfma_f32_16x16x32_bf16 v[42:45], v[94:97], v[198:201], v[42:45]
	v_mfma_f32_16x16x32_bf16 v[30:33], v[86:89], v[206:209], v[30:33]
	v_mfma_f32_16x16x32_bf16 v[26:29], v[94:97], v[206:209], v[26:29]
	v_mfma_f32_16x16x32_bf16 v[14:17], v[86:89], v[220:223], v[14:17]
	v_mfma_f32_16x16x32_bf16 v[10:13], v[94:97], v[220:223], v[10:13]
	s_setprio 0
	s_setprio 1
	v_mfma_f32_16x16x32_bf16 v[54:57], v[146:149], v[178:181], v[54:57]
	v_mfma_f32_16x16x32_bf16 v[50:53], v[154:157], v[178:181], v[50:53]
	v_mfma_f32_16x16x32_bf16 v[38:41], v[146:149], v[194:197], v[38:41]
	v_mfma_f32_16x16x32_bf16 v[34:37], v[154:157], v[194:197], v[34:37]
	v_mfma_f32_16x16x32_bf16 v[22:25], v[146:149], v[202:205], v[22:25]
	v_mfma_f32_16x16x32_bf16 v[18:21], v[154:157], v[202:205], v[18:21]
	v_mfma_f32_16x16x32_bf16 v[6:9], v[146:149], v[210:213], v[6:9]
	v_mfma_f32_16x16x32_bf16 v[2:5], v[154:157], v[210:213], v[2:5]
	v_mfma_f32_16x16x32_bf16 v[54:57], v[150:153], v[190:193], v[54:57]
	v_mfma_f32_16x16x32_bf16 v[50:53], v[158:161], v[190:193], v[50:53]
	v_mfma_f32_16x16x32_bf16 v[38:41], v[150:153], v[198:201], v[38:41]
	v_mfma_f32_16x16x32_bf16 v[34:37], v[158:161], v[198:201], v[34:37]
	v_mfma_f32_16x16x32_bf16 v[22:25], v[150:153], v[206:209], v[22:25]
	v_mfma_f32_16x16x32_bf16 v[18:21], v[158:161], v[206:209], v[18:21]
	v_mfma_f32_16x16x32_bf16 v[6:9], v[150:153], v[220:223], v[6:9]
	v_mfma_f32_16x16x32_bf16 v[2:5], v[158:161], v[220:223], v[2:5]
	s_setprio 0
	s_barrier
; #define PG8_STAGE(bufoff, gbase, voff) do { const char* gb_ = (const char*)(gbase); asm volatile("" : "+s"(gb_)); _Pragma("unroll") for (int _i = 0; _i < 2; ++_i) { unsigned vo_ = (voff)[_i]; asm volatile("" : "+v"(vo_));        \
;         __builtin_amdgcn_global_load_lds((const unsigned*)(gb_ + vo_), (PG8_LAS unsigned*)(lds + (bufoff) + ldsw + _i * 8192), 16, 0, 0); } } while (0)
; #define PG8_LDA(dst, b, h) do { _Pragma("unroll") for (int m = 0; m < 4; ++m) _Pragma("unroll") for (int k = 0; k < 2; ++k) dst[m][k] = *(const PG8_LAS bf16x8*)(lds + PG8_SA(b, h) + aoff + m * 2048 + k * 1024); } while (0)
; #define PG8_LDB(dst, b, h) do { _Pragma("unroll") for (int n = 0; n < 2; ++n) _Pragma("unroll") for (int k = 0; k < 2; ++k) dst[n][k] = *(const PG8_LAS bf16x8*)(lds + PG8_SB(b, h) + boff + n * 2048 + k * 1024); } while (0)
; #define PG8_MMA(ai, bj, At, Bt) do { __builtin_amdgcn_s_setprio(1); _Pragma("unroll") for (int m = 0; m < 4; ++m) _Pragma("unroll") for (int n = 0; n < 2; ++n) _Pragma("unroll") for (int k = 0; k < 2; ++k) \
;         acc[ai][bj][m][n] = __builtin_amdgcn_mfma_f32_16x16x32_bf16(Bt[n][k], At[m][k], acc[ai][bj][m][n], 0, 0, 0); __builtin_amdgcn_s_setprio(0); } while (0)
; #define PG8_WAIT_V(n) asm volatile("s_waitcnt vmcnt(" #n ")" ::: "memory")
; #define PG8_WAIT_L(n) asm volatile("s_waitcnt lgkmcnt(" #n ")" ::: "memory")
; #define PG8_BAR __builtin_amdgcn_s_barrier()
; #define PG8_SCHED __builtin_amdgcn_sched_barrier(0)
; template <class Epi, class Sched, bool ALIGN_EPI = false, bool SP2 = false>
; __device__ __forceinline__ void gemm_phase(PG8_LAS unsigned char* lds, const Gemm g, const Sched& S, const Epi& E) {
;     ...
;             PG8_LDB(B0, 1, 0); PG8_LDB(B1, 1, 1); PG8_SCHED; PG8_LDA(At, 1, 0); PG8_STAGE(PG8_SA(0, 1), a2 + hstep, voffA);
;             PG8_WAIT_V(8); PG8_WAIT_L(0); PG8_BAR; PG8_MMA(0, 0, At, B0); PG8_MMA(0, 1, At, B1); PG8_BAR; PG8_SCHED;
;             PG8_LDA(At, 1, 1); PG8_STAGE(PG8_SB(1, 0), b3, voffB); PG8_STAGE(PG8_SB(1, 1), b3 + hstep, voffB); PG8_STAGE(PG8_SA(1, 0), a3, voffA);
;             PG8_WAIT_V(8); PG8_WAIT_L(0); PG8_BAR; PG8_MMA(1, 0, At, B0); PG8_MMA(1, 1, At, B1); PG8_BAR; PG8_SCHED;
	s_add_i32 s54, 0, 0x18000
	s_add_i32 s55, 0, 0x1c000
	ds_read_b128 v[82:85], v244 offset:32768
	ds_read_b128 v[86:89], v244 offset:33792
	ds_read_b128 v[90:93], v244 offset:34816
	ds_read_b128 v[94:97], v244 offset:35840
	ds_read_b128 v[146:149], v244 offset:49152
	ds_read_b128 v[150:153], v244 offset:50176
	ds_read_b128 v[154:157], v244 offset:51200
	ds_read_b128 v[158:161], v244 offset:52224
	s_add_u32 s14, s22, 0x80000
	s_addc_u32 s15, s23, 0
	s_mov_b32 m0, s29
	ds_read_b128 v[178:181], v188 offset:32768
	ds_read_b128 v[190:193], v188 offset:33792
	ds_read_b128 v[194:197], v188 offset:34816
	ds_read_b128 v[198:201], v188 offset:35840
	ds_read_b128 v[202:205], v188 offset:36864
	ds_read_b128 v[206:209], v188 offset:37888
	ds_read_b128 v[210:213], v188 offset:38912
	ds_read_b128 v[220:223], v188 offset:39936
	s_nop 0
	global_load_lds_dwordx4 v1, s[14:15]
	s_mov_b32 m0, s33
	s_nop 0
	global_load_lds_dwordx4 v164, s[14:15]
	s_waitcnt vmcnt(8)
	s_waitcnt lgkmcnt(0)
	s_barrier
	s_setprio 1
	s_waitcnt lgkmcnt(0)
	v_mfma_f32_16x16x32_bf16 v[142:145], v[82:85], v[178:181], v[142:145]
	v_mfma_f32_16x16x32_bf16 v[138:141], v[90:93], v[178:181], v[138:141]
	v_mfma_f32_16x16x32_bf16 v[126:129], v[82:85], v[194:197], v[126:129]
	v_mfma_f32_16x16x32_bf16 v[122:125], v[90:93], v[194:197], v[122:125]
	v_mfma_f32_16x16x32_bf16 v[110:113], v[82:85], v[202:205], v[110:113]
	v_mfma_f32_16x16x32_bf16 v[106:109], v[90:93], v[202:205], v[106:109]
	v_mfma_f32_16x16x32_bf16 v[78:81], v[82:85], v[210:213], v[78:81]
	v_mfma_f32_16x16x32_bf16 v[74:77], v[90:93], v[210:213], v[74:77]
	v_mfma_f32_16x16x32_bf16 v[142:145], v[86:89], v[190:193], v[142:145]
	v_mfma_f32_16x16x32_bf16 v[138:141], v[94:97], v[190:193], v[138:141]
	v_mfma_f32_16x16x32_bf16 v[126:129], v[86:89], v[198:201], v[126:129]
	v_mfma_f32_16x16x32_bf16 v[122:125], v[94:97], v[198:201], v[122:125]
	v_mfma_f32_16x16x32_bf16 v[110:113], v[86:89], v[206:209], v[110:113]
	v_mfma_f32_16x16x32_bf16 v[106:109], v[94:97], v[206:209], v[106:109]
	v_mfma_f32_16x16x32_bf16 v[78:81], v[86:89], v[220:223], v[78:81]
	v_mfma_f32_16x16x32_bf16 v[74:77], v[94:97], v[220:223], v[74:77]
	s_setprio 0
	s_setprio 1
	v_mfma_f32_16x16x32_bf16 v[134:137], v[146:149], v[178:181], v[134:137]
	v_mfma_f32_16x16x32_bf16 v[130:133], v[154:157], v[178:181], v[130:133]
	v_mfma_f32_16x16x32_bf16 v[118:121], v[146:149], v[194:197], v[118:121]
	v_mfma_f32_16x16x32_bf16 v[114:117], v[154:157], v[194:197], v[114:117]
	v_mfma_f32_16x16x32_bf16 v[102:105], v[146:149], v[202:205], v[102:105]
	v_mfma_f32_16x16x32_bf16 v[98:101], v[154:157], v[202:205], v[98:101]
	v_mfma_f32_16x16x32_bf16 v[70:73], v[146:149], v[210:213], v[70:73]
	v_mfma_f32_16x16x32_bf16 v[66:69], v[154:157], v[210:213], v[66:69]
	v_mfma_f32_16x16x32_bf16 v[134:137], v[150:153], v[190:193], v[134:137]
	v_mfma_f32_16x16x32_bf16 v[130:133], v[158:161], v[190:193], v[130:133]
	v_mfma_f32_16x16x32_bf16 v[118:121], v[150:153], v[198:201], v[118:121]
	v_mfma_f32_16x16x32_bf16 v[114:117], v[158:161], v[198:201], v[114:117]
	v_mfma_f32_16x16x32_bf16 v[102:105], v[150:153], v[206:209], v[102:105]
	v_mfma_f32_16x16x32_bf16 v[98:101], v[158:161], v[206:209], v[98:101]
	v_mfma_f32_16x16x32_bf16 v[70:73], v[150:153], v[220:223], v[70:73]
	v_mfma_f32_16x16x32_bf16 v[66:69], v[158:161], v[220:223], v[66:69]
	s_setprio 0
	s_barrier
	s_add_u32 s14, s20, 0x80
	s_addc_u32 s15, s21, 0
	s_add_i32 s22, s54, s26
	ds_read_b128 v[178:181], v188 offset:49152
	ds_read_b128 v[190:193], v188 offset:50176
	ds_read_b128 v[194:197], v188 offset:51200
	ds_read_b128 v[198:201], v188 offset:52224
	ds_read_b128 v[202:205], v188 offset:53248
	ds_read_b128 v[206:209], v188 offset:54272
	ds_read_b128 v[210:213], v188 offset:55296
	ds_read_b128 v[220:223], v188 offset:56320
	s_mov_b32 m0, s22
	s_nop 0
	global_load_lds_dwordx4 v162, s[14:15]
	s_add_i32 m0, s22, 0x2000
	s_nop 0
	global_load_lds_dwordx4 v184, s[14:15]
	s_add_u32 s14, s20, 0x80080
	s_addc_u32 s15, s21, 0
	s_add_i32 s20, s55, s26
	s_mov_b32 m0, s20
	s_nop 0
	global_load_lds_dwordx4 v162, s[14:15]
	s_add_i32 m0, s20, 0x2000
	s_nop 0
	global_load_lds_dwordx4 v184, s[14:15]
	s_mov_b32 m0, s38
	s_nop 0
	global_load_lds_dwordx4 v1, s[18:19]
	s_mov_b32 m0, s39
	s_nop 0
	global_load_lds_dwordx4 v164, s[18:19]
	s_waitcnt vmcnt(8)
	s_waitcnt lgkmcnt(0)
	s_barrier
	s_setprio 1
	s_waitcnt lgkmcnt(0)
	v_mfma_f32_16x16x32_bf16 v[62:65], v[82:85], v[178:181], v[62:65]
	v_mfma_f32_16x16x32_bf16 v[58:61], v[90:93], v[178:181], v[58:61]
	v_mfma_f32_16x16x32_bf16 v[46:49], v[82:85], v[194:197], v[46:49]
	v_mfma_f32_16x16x32_bf16 v[42:45], v[90:93], v[194:197], v[42:45]
	v_mfma_f32_16x16x32_bf16 v[30:33], v[82:85], v[202:205], v[30:33]
	v_mfma_f32_16x16x32_bf16 v[26:29], v[90:93], v[202:205], v[26:29]
	v_mfma_f32_16x16x32_bf16 v[14:17], v[82:85], v[210:213], v[14:17]
	v_mfma_f32_16x16x32_bf16 v[10:13], v[90:93], v[210:213], v[10:13]
	v_mfma_f32_16x16x32_bf16 v[62:65], v[86:89], v[190:193], v[62:65]
	v_mfma_f32_16x16x32_bf16 v[58:61], v[94:97], v[190:193], v[58:61]
	v_mfma_f32_16x16x32_bf16 v[46:49], v[86:89], v[198:201], v[46:49]
	v_mfma_f32_16x16x32_bf16 v[42:45], v[94:97], v[198:201], v[42:45]
	v_mfma_f32_16x16x32_bf16 v[30:33], v[86:89], v[206:209], v[30:33]
	v_mfma_f32_16x16x32_bf16 v[26:29], v[94:97], v[206:209], v[26:29]
	v_mfma_f32_16x16x32_bf16 v[14:17], v[86:89], v[220:223], v[14:17]
	v_mfma_f32_16x16x32_bf16 v[10:13], v[94:97], v[220:223], v[10:13]
	s_setprio 0
	s_setprio 1
	v_mfma_f32_16x16x32_bf16 v[54:57], v[146:149], v[178:181], v[54:57]
	v_mfma_f32_16x16x32_bf16 v[50:53], v[154:157], v[178:181], v[50:53]
	v_mfma_f32_16x16x32_bf16 v[38:41], v[146:149], v[194:197], v[38:41]
	v_mfma_f32_16x16x32_bf16 v[34:37], v[154:157], v[194:197], v[34:37]
	v_mfma_f32_16x16x32_bf16 v[22:25], v[146:149], v[202:205], v[22:25]
	v_mfma_f32_16x16x32_bf16 v[18:21], v[154:157], v[202:205], v[18:21]
	v_mfma_f32_16x16x32_bf16 v[6:9], v[146:149], v[210:213], v[6:9]
	v_mfma_f32_16x16x32_bf16 v[2:5], v[154:157], v[210:213], v[2:5]
	v_mfma_f32_16x16x32_bf16 v[54:57], v[150:153], v[190:193], v[54:57]
	v_mfma_f32_16x16x32_bf16 v[50:53], v[158:161], v[190:193], v[50:53]
	v_mfma_f32_16x16x32_bf16 v[38:41], v[150:153], v[198:201], v[38:41]
	v_mfma_f32_16x16x32_bf16 v[34:37], v[158:161], v[198:201], v[34:37]
	v_mfma_f32_16x16x32_bf16 v[22:25], v[150:153], v[206:209], v[22:25]
	v_mfma_f32_16x16x32_bf16 v[18:21], v[158:161], v[206:209], v[18:21]
	v_mfma_f32_16x16x32_bf16 v[6:9], v[150:153], v[220:223], v[6:9]
	v_mfma_f32_16x16x32_bf16 v[2:5], v[158:161], v[220:223], v[2:5]
	s_setprio 0
	s_barrier
	s_add_i32 s53, s53, 2
	s_add_u32 s51, s51, 0x100
	s_addc_u32 s52, s52, 0
	s_cmp_gt_u32 s53, 29
	s_mov_b64 s[14:15], s[16:17]
	s_cbranch_scc0 .LBB0_634
	s_and_b64 vcc, exec, s[2:3]
	s_cbranch_vccz .LBB0_637
	s_barrier

; #define PG8_STAGE(bufoff, gbase, voff) do { const char* gb_ = (const char*)(gbase); asm volatile("" : "+s"(gb_)); _Pragma("unroll") for (int _i = 0; _i < 2; ++_i) { unsigned vo_ = (voff)[_i]; asm volatile("" : "+v"(vo_));        \
;         __builtin_amdgcn_global_load_lds((const unsigned*)(gb_ + vo_), (PG8_LAS unsigned*)(lds + (bufoff) + ldsw + _i * 8192), 16, 0, 0); } } while (0)
; #define PG8_LDA(dst, b, h) do { _Pragma("unroll") for (int m = 0; m < 4; ++m) _Pragma("unroll") for (int k = 0; k < 2; ++k) dst[m][k] = *(const PG8_LAS bf16x8*)(lds + PG8_SA(b, h) + aoff + m * 2048 + k * 1024); } while (0)
; #define PG8_LDB(dst, b, h) do { _Pragma("unroll") for (int n = 0; n < 2; ++n) _Pragma("unroll") for (int k = 0; k < 2; ++k) dst[n][k] = *(const PG8_LAS bf16x8*)(lds + PG8_SB(b, h) + boff + n * 2048 + k * 1024); } while (0)
; #define PG8_WAIT_V(n) asm volatile("s_waitcnt vmcnt(" #n ")" ::: "memory")
; #define PG8_WAIT_L(n) asm volatile("s_waitcnt lgkmcnt(" #n ")" ::: "memory")
; #define PG8_BAR __builtin_amdgcn_s_barrier()
; #define PG8_SCHED __builtin_amdgcn_sched_barrier(0)
; template <class Epi, class Sched, bool ALIGN_EPI = false, bool SP2 = false>
; __device__ __forceinline__ void gemm_phase(PG8_LAS unsigned char* lds, const Gemm g, const Sched& S, const Epi& E) {
;     ...
;         for (int t = 0; t < nt; t += 2) {
;             const bool last = (t == nt - 2);
;             const char* a1 = cA + (size_t)(t + 1) * kstep;
;             const char* a2 = last ? nA : cA + (size_t)(t + 2) * kstep; const char* b2 = last ? nB : cB + (size_t)(t + 2) * kstep;
;             const char* a3 = a2 + kstep; const char* b3 = b2 + kstep;
;             if (last && has_next) S.a_ready(nxt);
;             if constexpr (SP2) {
;             PG8_LDB(B0, 0, 0); PG8_LDB(B1, 0, 1); PG8_SCHED; PG8_LDA(At, 0, 0); PG8_STAGE(PG8_SA(1, 1), a1 + hstep, voffA);
;             PG8_WAIT_V(8); PG8_WAIT_L(0); PG8_BAR; PG8_MMA(0, 0, At, B0); PG8_MMA(0, 1, At, B1); PG8_BAR; PG8_SCHED;
;     ...
; #pragma unroll
;         for (int a = 0; a < 2; ++a)
; #pragma unroll
;             for (int b = 0; b < 2; ++b)
; #pragma unroll
;                 for (int m = 0; m < 4; ++m)
; #pragma unroll
;                     for (int n = 0; n < 2; ++n) acc[a][b][m][n] = (f32x4){0.f, 0.f, 0.f, 0.f};
;         cur = nxt; cA = nA; cB = nB; ++ui;
.LBB0_706:
	s_add_u32 s31, s6, 0x100
	v_mov_b32_e32 v2, 0
	s_addc_u32 s34, s7, 0
	s_mov_b32 s35, -2
	s_waitcnt lgkmcnt(0)
	v_mov_b32_e32 v3, v2
	v_mov_b32_e32 v4, v2
	v_mov_b32_e32 v5, v2
	v_mov_b32_e32 v6, v2
	v_mov_b32_e32 v7, v2
	v_mov_b32_e32 v8, v2
	v_mov_b32_e32 v9, v2
	v_mov_b32_e32 v10, v2
	v_mov_b32_e32 v11, v2
	v_mov_b32_e32 v12, v2
	v_mov_b32_e32 v13, v2
	v_mov_b32_e32 v14, v2
	v_mov_b32_e32 v15, v2
	v_mov_b32_e32 v16, v2
	v_mov_b32_e32 v17, v2
	v_mov_b32_e32 v18, v2
	v_mov_b32_e32 v19, v2
	v_mov_b32_e32 v20, v2
	v_mov_b32_e32 v21, v2
	v_mov_b32_e32 v22, v2
	v_mov_b32_e32 v23, v2
	v_mov_b32_e32 v24, v2
	v_mov_b32_e32 v25, v2
	v_mov_b32_e32 v26, v2
	v_mov_b32_e32 v27, v2
	v_mov_b32_e32 v28, v2
	v_mov_b32_e32 v29, v2
	v_mov_b32_e32 v30, v2
	v_mov_b32_e32 v31, v2
	v_mov_b32_e32 v32, v2
	v_mov_b32_e32 v33, v2
	v_mov_b32_e32 v74, v2
	v_mov_b32_e32 v75, v2
	v_mov_b32_e32 v76, v2
	v_mov_b32_e32 v77, v2
	v_mov_b32_e32 v78, v2
	v_mov_b32_e32 v79, v2
	v_mov_b32_e32 v80, v2
	v_mov_b32_e32 v81, v2
	v_mov_b32_e32 v82, v2
	v_mov_b32_e32 v83, v2
	v_mov_b32_e32 v84, v2
	v_mov_b32_e32 v85, v2
	v_mov_b32_e32 v86, v2
	v_mov_b32_e32 v87, v2
	v_mov_b32_e32 v88, v2
	v_mov_b32_e32 v89, v2
	v_mov_b32_e32 v90, v2
	v_mov_b32_e32 v91, v2
	v_mov_b32_e32 v92, v2
	v_mov_b32_e32 v93, v2
	v_mov_b32_e32 v94, v2
	v_mov_b32_e32 v95, v2
	v_mov_b32_e32 v96, v2
	v_mov_b32_e32 v97, v2
	v_mov_b32_e32 v106, v2
	v_mov_b32_e32 v107, v2
	v_mov_b32_e32 v108, v2
	v_mov_b32_e32 v109, v2
	v_mov_b32_e32 v110, v2
	v_mov_b32_e32 v111, v2
	v_mov_b32_e32 v112, v2
	v_mov_b32_e32 v113, v2
	v_mov_b32_e32 v42, v2
	v_mov_b32_e32 v43, v2
	v_mov_b32_e32 v44, v2
	v_mov_b32_e32 v45, v2
	v_mov_b32_e32 v46, v2
	v_mov_b32_e32 v47, v2
	v_mov_b32_e32 v48, v2
	v_mov_b32_e32 v49, v2
	v_mov_b32_e32 v50, v2
	v_mov_b32_e32 v51, v2
	v_mov_b32_e32 v52, v2
	v_mov_b32_e32 v53, v2
	v_mov_b32_e32 v54, v2
	v_mov_b32_e32 v55, v2
	v_mov_b32_e32 v56, v2
	v_mov_b32_e32 v57, v2
	v_mov_b32_e32 v58, v2
	v_mov_b32_e32 v59, v2
	v_mov_b32_e32 v60, v2
	v_mov_b32_e32 v61, v2
	v_mov_b32_e32 v62, v2
	v_mov_b32_e32 v63, v2
	v_mov_b32_e32 v64, v2
	v_mov_b32_e32 v65, v2
	v_mov_b32_e32 v66, v2
	v_mov_b32_e32 v67, v2
	v_mov_b32_e32 v68, v2
	v_mov_b32_e32 v69, v2
	v_mov_b32_e32 v70, v2
	v_mov_b32_e32 v71, v2
	v_mov_b32_e32 v72, v2
	v_mov_b32_e32 v73, v2
	v_mov_b32_e32 v114, v2
	v_mov_b32_e32 v115, v2
	v_mov_b32_e32 v116, v2
	v_mov_b32_e32 v117, v2
	v_mov_b32_e32 v118, v2
	v_mov_b32_e32 v119, v2
	v_mov_b32_e32 v120, v2
	v_mov_b32_e32 v121, v2
	v_mov_b32_e32 v122, v2
	v_mov_b32_e32 v123, v2
	v_mov_b32_e32 v124, v2
	v_mov_b32_e32 v125, v2
	v_mov_b32_e32 v126, v2
	v_mov_b32_e32 v127, v2
	v_mov_b32_e32 v128, v2
	v_mov_b32_e32 v129, v2
	v_mov_b32_e32 v130, v2
	v_mov_b32_e32 v131, v2
	v_mov_b32_e32 v132, v2
	v_mov_b32_e32 v133, v2
	v_mov_b32_e32 v134, v2
	v_mov_b32_e32 v135, v2
	v_mov_b32_e32 v136, v2
	v_mov_b32_e32 v137, v2
	v_mov_b32_e32 v138, v2
	v_mov_b32_e32 v139, v2
	v_mov_b32_e32 v140, v2
	v_mov_b32_e32 v141, v2
	v_mov_b32_e32 v142, v2
	v_mov_b32_e32 v143, v2
	v_mov_b32_e32 v144, v2
	v_mov_b32_e32 v145, v2
	v_add_u32_e32 v244, 0x10000, v192
.LBB0_707:
	s_add_u32 s2, s4, 0x100
	s_addc_u32 s3, s5, 0
	s_cmpk_eq_i32 s35, 0x54
	s_cselect_b32 s10, s52, s2
	s_cselect_b32 s11, s53, s3
	s_cselect_b32 s8, s42, s31
	s_cselect_b32 s9, s43, s34
	s_add_u32 s6, s10, 0x80
	s_addc_u32 s7, s11, 0
	s_add_i32 s38, 0, 0x10000
	s_add_i32 s39, 0, 0x14000
	ds_read_b128 v[34:37], v244
	ds_read_b128 v[38:41], v244 offset:1024
	ds_read_b128 v[98:101], v244 offset:2048
	ds_read_b128 v[102:105], v244 offset:3072
	ds_read_b128 v[146:149], v244 offset:16384
	ds_read_b128 v[150:153], v244 offset:17408
	ds_read_b128 v[154:157], v244 offset:18432
	ds_read_b128 v[158:161], v244 offset:19456
	s_add_u32 s4, s4, 0x160080
	s_addc_u32 s5, s5, 0
	ds_read_b128 v[178:181], v194
	ds_read_b128 v[182:185], v194 offset:1024
	ds_read_b128 v[186:189], v194 offset:2048
	ds_read_b128 v[196:199], v194 offset:3072
	ds_read_b128 v[200:203], v194 offset:4096
	ds_read_b128 v[204:207], v194 offset:5120
	ds_read_b128 v[208:211], v194 offset:6144
	ds_read_b128 v[212:215], v194 offset:7168
	s_add_i32 m0, s16, 0xc000
	s_nop 0
	global_load_lds_dwordx4 v1, s[4:5]
	s_add_i32 m0, s16, 0xe000
	s_nop 0
	global_load_lds_dwordx4 v164, s[4:5]
	s_waitcnt vmcnt(8)
	s_waitcnt lgkmcnt(0)
	s_barrier
	s_setprio 1
	s_waitcnt lgkmcnt(0)
	v_mfma_f32_16x16x32_bf16 v[142:145], v[34:37], v[178:181], v[142:145]
	v_mfma_f32_16x16x32_bf16 v[138:141], v[98:101], v[178:181], v[138:141]
	v_mfma_f32_16x16x32_bf16 v[134:137], v[34:37], v[186:189], v[134:137]
	v_mfma_f32_16x16x32_bf16 v[130:133], v[98:101], v[186:189], v[130:133]
	v_mfma_f32_16x16x32_bf16 v[126:129], v[34:37], v[200:203], v[126:129]
	v_mfma_f32_16x16x32_bf16 v[122:125], v[98:101], v[200:203], v[122:125]
	v_mfma_f32_16x16x32_bf16 v[118:121], v[34:37], v[208:211], v[118:121]
	v_mfma_f32_16x16x32_bf16 v[114:117], v[98:101], v[208:211], v[114:117]
	v_mfma_f32_16x16x32_bf16 v[142:145], v[38:41], v[182:185], v[142:145]
	v_mfma_f32_16x16x32_bf16 v[138:141], v[102:105], v[182:185], v[138:141]
	v_mfma_f32_16x16x32_bf16 v[134:137], v[38:41], v[196:199], v[134:137]
	v_mfma_f32_16x16x32_bf16 v[130:133], v[102:105], v[196:199], v[130:133]
	v_mfma_f32_16x16x32_bf16 v[126:129], v[38:41], v[204:207], v[126:129]
	v_mfma_f32_16x16x32_bf16 v[122:125], v[102:105], v[204:207], v[122:125]
	v_mfma_f32_16x16x32_bf16 v[118:121], v[38:41], v[212:215], v[118:121]
	v_mfma_f32_16x16x32_bf16 v[114:117], v[102:105], v[212:215], v[114:117]
	s_setprio 0
	s_setprio 1
	v_mfma_f32_16x16x32_bf16 v[70:73], v[146:149], v[178:181], v[70:73]
	v_mfma_f32_16x16x32_bf16 v[66:69], v[154:157], v[178:181], v[66:69]
	v_mfma_f32_16x16x32_bf16 v[62:65], v[146:149], v[186:189], v[62:65]
	v_mfma_f32_16x16x32_bf16 v[58:61], v[154:157], v[186:189], v[58:61]
	v_mfma_f32_16x16x32_bf16 v[54:57], v[146:149], v[200:203], v[54:57]
	v_mfma_f32_16x16x32_bf16 v[50:53], v[154:157], v[200:203], v[50:53]
	v_mfma_f32_16x16x32_bf16 v[46:49], v[146:149], v[208:211], v[46:49]
	v_mfma_f32_16x16x32_bf16 v[42:45], v[154:157], v[208:211], v[42:45]
	v_mfma_f32_16x16x32_bf16 v[70:73], v[150:153], v[182:185], v[70:73]
	v_mfma_f32_16x16x32_bf16 v[66:69], v[158:161], v[182:185], v[66:69]
	v_mfma_f32_16x16x32_bf16 v[62:65], v[150:153], v[196:199], v[62:65]
	v_mfma_f32_16x16x32_bf16 v[58:61], v[158:161], v[196:199], v[58:61]
	v_mfma_f32_16x16x32_bf16 v[54:57], v[150:153], v[204:207], v[54:57]
	v_mfma_f32_16x16x32_bf16 v[50:53], v[158:161], v[204:207], v[50:53]
	v_mfma_f32_16x16x32_bf16 v[46:49], v[150:153], v[212:215], v[46:49]
	v_mfma_f32_16x16x32_bf16 v[42:45], v[158:161], v[212:215], v[42:45]
	s_setprio 0
	s_barrier
; #define PG8_STAGE(bufoff, gbase, voff) do { const char* gb_ = (const char*)(gbase); asm volatile("" : "+s"(gb_)); _Pragma("unroll") for (int _i = 0; _i < 2; ++_i) { unsigned vo_ = (voff)[_i]; asm volatile("" : "+v"(vo_));        \
;         __builtin_amdgcn_global_load_lds((const unsigned*)(gb_ + vo_), (PG8_LAS unsigned*)(lds + (bufoff) + ldsw + _i * 8192), 16, 0, 0); } } while (0)
; #define PG8_LDA(dst, b, h) do { _Pragma("unroll") for (int m = 0; m < 4; ++m) _Pragma("unroll") for (int k = 0; k < 2; ++k) dst[m][k] = *(const PG8_LAS bf16x8*)(lds + PG8_SA(b, h) + aoff + m * 2048 + k * 1024); } while (0)
; #define PG8_LDB(dst, b, h) do { _Pragma("unroll") for (int n = 0; n < 2; ++n) _Pragma("unroll") for (int k = 0; k < 2; ++k) dst[n][k] = *(const PG8_LAS bf16x8*)(lds + PG8_SB(b, h) + boff + n * 2048 + k * 1024); } while (0)
; #define PG8_MMA(ai, bj, At, Bt) do { __builtin_amdgcn_s_setprio(1); _Pragma("unroll") for (int m = 0; m < 4; ++m) _Pragma("unroll") for (int n = 0; n < 2; ++n) _Pragma("unroll") for (int k = 0; k < 2; ++k) \
;         acc[ai][bj][m][n] = __builtin_amdgcn_mfma_f32_16x16x32_bf16(Bt[n][k], At[m][k], acc[ai][bj][m][n], 0, 0, 0); __builtin_amdgcn_s_setprio(0); } while (0)
; #define PG8_WAIT_V(n) asm volatile("s_waitcnt vmcnt(" #n ")" ::: "memory")
; #define PG8_WAIT_L(n) asm volatile("s_waitcnt lgkmcnt(" #n ")" ::: "memory")
; #define PG8_BAR __builtin_amdgcn_s_barrier()
; #define PG8_SCHED __builtin_amdgcn_sched_barrier(0)
; template <class Epi, class Sched, bool ALIGN_EPI = false, bool SP2 = false>
; __device__ __forceinline__ void gemm_phase(PG8_LAS unsigned char* lds, const Gemm g, const Sched& S, const Epi& E) {
;     ...
;             PG8_LDA(At, 0, 1); PG8_STAGE(PG8_SB(0, 0), b2, voffB); PG8_STAGE(PG8_SB(0, 1), b2 + hstep, voffB); PG8_STAGE(PG8_SA(0, 0), a2, voffA);
;             PG8_WAIT_V(8); PG8_WAIT_L(0); PG8_BAR; PG8_MMA(1, 0, At, B0); PG8_MMA(1, 1, At, B1); PG8_BAR; PG8_SCHED;
;             PG8_LDB(B0, 1, 0); PG8_LDB(B1, 1, 1); PG8_SCHED; PG8_LDA(At, 1, 0); PG8_STAGE(PG8_SA(0, 1), a2 + hstep, voffA);
;             PG8_WAIT_V(8); PG8_WAIT_L(0); PG8_BAR; PG8_MMA(0, 0, At, B0); PG8_MMA(0, 1, At, B1); PG8_BAR; PG8_SCHED;
	s_mov_b64 s[4:5], s[8:9]
	s_add_i32 s38, s38, s15
	ds_read_b128 v[178:181], v194 offset:16384
	ds_read_b128 v[182:185], v194 offset:17408
	ds_read_b128 v[186:189], v194 offset:18432
	ds_read_b128 v[196:199], v194 offset:19456
	ds_read_b128 v[200:203], v194 offset:20480
	ds_read_b128 v[204:207], v194 offset:21504
	ds_read_b128 v[208:211], v194 offset:22528
	ds_read_b128 v[212:215], v194 offset:23552
	s_mov_b32 m0, s38
	s_nop 0
	global_load_lds_dwordx4 v162, s[4:5]
	s_add_i32 m0, s38, 0x2000
	s_nop 0
	global_load_lds_dwordx4 v190, s[4:5]
	s_add_u32 s4, s8, 0x160000
	s_addc_u32 s5, s9, 0
	s_add_i32 s38, s39, s15
	s_mov_b32 m0, s38
	s_nop 0
	global_load_lds_dwordx4 v162, s[4:5]
	s_add_i32 m0, s38, 0x2000
	s_nop 0
	global_load_lds_dwordx4 v190, s[4:5]
	s_mov_b64 s[4:5], s[10:11]
	s_mov_b32 m0, s16
	s_nop 0
	global_load_lds_dwordx4 v1, s[4:5]
	s_mov_b32 m0, s17
	s_nop 0
	global_load_lds_dwordx4 v164, s[4:5]
	s_waitcnt vmcnt(8)
	s_waitcnt lgkmcnt(0)
	s_barrier
	s_setprio 1
	s_waitcnt lgkmcnt(0)
	v_mfma_f32_16x16x32_bf16 v[110:113], v[34:37], v[178:181], v[110:113]
	v_mfma_f32_16x16x32_bf16 v[106:109], v[98:101], v[178:181], v[106:109]
	v_mfma_f32_16x16x32_bf16 v[94:97], v[34:37], v[186:189], v[94:97]
	v_mfma_f32_16x16x32_bf16 v[90:93], v[98:101], v[186:189], v[90:93]
	v_mfma_f32_16x16x32_bf16 v[86:89], v[34:37], v[200:203], v[86:89]
	v_mfma_f32_16x16x32_bf16 v[82:85], v[98:101], v[200:203], v[82:85]
	v_mfma_f32_16x16x32_bf16 v[34:37], v[34:37], v[208:211], v[78:81]
	v_mfma_f32_16x16x32_bf16 v[110:113], v[38:41], v[182:185], v[110:113]
	v_mfma_f32_16x16x32_bf16 v[106:109], v[102:105], v[182:185], v[106:109]
	v_mfma_f32_16x16x32_bf16 v[94:97], v[38:41], v[196:199], v[94:97]
	v_mfma_f32_16x16x32_bf16 v[90:93], v[102:105], v[196:199], v[90:93]
	v_mfma_f32_16x16x32_bf16 v[86:89], v[38:41], v[204:207], v[86:89]
	v_mfma_f32_16x16x32_bf16 v[82:85], v[102:105], v[204:207], v[82:85]
	v_mfma_f32_16x16x32_bf16 v[34:37], v[38:41], v[212:215], v[34:37]
	v_mfma_f32_16x16x32_bf16 v[38:41], v[98:101], v[208:211], v[74:77]
	v_mfma_f32_16x16x32_bf16 v[38:41], v[102:105], v[212:215], v[38:41]
	s_setprio 0
	s_setprio 1
	v_mfma_f32_16x16x32_bf16 v[30:33], v[146:149], v[178:181], v[30:33]
	v_mfma_f32_16x16x32_bf16 v[26:29], v[154:157], v[178:181], v[26:29]
	v_mfma_f32_16x16x32_bf16 v[22:25], v[146:149], v[186:189], v[22:25]
	v_mfma_f32_16x16x32_bf16 v[18:21], v[154:157], v[186:189], v[18:21]
	v_mfma_f32_16x16x32_bf16 v[14:17], v[146:149], v[200:203], v[14:17]
	v_mfma_f32_16x16x32_bf16 v[10:13], v[154:157], v[200:203], v[10:13]
	v_mfma_f32_16x16x32_bf16 v[6:9], v[146:149], v[208:211], v[6:9]
	v_mfma_f32_16x16x32_bf16 v[2:5], v[154:157], v[208:211], v[2:5]
	v_mfma_f32_16x16x32_bf16 v[30:33], v[150:153], v[182:185], v[30:33]
	v_mfma_f32_16x16x32_bf16 v[26:29], v[158:161], v[182:185], v[26:29]
	v_mfma_f32_16x16x32_bf16 v[22:25], v[150:153], v[196:199], v[22:25]
	v_mfma_f32_16x16x32_bf16 v[18:21], v[158:161], v[196:199], v[18:21]
	v_mfma_f32_16x16x32_bf16 v[14:17], v[150:153], v[204:207], v[14:17]
	v_mfma_f32_16x16x32_bf16 v[10:13], v[158:161], v[204:207], v[10:13]
	v_mfma_f32_16x16x32_bf16 v[6:9], v[150:153], v[212:215], v[6:9]
	v_mfma_f32_16x16x32_bf16 v[2:5], v[158:161], v[212:215], v[2:5]
	s_setprio 0
	s_barrier
	s_add_i32 s38, 0, 0x18000
	s_add_i32 s39, 0, 0x1c000
	ds_read_b128 v[74:77], v244 offset:32768
	ds_read_b128 v[78:81], v244 offset:33792
	ds_read_b128 v[98:101], v244 offset:34816
	ds_read_b128 v[102:105], v244 offset:35840
	ds_read_b128 v[146:149], v244 offset:49152
	ds_read_b128 v[150:153], v244 offset:50176
	ds_read_b128 v[154:157], v244 offset:51200
	ds_read_b128 v[158:161], v244 offset:52224
	s_add_u32 s4, s10, 0x160000
	s_addc_u32 s5, s11, 0
	s_mov_b32 m0, s18
	ds_read_b128 v[178:181], v194 offset:32768
	ds_read_b128 v[182:185], v194 offset:33792
	ds_read_b128 v[186:189], v194 offset:34816
	ds_read_b128 v[196:199], v194 offset:35840
	ds_read_b128 v[200:203], v194 offset:36864
	ds_read_b128 v[204:207], v194 offset:37888
	ds_read_b128 v[208:211], v194 offset:38912
	ds_read_b128 v[212:215], v194 offset:39936
	s_nop 0
	global_load_lds_dwordx4 v1, s[4:5]
	s_mov_b32 m0, s19
	s_nop 0
	global_load_lds_dwordx4 v164, s[4:5]
	s_waitcnt vmcnt(8)
	s_waitcnt lgkmcnt(0)
	s_barrier
	s_setprio 1
	s_waitcnt lgkmcnt(0)
	v_mfma_f32_16x16x32_bf16 v[142:145], v[74:77], v[178:181], v[142:145]
	v_mfma_f32_16x16x32_bf16 v[138:141], v[98:101], v[178:181], v[138:141]
	v_mfma_f32_16x16x32_bf16 v[134:137], v[74:77], v[186:189], v[134:137]
	v_mfma_f32_16x16x32_bf16 v[130:133], v[98:101], v[186:189], v[130:133]
	v_mfma_f32_16x16x32_bf16 v[126:129], v[74:77], v[200:203], v[126:129]
	v_mfma_f32_16x16x32_bf16 v[122:125], v[98:101], v[200:203], v[122:125]
	v_mfma_f32_16x16x32_bf16 v[118:121], v[74:77], v[208:211], v[118:121]
	v_mfma_f32_16x16x32_bf16 v[114:117], v[98:101], v[208:211], v[114:117]
	v_mfma_f32_16x16x32_bf16 v[142:145], v[78:81], v[182:185], v[142:145]
	v_mfma_f32_16x16x32_bf16 v[138:141], v[102:105], v[182:185], v[138:141]
	v_mfma_f32_16x16x32_bf16 v[134:137], v[78:81], v[196:199], v[134:137]
	v_mfma_f32_16x16x32_bf16 v[130:133], v[102:105], v[196:199], v[130:133]
	v_mfma_f32_16x16x32_bf16 v[126:129], v[78:81], v[204:207], v[126:129]
	v_mfma_f32_16x16x32_bf16 v[122:125], v[102:105], v[204:207], v[122:125]
	v_mfma_f32_16x16x32_bf16 v[118:121], v[78:81], v[212:215], v[118:121]
	v_mfma_f32_16x16x32_bf16 v[114:117], v[102:105], v[212:215], v[114:117]
	s_setprio 0
	s_setprio 1
	v_mfma_f32_16x16x32_bf16 v[70:73], v[146:149], v[178:181], v[70:73]
	v_mfma_f32_16x16x32_bf16 v[66:69], v[154:157], v[178:181], v[66:69]
	v_mfma_f32_16x16x32_bf16 v[62:65], v[146:149], v[186:189], v[62:65]
	v_mfma_f32_16x16x32_bf16 v[58:61], v[154:157], v[186:189], v[58:61]
	v_mfma_f32_16x16x32_bf16 v[54:57], v[146:149], v[200:203], v[54:57]
	v_mfma_f32_16x16x32_bf16 v[50:53], v[154:157], v[200:203], v[50:53]
	v_mfma_f32_16x16x32_bf16 v[46:49], v[146:149], v[208:211], v[46:49]
	v_mfma_f32_16x16x32_bf16 v[42:45], v[154:157], v[208:211], v[42:45]
	v_mfma_f32_16x16x32_bf16 v[70:73], v[150:153], v[182:185], v[70:73]
	v_mfma_f32_16x16x32_bf16 v[66:69], v[158:161], v[182:185], v[66:69]
	v_mfma_f32_16x16x32_bf16 v[62:65], v[150:153], v[196:199], v[62:65]
	v_mfma_f32_16x16x32_bf16 v[58:61], v[158:161], v[196:199], v[58:61]
	v_mfma_f32_16x16x32_bf16 v[54:57], v[150:153], v[204:207], v[54:57]
	v_mfma_f32_16x16x32_bf16 v[50:53], v[158:161], v[204:207], v[50:53]
	v_mfma_f32_16x16x32_bf16 v[46:49], v[150:153], v[212:215], v[46:49]
	v_mfma_f32_16x16x32_bf16 v[42:45], v[158:161], v[212:215], v[42:45]
	s_setprio 0
	s_barrier
; #define PG8_STAGE(bufoff, gbase, voff) do { const char* gb_ = (const char*)(gbase); asm volatile("" : "+s"(gb_)); _Pragma("unroll") for (int _i = 0; _i < 2; ++_i) { unsigned vo_ = (voff)[_i]; asm volatile("" : "+v"(vo_));        \
;         __builtin_amdgcn_global_load_lds((const unsigned*)(gb_ + vo_), (PG8_LAS unsigned*)(lds + (bufoff) + ldsw + _i * 8192), 16, 0, 0); } } while (0)
; #define PG8_LDA(dst, b, h) do { _Pragma("unroll") for (int m = 0; m < 4; ++m) _Pragma("unroll") for (int k = 0; k < 2; ++k) dst[m][k] = *(const PG8_LAS bf16x8*)(lds + PG8_SA(b, h) + aoff + m * 2048 + k * 1024); } while (0)
; #define PG8_WAIT_V(n) asm volatile("s_waitcnt vmcnt(" #n ")" ::: "memory")
; #define PG8_WAIT_L(n) asm volatile("s_waitcnt lgkmcnt(" #n ")" ::: "memory")
; #define PG8_BAR __builtin_amdgcn_s_barrier()
; #define PG8_SCHED __builtin_amdgcn_sched_barrier(0)
;     __device__ __forceinline__ void operator()(const f32x4 (&acc)[2][2][4][2], const Unit& u, int wr, int wc, int fr, int fq) const {
;         const int row0 = u.pm * BM + wr * 64 + fr, col0 = u.pn * BM + wc * 32 + 8 * fq, b = (u.pm * BM) / rows_per_batch;
;         const float* g = gate + (size_t)b * gate_bstride + col0;
;         float ssq[2][4];
; #pragma unroll
;         for (int ai = 0; ai < 2; ++ai)
; #pragma unroll
;             for (int m = 0; m < 4; ++m) ssq[ai][m] = 0.f;
;         f32x4 gv[2][2], Gv[2][2];
; #pragma unroll
;         for (int bj = 0; bj < 2; ++bj) { gv[bj][0] = *(const f32x4*)(g + bj * HALF); gv[bj][1] = *(const f32x4*)(g + bj * HALF + 4); Gv[bj][0] = (f32x4){0.f, 0.f, 0.f, 0.f}; Gv[bj][1] = (f32x4){0.f, 0.f, 0.f, 0.f};
;             if (Hn) { const float* sc = scnext + (size_t)b * gate_bstride + col0 + bj * HALF;
;                 Gv[bj][0] = *(const f32x4*)(gnext + col0 + bj * HALF) * (1.0f + *(const f32x4*)(sc)); Gv[bj][1] = *(const f32x4*)(gnext + col0 + bj * HALF + 4) * (1.0f + *(const f32x4*)(sc + 4)); } }
; template <class Epi, class Sched, bool ALIGN_EPI = false, bool SP2 = false>
; __device__ __forceinline__ void gemm_phase(PG8_LAS unsigned char* lds, const Gemm g, const Sched& S, const Epi& E) {
;     ...
;             PG8_LDA(At, 1, 1); PG8_STAGE(PG8_SB(1, 0), b3, voffB); PG8_STAGE(PG8_SB(1, 1), b3 + hstep, voffB); PG8_STAGE(PG8_SA(1, 0), a3, voffA);
;             PG8_WAIT_V(8); PG8_WAIT_L(0); PG8_BAR; PG8_MMA(1, 0, At, B0); PG8_MMA(1, 1, At, B1); PG8_BAR; PG8_SCHED;
	s_add_u32 s4, s8, 0x80
	s_addc_u32 s5, s9, 0
	s_add_i32 s10, s38, s15
	ds_read_b128 v[178:181], v194 offset:49152
	ds_read_b128 v[182:185], v194 offset:50176
	ds_read_b128 v[186:189], v194 offset:51200
	ds_read_b128 v[196:199], v194 offset:52224
	ds_read_b128 v[200:203], v194 offset:53248
	ds_read_b128 v[204:207], v194 offset:54272
	ds_read_b128 v[208:211], v194 offset:55296
	ds_read_b128 v[212:215], v194 offset:56320
	s_mov_b32 m0, s10
	s_nop 0
	global_load_lds_dwordx4 v162, s[4:5]
	s_add_i32 m0, s10, 0x2000
	s_nop 0
	global_load_lds_dwordx4 v190, s[4:5]
	s_add_u32 s4, s8, 0x160080
	s_addc_u32 s5, s9, 0
	s_add_i32 s8, s39, s15
	s_mov_b32 m0, s8
	s_nop 0
	global_load_lds_dwordx4 v162, s[4:5]
	s_add_i32 m0, s8, 0x2000
	s_nop 0
	global_load_lds_dwordx4 v190, s[4:5]
	s_mov_b32 m0, s24
	s_nop 0
	global_load_lds_dwordx4 v1, s[6:7]
	s_mov_b32 m0, s25
	s_nop 0
	global_load_lds_dwordx4 v164, s[6:7]
	s_waitcnt vmcnt(8)
	s_waitcnt lgkmcnt(0)
	s_barrier
	s_setprio 1
	s_waitcnt lgkmcnt(0)
	v_mfma_f32_16x16x32_bf16 v[110:113], v[74:77], v[178:181], v[110:113]
	v_mfma_f32_16x16x32_bf16 v[94:97], v[74:77], v[186:189], v[94:97]
	v_mfma_f32_16x16x32_bf16 v[86:89], v[74:77], v[200:203], v[86:89]
	v_mfma_f32_16x16x32_bf16 v[34:37], v[74:77], v[208:211], v[34:37]
	v_mfma_f32_16x16x32_bf16 v[110:113], v[78:81], v[182:185], v[110:113]
	v_mfma_f32_16x16x32_bf16 v[106:109], v[98:101], v[178:181], v[106:109]
	v_mfma_f32_16x16x32_bf16 v[94:97], v[78:81], v[196:199], v[94:97]
	v_mfma_f32_16x16x32_bf16 v[90:93], v[98:101], v[186:189], v[90:93]
	v_mfma_f32_16x16x32_bf16 v[86:89], v[78:81], v[204:207], v[86:89]
	v_mfma_f32_16x16x32_bf16 v[82:85], v[98:101], v[200:203], v[82:85]
	v_mfma_f32_16x16x32_bf16 v[78:81], v[78:81], v[212:215], v[34:37]
	v_mfma_f32_16x16x32_bf16 v[34:37], v[98:101], v[208:211], v[38:41]
	v_mfma_f32_16x16x32_bf16 v[106:109], v[102:105], v[182:185], v[106:109]
	v_mfma_f32_16x16x32_bf16 v[90:93], v[102:105], v[196:199], v[90:93]
	v_mfma_f32_16x16x32_bf16 v[82:85], v[102:105], v[204:207], v[82:85]
	v_mfma_f32_16x16x32_bf16 v[74:77], v[102:105], v[212:215], v[34:37]
	s_setprio 0
	s_setprio 1
	v_mfma_f32_16x16x32_bf16 v[30:33], v[146:149], v[178:181], v[30:33]
	v_mfma_f32_16x16x32_bf16 v[26:29], v[154:157], v[178:181], v[26:29]
	v_mfma_f32_16x16x32_bf16 v[22:25], v[146:149], v[186:189], v[22:25]
	v_mfma_f32_16x16x32_bf16 v[18:21], v[154:157], v[186:189], v[18:21]
	v_mfma_f32_16x16x32_bf16 v[14:17], v[146:149], v[200:203], v[14:17]
	v_mfma_f32_16x16x32_bf16 v[10:13], v[154:157], v[200:203], v[10:13]
	v_mfma_f32_16x16x32_bf16 v[6:9], v[146:149], v[208:211], v[6:9]
	v_mfma_f32_16x16x32_bf16 v[2:5], v[154:157], v[208:211], v[2:5]
	v_mfma_f32_16x16x32_bf16 v[30:33], v[150:153], v[182:185], v[30:33]
	v_mfma_f32_16x16x32_bf16 v[26:29], v[158:161], v[182:185], v[26:29]
	v_mfma_f32_16x16x32_bf16 v[22:25], v[150:153], v[196:199], v[22:25]
	v_mfma_f32_16x16x32_bf16 v[18:21], v[158:161], v[196:199], v[18:21]
	v_mfma_f32_16x16x32_bf16 v[14:17], v[150:153], v[204:207], v[14:17]
	v_mfma_f32_16x16x32_bf16 v[10:13], v[158:161], v[204:207], v[10:13]
	v_mfma_f32_16x16x32_bf16 v[6:9], v[150:153], v[212:215], v[6:9]
	v_mfma_f32_16x16x32_bf16 v[2:5], v[158:161], v[212:215], v[2:5]
	s_setprio 0
	s_barrier
	s_add_i32 s35, s35, 2
	s_add_u32 s31, s31, 0x100
	s_addc_u32 s34, s34, 0
	s_cmpk_gt_u32 s35, 0x55
	s_mov_b64 s[4:5], s[2:3]
	s_cbranch_scc0 .LBB0_707
	s_ashr_i32 s2, s29, 31
	s_lshr_b32 s2, s2, 27
	s_add_i32 s2, s29, s2
	s_ashr_i32 s2, s2, 5
	v_lshl_or_b32 v156, s30, 8, v193
	s_mul_i32 s5, s2, 0xc000
	v_ashrrev_i32_e32 v157, 31, v156
	s_mul_hi_i32 s4, s2, 0xc000
	s_add_u32 s2, s20, s5
	s_addc_u32 s3, s21, s4
	v_lshlrev_b64 v[34:35], 2, v[156:157]
	v_lshl_add_u64 v[38:39], s[2:3], 0, v[34:35]
	global_load_dwordx4 v[98:101], v[38:39], off offset:16
	global_load_dwordx4 v[102:105], v[38:39], off
	s_add_u32 s2, s22, s5
	s_addc_u32 s3, s23, s4
	v_lshl_add_u64 v[148:149], s[2:3], 0, v[34:35]
	v_lshl_add_u64 v[146:147], s[48:49], 0, v[34:35]
	v_mov_b32_e32 v158, 0
	v_cndmask_b32_e64 v34, 0, 1, s[46:47]
	v_cmp_ne_u32_e64 s[2:3], 1, v34
	s_andn2_b64 vcc, exec, s[46:47]
	v_mov_b32_e32 v159, v158
	v_mov_b32_e32 v160, v158
	v_mov_b32_e32 v161, v158
	v_mov_b32_e32 v178, v158
	v_mov_b32_e32 v179, v158
	v_mov_b32_e32 v180, v158
	v_mov_b32_e32 v181, v158
	s_cbranch_vccnz .LBB0_710
	global_load_dwordx4 v[34:37], v[148:149], off
	global_load_dwordx4 v[150:153], v[148:149], off offset:16
	global_load_dwordx4 v[158:161], v[146:147], off
	global_load_dwordx4 v[178:181], v[146:147], off offset:16
	s_waitcnt vmcnt(0)
	v_pk_add_f32 v[36:37], v[36:37], 1.0 op_sel_hi:[1,0]
	v_pk_add_f32 v[34:35], v[34:35], 1.0 op_sel_hi:[1,0]
	v_pk_add_f32 v[40:41], v[152:153], 1.0 op_sel_hi:[1,0]
	v_pk_add_f32 v[150:151], v[150:151], 1.0 op_sel_hi:[1,0]
	v_pk_mul_f32 v[160:161], v[160:161], v[36:37]
	v_pk_mul_f32 v[158:159], v[158:159], v[34:35]
	v_pk_mul_f32 v[180:181], v[180:181], v[40:41]
	v_pk_mul_f32 v[178:179], v[178:179], v[150:151]

; __global__ void __launch_bounds__(NWAVES * 64, 2) skel_fwd(Args args) {
;     extern __shared__ __attribute__((aligned(16))) unsigned char lds[];
	.amdhsa_kernel _Z8skel_fwd4Args
		.amdhsa_group_segment_fixed_size 0
		.amdhsa_private_segment_fixed_size 0
		.amdhsa_kernarg_size 408
		.amdhsa_user_sgpr_count 2
		.amdhsa_user_sgpr_dispatch_ptr 0
		.amdhsa_user_sgpr_queue_ptr 0
		.amdhsa_user_sgpr_kernarg_segment_ptr 1
		.amdhsa_user_sgpr_dispatch_id 0
		.amdhsa_user_sgpr_kernarg_preload_length 0
		.amdhsa_user_sgpr_kernarg_preload_offset 0
		.amdhsa_user_sgpr_private_segment_size 0
		.amdhsa_uses_dynamic_stack 0
		.amdhsa_enable_private_segment 0
		.amdhsa_system_sgpr_workgroup_id_x 1
		.amdhsa_system_sgpr_workgroup_id_y 0
		.amdhsa_system_sgpr_workgroup_id_z 0
		.amdhsa_system_sgpr_workgroup_info 0
		.amdhsa_system_vgpr_workitem_id 0
		.amdhsa_next_free_vgpr 248
		.amdhsa_next_free_sgpr 98
		.amdhsa_accum_offset 248
		.amdhsa_reserve_vcc 1
		.amdhsa_float_round_mode_32 0
		.amdhsa_float_round_mode_16_64 0
		.amdhsa_float_denorm_mode_32 3
		.amdhsa_float_denorm_mode_16_64 3
		.amdhsa_dx10_clamp 1
		.amdhsa_ieee_mode 1
		.amdhsa_fp16_overflow 0
		.amdhsa_tg_split 0
		.amdhsa_exception_fp_ieee_invalid_op 0
		.amdhsa_exception_fp_denorm_src 0
		.amdhsa_exception_fp_ieee_div_zero 0
		.amdhsa_exception_fp_ieee_overflow 0
		.amdhsa_exception_fp_ieee_underflow 0
		.amdhsa_exception_fp_ieee_inexact 0
		.amdhsa_exception_int_div_zero 0
	.end_amdhsa_kernel

; __global__ void __launch_bounds__(NWAVES * 64, 2) skel_fwd(Args args) {
amdhsa.kernels:
  - .agpr_count:     0
    .args:
      - .offset:         0
        .size:           152
        .value_kind:     by_value
      - .offset:         152
        .size:           4
        .value_kind:     hidden_block_count_x
      - .offset:         156
        .size:           4
        .value_kind:     hidden_block_count_y
      - .offset:         160
        .size:           4
        .value_kind:     hidden_block_count_z
      - .offset:         164
        .size:           2
        .value_kind:     hidden_group_size_x
      - .offset:         166
        .size:           2
        .value_kind:     hidden_group_size_y
      - .offset:         168
        .size:           2
        .value_kind:     hidden_group_size_z
      - .offset:         170
        .size:           2
        .value_kind:     hidden_remainder_x
      - .offset:         172
        .size:           2
        .value_kind:     hidden_remainder_y
      - .offset:         174
        .size:           2
        .value_kind:     hidden_remainder_z
      - .offset:         192
        .size:           8
        .value_kind:     hidden_global_offset_x
      - .offset:         200
        .size:           8
        .value_kind:     hidden_global_offset_y
      - .offset:         208
        .size:           8
        .value_kind:     hidden_global_offset_z
      - .offset:         216
        .size:           2
        .value_kind:     hidden_grid_dims
      - .offset:         272
        .size:           4
        .value_kind:     hidden_dynamic_lds_size
    .group_segment_fixed_size: 0
    .kernarg_segment_align: 8
    .kernarg_segment_size: 408
    .language:       OpenCL C
    .language_version:
      - 2
      - 0
    .max_flat_workgroup_size: 512
    .name:           _Z8skel_fwd4Args
    .private_segment_fixed_size: 0
    .sgpr_count:     104
    .sgpr_spill_count: 247
    .symbol:         _Z8skel_fwd4Args.kd
    .uniform_work_group_size: 1
    .uses_dynamic_stack: false
    .vgpr_count:     248
    .vgpr_spill_count: 0
    .wavefront_size: 64
